# adds: CO short-conv loads hoisted over the LayerNorm section; dead trailing K-tile loads made one-line; single accumulator zeroing; saddr LDS-DMA in UP; header waits dropped in PL/MG; leader no longer
# speedup vs baseline: 1.0112x; 1.0112x over previous
; #define PG8_STAGE(bufoff, gbase, voff) do { _Pragma("unroll") for (int _i = 0; _i < 2; ++_i) \
;         __builtin_amdgcn_global_load_lds((const unsigned*)((const char*)(gbase) + (voff)[_i]), (PG8_LAS unsigned*)(lds + (bufoff) + ldsw + _i * 8192), 16, 0, 0); } while (0)
; #define PG8_LDA(dst, b, h) do { _Pragma("unroll") for (int m = 0; m < 4; ++m) _Pragma("unroll") for (int k = 0; k < 2; ++k) dst[m][k] = *(const PG8_LAS bf16x8*)(lds + PG8_SA(b, h) + aoff + m * 2048 + k * 1024); } while (0)
; #define PG8_LDB(dst, b, h) do { _Pragma("unroll") for (int n = 0; n < 2; ++n) _Pragma("unroll") for (int k = 0; k < 2; ++k) dst[n][k] = *(const PG8_LAS bf16x8*)(lds + PG8_SB(b, h) + boff + n * 2048 + k * 1024); } while (0)
; #define PG8_WAIT_V(n) asm volatile("s_waitcnt vmcnt(" #n ")" ::: "memory")
; #define PG8_WAIT_L(n) asm volatile("s_waitcnt lgkmcnt(" #n ")" ::: "memory")
; template <class Epi, class Sched, bool ALIGN_EPI = false, bool SP2 = false, bool ACHUNK = false>
; __device__ __forceinline__ void gemm_phase(PG8_LAS unsigned char* lds, const Gemm g, const Sched& S, const Epi& E) {
;     ...
;         const bool has_next = S.next(ui + 1, nxt);
;         const char* nA = has_next ? (const char*)g.A + (size_t)nxt.pm * tstepA : cA; const char* nB = has_next ? (const char*)g.Bt + (size_t)nxt.pn * tstepB : cB;
;         for (int t = 0; t < nt; t += 2) {
;             const bool last = (t == nt - 2);
;             if constexpr (Epi::HAS_MID) { if (t == Epi::MID_T) E.mid(acc, cur, wr, wc, fr, fq, ShflDev{}); }
;             const char* a1 = cA + (size_t)(t + 1) * kstep;
;             const char* a2 = last ? nA : cA + (size_t)(t + 2) * kstep; const char* b2 = last ? nB : cB + (size_t)(t + 2) * kstep;
;             const char* a3 = a2 + kstep; const char* b3 = b2 + kstep;
;             if (last && has_next) S.a_ready(nxt);
;             if constexpr (SP2) {
;             PG8_LDB(B0, 0, 0); PG8_LDB(B1, 0, 1); PG8_SCHED; PG8_LDA(At, 0, 0); PG8_STAGE(PG8_SA(1, 1), a1 + hstepA, voffA);
;             PG8_WAIT_V(8); PG8_WAIT_L(0); PG8_BAR; PG8_MMA(0, 0, At, B0); PG8_MMA(0, 1, At, B1); PG8_BAR; PG8_SCHED;
;             PG8_LDA(At, 0, 1); PG8_STAGE(PG8_SB(0, 0), b2, voffB); PG8_STAGE(PG8_SB(0, 1), b2 + hstepB, voffB); PG8_STAGE(PG8_SA(0, 0), a2, voffA);
;             PG8_WAIT_V(8); PG8_WAIT_L(0); PG8_BAR; PG8_MMA(1, 0, At, B0); PG8_MMA(1, 1, At, B1); PG8_BAR; PG8_SCHED;
.LBB0_52:
	s_add_i32 s46, s18, 2
	s_add_u32 s47, s20, 0x80
	s_addc_u32 s19, s21, 0
	s_add_i32 s50, 0, 0x10000
	s_cmp_eq_u32 s30, s18
	s_cselect_b32 s19, s1, s19
	s_cselect_b32 s18, s0, s47
	v_add_u32_e32 v151, s50, v147
	s_cselect_b32 s49, s17, s45
	s_cselect_b32 s48, s16, s44
	s_cbranch_scc0 .Lnl_dn
	s_cmpk_lg_u32 s87, 0x100
	s_cbranch_scc1 .Lnl_dn
	v_mov_b32_e32 v2, 0
	v_mov_b32_e32 v136, 0
	v_mov_b32_e32 v132, 0
	v_mov_b32_e32 v134, 0
.Lnl_dn:
	s_add_i32 s47, 0, 0x14000
	ds_read_b128 v[142:145], v151
	ds_read_b128 v[152:155], v151 offset:1024
	ds_read_b128 v[156:159], v151 offset:2048
	ds_read_b128 v[160:163], v151 offset:3072
	v_add_u32_e32 v151, s47, v147
	ds_read_b128 v[164:167], v151
	ds_read_b128 v[168:171], v151 offset:1024
	ds_read_b128 v[172:175], v151 offset:2048
	ds_read_b128 v[176:179], v151 offset:3072
	v_lshl_add_u64 v[192:193], s[20:21], 0, v[138:139]
	s_add_i32 m0, s23, 0xc000
	ds_read_b128 v[180:183], v150
	ds_read_b128 v[184:187], v150 offset:1024
	ds_read_b128 v[188:191], v150 offset:2048
	ds_read_b128 v[198:201], v150 offset:3072
	ds_read_b128 v[202:205], v150 offset:4096
	ds_read_b128 v[206:209], v150 offset:5120
	ds_read_b128 v[210:213], v150 offset:6144
	ds_read_b128 v[214:217], v150 offset:7168
	global_load_lds_dwordx4 v[192:193], off
	v_lshl_add_u64 v[192:193], s[20:21], 0, v[140:141]
	s_add_i32 m0, s23, 0xe000
	s_nop 0
	global_load_lds_dwordx4 v[192:193], off
	s_waitcnt vmcnt(8)
	s_waitcnt lgkmcnt(0)
	s_barrier
	s_setprio 1
	s_waitcnt lgkmcnt(0)
	v_mfma_f32_16x16x32_bf16 v[120:123], v[142:145], v[180:183], v[120:123]
	v_mfma_f32_16x16x32_bf16 v[128:131], v[156:159], v[180:183], v[128:131]
	v_mfma_f32_16x16x32_bf16 v[104:107], v[142:145], v[188:191], v[104:107]
	v_mfma_f32_16x16x32_bf16 v[112:115], v[156:159], v[188:191], v[112:115]
	v_mfma_f32_16x16x32_bf16 v[88:91], v[142:145], v[202:205], v[88:91]
	v_mfma_f32_16x16x32_bf16 v[96:99], v[156:159], v[202:205], v[96:99]
	v_mfma_f32_16x16x32_bf16 v[72:75], v[142:145], v[210:213], v[72:75]
	v_mfma_f32_16x16x32_bf16 v[80:83], v[156:159], v[210:213], v[80:83]
	v_mfma_f32_16x16x32_bf16 v[120:123], v[152:155], v[184:187], v[120:123]
	v_mfma_f32_16x16x32_bf16 v[128:131], v[160:163], v[184:187], v[128:131]
	v_mfma_f32_16x16x32_bf16 v[104:107], v[152:155], v[198:201], v[104:107]
	v_mfma_f32_16x16x32_bf16 v[112:115], v[160:163], v[198:201], v[112:115]
	v_mfma_f32_16x16x32_bf16 v[88:91], v[152:155], v[206:209], v[88:91]
	v_mfma_f32_16x16x32_bf16 v[96:99], v[160:163], v[206:209], v[96:99]
	v_mfma_f32_16x16x32_bf16 v[72:75], v[152:155], v[214:217], v[72:75]
	v_mfma_f32_16x16x32_bf16 v[80:83], v[160:163], v[214:217], v[80:83]
	s_setprio 0
	s_setprio 1
	v_mfma_f32_16x16x32_bf16 v[116:119], v[164:167], v[180:183], v[116:119]
	v_mfma_f32_16x16x32_bf16 v[124:127], v[172:175], v[180:183], v[124:127]
	v_mfma_f32_16x16x32_bf16 v[100:103], v[164:167], v[188:191], v[100:103]
	v_mfma_f32_16x16x32_bf16 v[108:111], v[172:175], v[188:191], v[108:111]
	v_mfma_f32_16x16x32_bf16 v[84:87], v[164:167], v[202:205], v[84:87]
	v_mfma_f32_16x16x32_bf16 v[92:95], v[172:175], v[202:205], v[92:95]
	v_mfma_f32_16x16x32_bf16 v[68:71], v[164:167], v[210:213], v[68:71]
	v_mfma_f32_16x16x32_bf16 v[76:79], v[172:175], v[210:213], v[76:79]
	v_mfma_f32_16x16x32_bf16 v[116:119], v[168:171], v[184:187], v[116:119]
	v_mfma_f32_16x16x32_bf16 v[124:127], v[176:179], v[184:187], v[124:127]
	v_mfma_f32_16x16x32_bf16 v[100:103], v[168:171], v[198:201], v[100:103]
	v_mfma_f32_16x16x32_bf16 v[108:111], v[176:179], v[198:201], v[108:111]
	v_mfma_f32_16x16x32_bf16 v[84:87], v[168:171], v[206:209], v[84:87]
	v_mfma_f32_16x16x32_bf16 v[92:95], v[176:179], v[206:209], v[92:95]
	v_mfma_f32_16x16x32_bf16 v[68:71], v[168:171], v[214:217], v[68:71]
	v_mfma_f32_16x16x32_bf16 v[76:79], v[176:179], v[214:217], v[76:79]
	s_setprio 0
	s_barrier
	s_add_i32 s50, s50, s22
	v_lshl_add_u64 v[192:193], s[48:49], 0, v[2:3]
	s_mov_b32 m0, s50
	ds_read_b128 v[180:183], v150 offset:16384
	ds_read_b128 v[184:187], v150 offset:17408
	ds_read_b128 v[188:191], v150 offset:18432
	ds_read_b128 v[198:201], v150 offset:19456
	ds_read_b128 v[202:205], v150 offset:20480
	ds_read_b128 v[206:209], v150 offset:21504
	ds_read_b128 v[210:213], v150 offset:22528
	ds_read_b128 v[214:217], v150 offset:23552
	global_load_lds_dwordx4 v[192:193], off
	s_add_i32 m0, s50, 0x2000
	v_lshl_add_u64 v[218:219], s[48:49], 0, v[136:137]
	s_add_u32 s48, s48, s2
	s_addc_u32 s49, s49, s3
	s_add_i32 s47, s47, s22
	global_load_lds_dwordx4 v[218:219], off
	v_lshl_add_u64 v[220:221], s[48:49], 0, v[2:3]
	s_mov_b32 m0, s47
	v_lshl_add_u64 v[222:223], s[48:49], 0, v[136:137]
	global_load_lds_dwordx4 v[220:221], off
	s_add_i32 m0, s47, 0x2000
	v_lshl_add_u64 v[224:225], s[18:19], 0, v[132:133]
	global_load_lds_dwordx4 v[222:223], off
	s_mov_b32 m0, s23
	v_lshl_add_u64 v[232:233], s[18:19], 0, v[134:135]
	global_load_lds_dwordx4 v[224:225], off
	s_mov_b32 m0, s24
	s_nop 0
	global_load_lds_dwordx4 v[232:233], off
	s_waitcnt vmcnt(8)
	s_waitcnt lgkmcnt(0)
	s_barrier
; #define PG8_STAGE(bufoff, gbase, voff) do { _Pragma("unroll") for (int _i = 0; _i < 2; ++_i) \
;         __builtin_amdgcn_global_load_lds((const unsigned*)((const char*)(gbase) + (voff)[_i]), (PG8_LAS unsigned*)(lds + (bufoff) + ldsw + _i * 8192), 16, 0, 0); } while (0)
; #define PG8_LDA(dst, b, h) do { _Pragma("unroll") for (int m = 0; m < 4; ++m) _Pragma("unroll") for (int k = 0; k < 2; ++k) dst[m][k] = *(const PG8_LAS bf16x8*)(lds + PG8_SA(b, h) + aoff + m * 2048 + k * 1024); } while (0)
; #define PG8_LDB(dst, b, h) do { _Pragma("unroll") for (int n = 0; n < 2; ++n) _Pragma("unroll") for (int k = 0; k < 2; ++k) dst[n][k] = *(const PG8_LAS bf16x8*)(lds + PG8_SB(b, h) + boff + n * 2048 + k * 1024); } while (0)
; #define PG8_MMA(ai, bj, At, Bt) do { __builtin_amdgcn_s_setprio(1); _Pragma("unroll") for (int m = 0; m < 4; ++m) _Pragma("unroll") for (int n = 0; n < 2; ++n) _Pragma("unroll") for (int k = 0; k < 2; ++k) \
;         acc[ai][bj][m][n] = __builtin_amdgcn_mfma_f32_16x16x32_bf16(Bt[n][k], At[m][k], acc[ai][bj][m][n], 0, 0, 0); __builtin_amdgcn_s_setprio(0); } while (0)
; #define PG8_WAIT_V(n) asm volatile("s_waitcnt vmcnt(" #n ")" ::: "memory")
; #define PG8_WAIT_L(n) asm volatile("s_waitcnt lgkmcnt(" #n ")" ::: "memory")
; #define PG8_BAR __builtin_amdgcn_s_barrier()
; #define PG8_SCHED __builtin_amdgcn_sched_barrier(0)
; template <class Epi, class Sched, bool ALIGN_EPI = false, bool SP2 = false, bool ACHUNK = false>
; __device__ __forceinline__ void gemm_phase(PG8_LAS unsigned char* lds, const Gemm g, const Sched& S, const Epi& E) {
;     ...
;             PG8_WAIT_V(8); PG8_WAIT_L(0); PG8_BAR; PG8_MMA(1, 0, At, B0); PG8_MMA(1, 1, At, B1); PG8_BAR; PG8_SCHED;
;             PG8_LDB(B0, 1, 0); PG8_LDB(B1, 1, 1); PG8_SCHED; PG8_LDA(At, 1, 0); PG8_STAGE(PG8_SA(0, 1), a2 + hstepA, voffA);
;             PG8_WAIT_V(8); PG8_WAIT_L(0); PG8_BAR; PG8_MMA(0, 0, At, B0); PG8_MMA(0, 1, At, B1); PG8_BAR; PG8_SCHED;
	s_setprio 1
	s_waitcnt lgkmcnt(0)
	v_mfma_f32_16x16x32_bf16 v[56:59], v[142:145], v[180:183], v[56:59]
	v_mfma_f32_16x16x32_bf16 v[64:67], v[156:159], v[180:183], v[64:67]
	v_mfma_f32_16x16x32_bf16 v[40:43], v[142:145], v[188:191], v[40:43]
	v_mfma_f32_16x16x32_bf16 v[48:51], v[156:159], v[188:191], v[48:51]
	v_mfma_f32_16x16x32_bf16 v[24:27], v[142:145], v[202:205], v[24:27]
	v_mfma_f32_16x16x32_bf16 v[32:35], v[156:159], v[202:205], v[32:35]
	v_mfma_f32_16x16x32_bf16 v[8:11], v[142:145], v[210:213], v[8:11]
	v_mfma_f32_16x16x32_bf16 v[16:19], v[156:159], v[210:213], v[16:19]
	v_mfma_f32_16x16x32_bf16 v[56:59], v[152:155], v[184:187], v[56:59]
	v_mfma_f32_16x16x32_bf16 v[64:67], v[160:163], v[184:187], v[64:67]
	v_mfma_f32_16x16x32_bf16 v[40:43], v[152:155], v[198:201], v[40:43]
	v_mfma_f32_16x16x32_bf16 v[48:51], v[160:163], v[198:201], v[48:51]
	v_mfma_f32_16x16x32_bf16 v[24:27], v[152:155], v[206:209], v[24:27]
	v_mfma_f32_16x16x32_bf16 v[32:35], v[160:163], v[206:209], v[32:35]
	v_mfma_f32_16x16x32_bf16 v[8:11], v[152:155], v[214:217], v[8:11]
	v_mfma_f32_16x16x32_bf16 v[16:19], v[160:163], v[214:217], v[16:19]
	s_setprio 0
	s_setprio 1
	v_mfma_f32_16x16x32_bf16 v[52:55], v[164:167], v[180:183], v[52:55]
	v_mfma_f32_16x16x32_bf16 v[60:63], v[172:175], v[180:183], v[60:63]
	v_mfma_f32_16x16x32_bf16 v[36:39], v[164:167], v[188:191], v[36:39]
	v_mfma_f32_16x16x32_bf16 v[44:47], v[172:175], v[188:191], v[44:47]
	v_mfma_f32_16x16x32_bf16 v[20:23], v[164:167], v[202:205], v[20:23]
	v_mfma_f32_16x16x32_bf16 v[28:31], v[172:175], v[202:205], v[28:31]
	v_mfma_f32_16x16x32_bf16 v[4:7], v[164:167], v[210:213], v[4:7]
	v_mfma_f32_16x16x32_bf16 v[12:15], v[172:175], v[210:213], v[12:15]
	v_mfma_f32_16x16x32_bf16 v[52:55], v[168:171], v[184:187], v[52:55]
	v_mfma_f32_16x16x32_bf16 v[60:63], v[176:179], v[184:187], v[60:63]
	v_mfma_f32_16x16x32_bf16 v[36:39], v[168:171], v[198:201], v[36:39]
	v_mfma_f32_16x16x32_bf16 v[44:47], v[176:179], v[198:201], v[44:47]
	v_mfma_f32_16x16x32_bf16 v[20:23], v[168:171], v[206:209], v[20:23]
	v_mfma_f32_16x16x32_bf16 v[28:31], v[176:179], v[206:209], v[28:31]
	v_mfma_f32_16x16x32_bf16 v[4:7], v[168:171], v[214:217], v[4:7]
	v_mfma_f32_16x16x32_bf16 v[12:15], v[176:179], v[214:217], v[12:15]
	s_setprio 0
	s_barrier
	s_add_i32 s47, 0, 0x18000
	v_add_u32_e32 v151, s47, v147
	s_add_i32 s48, 0, 0x1c000
	ds_read_b128 v[142:145], v151
	ds_read_b128 v[152:155], v151 offset:1024
	ds_read_b128 v[156:159], v151 offset:2048
	ds_read_b128 v[160:163], v151 offset:3072
	v_add_u32_e32 v151, s48, v147
	ds_read_b128 v[164:167], v151
	ds_read_b128 v[168:171], v151 offset:1024
	ds_read_b128 v[172:175], v151 offset:2048
	ds_read_b128 v[176:179], v151 offset:3072
	s_add_u32 s18, s18, s2
	s_addc_u32 s19, s19, s3
	s_mov_b32 m0, s25
	v_lshl_add_u64 v[234:235], s[18:19], 0, v[132:133]
	ds_read_b128 v[180:183], v150 offset:32768
	ds_read_b128 v[184:187], v150 offset:33792
	ds_read_b128 v[188:191], v150 offset:34816
	ds_read_b128 v[198:201], v150 offset:35840
	ds_read_b128 v[202:205], v150 offset:36864
	ds_read_b128 v[206:209], v150 offset:37888
	ds_read_b128 v[210:213], v150 offset:38912
	ds_read_b128 v[214:217], v150 offset:39936
	global_load_lds_dwordx4 v[234:235], off
	v_lshl_add_u64 v[234:235], s[18:19], 0, v[134:135]
	s_mov_b32 m0, s26
	s_nop 0
	global_load_lds_dwordx4 v[234:235], off
	s_waitcnt vmcnt(8)
	s_waitcnt lgkmcnt(0)
	s_barrier
	s_setprio 1
	s_waitcnt lgkmcnt(0)
	v_mfma_f32_16x16x32_bf16 v[120:123], v[142:145], v[180:183], v[120:123]
	v_mfma_f32_16x16x32_bf16 v[128:131], v[156:159], v[180:183], v[128:131]
	v_mfma_f32_16x16x32_bf16 v[104:107], v[142:145], v[188:191], v[104:107]
	v_mfma_f32_16x16x32_bf16 v[112:115], v[156:159], v[188:191], v[112:115]
	v_mfma_f32_16x16x32_bf16 v[88:91], v[142:145], v[202:205], v[88:91]
	v_mfma_f32_16x16x32_bf16 v[96:99], v[156:159], v[202:205], v[96:99]
	v_mfma_f32_16x16x32_bf16 v[72:75], v[142:145], v[210:213], v[72:75]
	v_mfma_f32_16x16x32_bf16 v[80:83], v[156:159], v[210:213], v[80:83]
	v_mfma_f32_16x16x32_bf16 v[120:123], v[152:155], v[184:187], v[120:123]
	v_mfma_f32_16x16x32_bf16 v[128:131], v[160:163], v[184:187], v[128:131]
	v_mfma_f32_16x16x32_bf16 v[104:107], v[152:155], v[198:201], v[104:107]
	v_mfma_f32_16x16x32_bf16 v[112:115], v[160:163], v[198:201], v[112:115]
	v_mfma_f32_16x16x32_bf16 v[88:91], v[152:155], v[206:209], v[88:91]
	v_mfma_f32_16x16x32_bf16 v[96:99], v[160:163], v[206:209], v[96:99]
	v_mfma_f32_16x16x32_bf16 v[72:75], v[152:155], v[214:217], v[72:75]
	v_mfma_f32_16x16x32_bf16 v[80:83], v[160:163], v[214:217], v[80:83]
	s_setprio 0
	s_setprio 1
	v_mfma_f32_16x16x32_bf16 v[116:119], v[164:167], v[180:183], v[116:119]
	v_mfma_f32_16x16x32_bf16 v[124:127], v[172:175], v[180:183], v[124:127]
	v_mfma_f32_16x16x32_bf16 v[100:103], v[164:167], v[188:191], v[100:103]
	v_mfma_f32_16x16x32_bf16 v[108:111], v[172:175], v[188:191], v[108:111]
	v_mfma_f32_16x16x32_bf16 v[84:87], v[164:167], v[202:205], v[84:87]
	v_mfma_f32_16x16x32_bf16 v[92:95], v[172:175], v[202:205], v[92:95]
	v_mfma_f32_16x16x32_bf16 v[68:71], v[164:167], v[210:213], v[68:71]
	v_mfma_f32_16x16x32_bf16 v[76:79], v[172:175], v[210:213], v[76:79]
	v_mfma_f32_16x16x32_bf16 v[116:119], v[168:171], v[184:187], v[116:119]
	v_mfma_f32_16x16x32_bf16 v[124:127], v[176:179], v[184:187], v[124:127]
	v_mfma_f32_16x16x32_bf16 v[100:103], v[168:171], v[198:201], v[100:103]
	v_mfma_f32_16x16x32_bf16 v[108:111], v[176:179], v[198:201], v[108:111]
	v_mfma_f32_16x16x32_bf16 v[84:87], v[168:171], v[206:209], v[84:87]
	v_mfma_f32_16x16x32_bf16 v[92:95], v[176:179], v[206:209], v[92:95]
	v_mfma_f32_16x16x32_bf16 v[68:71], v[168:171], v[214:217], v[68:71]
	v_mfma_f32_16x16x32_bf16 v[76:79], v[176:179], v[214:217], v[76:79]
	s_setprio 0
	s_barrier
; #define PG8_STAGE(bufoff, gbase, voff) do { _Pragma("unroll") for (int _i = 0; _i < 2; ++_i) \
;         __builtin_amdgcn_global_load_lds((const unsigned*)((const char*)(gbase) + (voff)[_i]), (PG8_LAS unsigned*)(lds + (bufoff) + ldsw + _i * 8192), 16, 0, 0); } while (0)
; #define PG8_LDA(dst, b, h) do { _Pragma("unroll") for (int m = 0; m < 4; ++m) _Pragma("unroll") for (int k = 0; k < 2; ++k) dst[m][k] = *(const PG8_LAS bf16x8*)(lds + PG8_SA(b, h) + aoff + m * 2048 + k * 1024); } while (0)
; #define PG8_MMA(ai, bj, At, Bt) do { __builtin_amdgcn_s_setprio(1); _Pragma("unroll") for (int m = 0; m < 4; ++m) _Pragma("unroll") for (int n = 0; n < 2; ++n) _Pragma("unroll") for (int k = 0; k < 2; ++k) \
;         acc[ai][bj][m][n] = __builtin_amdgcn_mfma_f32_16x16x32_bf16(Bt[n][k], At[m][k], acc[ai][bj][m][n], 0, 0, 0); __builtin_amdgcn_s_setprio(0); } while (0)
; #define PG8_WAIT_V(n) asm volatile("s_waitcnt vmcnt(" #n ")" ::: "memory")
; #define PG8_WAIT_L(n) asm volatile("s_waitcnt lgkmcnt(" #n ")" ::: "memory")
; #define PG8_BAR __builtin_amdgcn_s_barrier()
; #define PG8_SCHED __builtin_amdgcn_sched_barrier(0)
; template <class Epi, class Sched, bool ALIGN_EPI = false, bool SP2 = false, bool ACHUNK = false>
; __device__ __forceinline__ void gemm_phase(PG8_LAS unsigned char* lds, const Gemm g, const Sched& S, const Epi& E) {
;     ...
;         for (int t = 0; t < nt; t += 2) {
;     ...
;             PG8_LDA(At, 1, 1); PG8_STAGE(PG8_SB(1, 0), b3, voffB); PG8_STAGE(PG8_SB(1, 1), b3 + hstepB, voffB); PG8_STAGE(PG8_SA(1, 0), a3, voffA);
;             PG8_WAIT_V(8); PG8_WAIT_L(0); PG8_BAR; PG8_MMA(1, 0, At, B0); PG8_MMA(1, 1, At, B1); PG8_BAR; PG8_SCHED;
	s_add_i32 s18, s47, s22
	v_lshl_add_u64 v[192:193], v[192:193], 0, s[10:11]
	s_mov_b32 m0, s18
	ds_read_b128 v[180:183], v150 offset:49152
	ds_read_b128 v[184:187], v150 offset:50176
	ds_read_b128 v[188:191], v150 offset:51200
	ds_read_b128 v[198:201], v150 offset:52224
	ds_read_b128 v[202:205], v150 offset:53248
	ds_read_b128 v[206:209], v150 offset:54272
	ds_read_b128 v[210:213], v150 offset:55296
	ds_read_b128 v[214:217], v150 offset:56320
	global_load_lds_dwordx4 v[192:193], off
	v_lshl_add_u64 v[192:193], v[218:219], 0, s[10:11]
	s_add_i32 m0, s18, 0x2000
	s_add_i32 s18, s48, s22
	global_load_lds_dwordx4 v[192:193], off
	v_lshl_add_u64 v[192:193], v[220:221], 0, s[10:11]
	s_mov_b32 m0, s18
	s_nop 0
	global_load_lds_dwordx4 v[192:193], off
	v_lshl_add_u64 v[192:193], v[222:223], 0, s[10:11]
	s_add_i32 m0, s18, 0x2000
	s_nop 0
	global_load_lds_dwordx4 v[192:193], off
	v_lshl_add_u64 v[192:193], v[224:225], 0, s[10:11]
	s_mov_b32 m0, s27
	s_nop 0
	global_load_lds_dwordx4 v[192:193], off
	v_lshl_add_u64 v[192:193], v[232:233], 0, s[10:11]
	s_mov_b32 m0, s28
	s_nop 0
	global_load_lds_dwordx4 v[192:193], off
	s_waitcnt vmcnt(8)
	s_waitcnt lgkmcnt(0)
	s_barrier
	s_setprio 1
	s_waitcnt lgkmcnt(0)
	v_mfma_f32_16x16x32_bf16 v[56:59], v[142:145], v[180:183], v[56:59]
	v_mfma_f32_16x16x32_bf16 v[64:67], v[156:159], v[180:183], v[64:67]
	v_mfma_f32_16x16x32_bf16 v[40:43], v[142:145], v[188:191], v[40:43]
	v_mfma_f32_16x16x32_bf16 v[48:51], v[156:159], v[188:191], v[48:51]
	v_mfma_f32_16x16x32_bf16 v[24:27], v[142:145], v[202:205], v[24:27]
	v_mfma_f32_16x16x32_bf16 v[32:35], v[156:159], v[202:205], v[32:35]
	v_mfma_f32_16x16x32_bf16 v[8:11], v[142:145], v[210:213], v[8:11]
	v_mfma_f32_16x16x32_bf16 v[16:19], v[156:159], v[210:213], v[16:19]
	v_mfma_f32_16x16x32_bf16 v[56:59], v[152:155], v[184:187], v[56:59]
	v_mfma_f32_16x16x32_bf16 v[64:67], v[160:163], v[184:187], v[64:67]
	v_mfma_f32_16x16x32_bf16 v[40:43], v[152:155], v[198:201], v[40:43]
	v_mfma_f32_16x16x32_bf16 v[48:51], v[160:163], v[198:201], v[48:51]
	v_mfma_f32_16x16x32_bf16 v[24:27], v[152:155], v[206:209], v[24:27]
	v_mfma_f32_16x16x32_bf16 v[32:35], v[160:163], v[206:209], v[32:35]
	v_mfma_f32_16x16x32_bf16 v[8:11], v[152:155], v[214:217], v[8:11]
	v_mfma_f32_16x16x32_bf16 v[16:19], v[160:163], v[214:217], v[16:19]
	s_setprio 0
	s_setprio 1
	v_mfma_f32_16x16x32_bf16 v[52:55], v[164:167], v[180:183], v[52:55]
	v_mfma_f32_16x16x32_bf16 v[60:63], v[172:175], v[180:183], v[60:63]
	v_mfma_f32_16x16x32_bf16 v[36:39], v[164:167], v[188:191], v[36:39]
	v_mfma_f32_16x16x32_bf16 v[44:47], v[172:175], v[188:191], v[44:47]
	v_mfma_f32_16x16x32_bf16 v[20:23], v[164:167], v[202:205], v[20:23]
	v_mfma_f32_16x16x32_bf16 v[28:31], v[172:175], v[202:205], v[28:31]
	v_mfma_f32_16x16x32_bf16 v[4:7], v[164:167], v[210:213], v[4:7]
	v_mfma_f32_16x16x32_bf16 v[12:15], v[172:175], v[210:213], v[12:15]
	v_mfma_f32_16x16x32_bf16 v[52:55], v[168:171], v[184:187], v[52:55]
	v_mfma_f32_16x16x32_bf16 v[60:63], v[176:179], v[184:187], v[60:63]
	v_mfma_f32_16x16x32_bf16 v[36:39], v[168:171], v[198:201], v[36:39]
	v_mfma_f32_16x16x32_bf16 v[44:47], v[176:179], v[198:201], v[44:47]
	v_mfma_f32_16x16x32_bf16 v[20:23], v[168:171], v[206:209], v[20:23]
	v_mfma_f32_16x16x32_bf16 v[28:31], v[176:179], v[206:209], v[28:31]
	v_mfma_f32_16x16x32_bf16 v[4:7], v[168:171], v[214:217], v[4:7]
	v_mfma_f32_16x16x32_bf16 v[12:15], v[176:179], v[214:217], v[12:15]
	s_setprio 0
	s_barrier
	s_add_u32 s20, s20, 0x100
	s_addc_u32 s21, s21, 0
	s_add_u32 s44, s44, 0x100
	s_addc_u32 s45, s45, 0
	s_cmp_ge_i32 s46, s29
	s_mov_b32 s18, s46
	s_cbranch_scc0 .LBB0_52
	v_readlane_b32 s47, v255, 0
	s_mov_b32 s50, s94
	s_and_b64 vcc, exec, s[12:13]
	s_cbranch_vccnz .LBB0_57
	s_branch .LBB0_58

; #define PG8_STAGE(bufoff, gbase, voff) do { _Pragma("unroll") for (int _i = 0; _i < 2; ++_i) \
;         __builtin_amdgcn_global_load_lds((const unsigned*)((const char*)(gbase) + (voff)[_i]), (PG8_LAS unsigned*)(lds + (bufoff) + ldsw + _i * 8192), 16, 0, 0); } while (0)
; #define PG8_LDA(dst, b, h) do { _Pragma("unroll") for (int m = 0; m < 4; ++m) _Pragma("unroll") for (int k = 0; k < 2; ++k) dst[m][k] = *(const PG8_LAS bf16x8*)(lds + PG8_SA(b, h) + aoff + m * 2048 + k * 1024); } while (0)
; #define PG8_LDB(dst, b, h) do { _Pragma("unroll") for (int n = 0; n < 2; ++n) _Pragma("unroll") for (int k = 0; k < 2; ++k) dst[n][k] = *(const PG8_LAS bf16x8*)(lds + PG8_SB(b, h) + boff + n * 2048 + k * 1024); } while (0)
; #define PG8_WAIT_V(n) asm volatile("s_waitcnt vmcnt(" #n ")" ::: "memory")
; #define PG8_WAIT_L(n) asm volatile("s_waitcnt lgkmcnt(" #n ")" ::: "memory")
; template <class Epi, class Sched, bool ALIGN_EPI = false, bool SP2 = false, bool ACHUNK = false>
; __device__ __forceinline__ void gemm_phase(PG8_LAS unsigned char* lds, const Gemm g, const Sched& S, const Epi& E) {
;     ...
;         const bool has_next = S.next(ui + 1, nxt);
;         const char* nA = has_next ? (const char*)g.A + (size_t)nxt.pm * tstepA : cA; const char* nB = has_next ? (const char*)g.Bt + (size_t)nxt.pn * tstepB : cB;
;         for (int t = 0; t < nt; t += 2) {
;             const bool last = (t == nt - 2);
;             if constexpr (Epi::HAS_MID) { if (t == Epi::MID_T) E.mid(acc, cur, wr, wc, fr, fq, ShflDev{}); }
;             const char* a1 = cA + (size_t)(t + 1) * kstep;
;             const char* a2 = last ? nA : cA + (size_t)(t + 2) * kstep; const char* b2 = last ? nB : cB + (size_t)(t + 2) * kstep;
;             const char* a3 = a2 + kstep; const char* b3 = b2 + kstep;
;             if (last && has_next) S.a_ready(nxt);
;             if constexpr (SP2) {
;             PG8_LDB(B0, 0, 0); PG8_LDB(B1, 0, 1); PG8_SCHED; PG8_LDA(At, 0, 0); PG8_STAGE(PG8_SA(1, 1), a1 + hstepA, voffA);
;             PG8_WAIT_V(8); PG8_WAIT_L(0); PG8_BAR; PG8_MMA(0, 0, At, B0); PG8_MMA(0, 1, At, B1); PG8_BAR; PG8_SCHED;
;     ...
;         for (int a = 0; a < 2; ++a)
; #pragma unroll
;             for (int b = 0; b < 2; ++b)
; #pragma unroll
;                 for (int m = 0; m < 4; ++m)
; #pragma unroll
;                     for (int n = 0; n < 2; ++n) acc[a][b][m][n] = (f32x4){0.f, 0.f, 0.f, 0.f};
.LBB0_106:
	s_andn2_b64 vcc, exec, s[44:45]
	s_waitcnt vmcnt(0)
	s_cbranch_vccnz .LBB0_110
	s_add_u32 s8, s4, 0x100
	s_addc_u32 s9, s5, 0
	s_add_u32 s0, s6, 0x80
	v_mov_b32_e32 v4, 0
	s_addc_u32 s1, s7, 0
	s_mov_b32 s4, 0
	v_mov_b32_e32 v5, v4
	v_mov_b32_e32 v6, v4
	v_mov_b32_e32 v7, v4
	v_mov_b32_e32 v8, v4
	v_mov_b32_e32 v9, v4
	v_mov_b32_e32 v10, v4
	v_mov_b32_e32 v11, v4
	v_mov_b32_e32 v12, v4
	v_mov_b32_e32 v13, v4
	v_mov_b32_e32 v14, v4
	v_mov_b32_e32 v15, v4
	v_mov_b32_e32 v16, v4
	v_mov_b32_e32 v17, v4
	v_mov_b32_e32 v18, v4
	v_mov_b32_e32 v19, v4
	v_mov_b32_e32 v24, v4
	v_mov_b32_e32 v25, v4
	v_mov_b32_e32 v26, v4
	v_mov_b32_e32 v27, v4
	v_mov_b32_e32 v20, v4
	v_mov_b32_e32 v21, v4
	v_mov_b32_e32 v22, v4
	v_mov_b32_e32 v23, v4
	v_mov_b32_e32 v32, v4
	v_mov_b32_e32 v33, v4
	v_mov_b32_e32 v34, v4
	v_mov_b32_e32 v35, v4
	v_mov_b32_e32 v28, v4
	v_mov_b32_e32 v29, v4
	v_mov_b32_e32 v30, v4
	v_mov_b32_e32 v31, v4
	v_mov_b32_e32 v68, v4
	v_mov_b32_e32 v69, v4
	v_mov_b32_e32 v70, v4
	v_mov_b32_e32 v71, v4
	v_mov_b32_e32 v72, v4
	v_mov_b32_e32 v73, v4
	v_mov_b32_e32 v74, v4
	v_mov_b32_e32 v75, v4
	v_mov_b32_e32 v76, v4
	v_mov_b32_e32 v77, v4
	v_mov_b32_e32 v78, v4
	v_mov_b32_e32 v79, v4
	v_mov_b32_e32 v80, v4
	v_mov_b32_e32 v81, v4
	v_mov_b32_e32 v82, v4
	v_mov_b32_e32 v83, v4
	v_mov_b32_e32 v84, v4
	v_mov_b32_e32 v85, v4
	v_mov_b32_e32 v86, v4
	v_mov_b32_e32 v87, v4
	v_mov_b32_e32 v88, v4
	v_mov_b32_e32 v89, v4
	v_mov_b32_e32 v90, v4
	v_mov_b32_e32 v91, v4
	v_mov_b32_e32 v92, v4
	v_mov_b32_e32 v93, v4
	v_mov_b32_e32 v94, v4
	v_mov_b32_e32 v95, v4
	v_mov_b32_e32 v96, v4
	v_mov_b32_e32 v97, v4
	v_mov_b32_e32 v98, v4
	v_mov_b32_e32 v99, v4
	v_mov_b32_e32 v100, v4
	v_mov_b32_e32 v101, v4
	v_mov_b32_e32 v102, v4
	v_mov_b32_e32 v103, v4
	v_mov_b32_e32 v104, v4
	v_mov_b32_e32 v105, v4
	v_mov_b32_e32 v106, v4
	v_mov_b32_e32 v107, v4
	v_mov_b32_e32 v108, v4
	v_mov_b32_e32 v109, v4
	v_mov_b32_e32 v110, v4
	v_mov_b32_e32 v111, v4
	v_mov_b32_e32 v112, v4
	v_mov_b32_e32 v113, v4
	v_mov_b32_e32 v114, v4
	v_mov_b32_e32 v115, v4
	v_mov_b32_e32 v120, v4
	v_mov_b32_e32 v121, v4
	v_mov_b32_e32 v122, v4
	v_mov_b32_e32 v123, v4
	v_mov_b32_e32 v116, v4
	v_mov_b32_e32 v117, v4
	v_mov_b32_e32 v118, v4
	v_mov_b32_e32 v119, v4
	v_mov_b32_e32 v128, v4
	v_mov_b32_e32 v129, v4
	v_mov_b32_e32 v130, v4
	v_mov_b32_e32 v131, v4
	v_mov_b32_e32 v124, v4
	v_mov_b32_e32 v125, v4
	v_mov_b32_e32 v126, v4
	v_mov_b32_e32 v127, v4
	v_mov_b32_e32 v156, v4
	v_mov_b32_e32 v157, v4
	v_mov_b32_e32 v158, v4
	v_mov_b32_e32 v159, v4
	v_mov_b32_e32 v160, v4
	v_mov_b32_e32 v161, v4
	v_mov_b32_e32 v162, v4
	v_mov_b32_e32 v163, v4
	v_mov_b32_e32 v144, v4
	v_mov_b32_e32 v145, v4
	v_mov_b32_e32 v146, v4
	v_mov_b32_e32 v147, v4
	v_mov_b32_e32 v136, v4
	v_mov_b32_e32 v137, v4
	v_mov_b32_e32 v138, v4
	v_mov_b32_e32 v139, v4
	v_mov_b32_e32 v140, v4
	v_mov_b32_e32 v141, v4
	v_mov_b32_e32 v142, v4
	v_mov_b32_e32 v143, v4
	v_mov_b32_e32 v132, v4
	v_mov_b32_e32 v133, v4
	v_mov_b32_e32 v134, v4
	v_mov_b32_e32 v135, v4
	v_mov_b32_e32 v152, v4
	v_mov_b32_e32 v153, v4
	v_mov_b32_e32 v154, v4
	v_mov_b32_e32 v155, v4
	v_mov_b32_e32 v148, v4
	v_mov_b32_e32 v149, v4
	v_mov_b32_e32 v150, v4
	v_mov_b32_e32 v151, v4
.LBB0_108:
	s_add_i32 s6, s4, 2
	s_add_u32 s7, s0, 0x80
	s_addc_u32 s5, s1, 0
	s_add_i32 s77, 0, 0x10000
	s_cmp_eq_u32 s54, s4
	s_cselect_b32 s5, s49, s5
	s_cselect_b32 s4, s48, s7
	v_add_u32_e32 v2, s77, v224
	s_cselect_b32 s79, s51, s9
	s_cselect_b32 s78, s50, s8
	s_add_i32 s7, 0, 0x14000
	s_waitcnt lgkmcnt(0)
	ds_read_b128 v[36:39], v2
	ds_read_b128 v[40:43], v2 offset:1024
	ds_read_b128 v[44:47], v2 offset:2048
	ds_read_b128 v[48:51], v2 offset:3072
	v_add_u32_e32 v2, s7, v224
	ds_read_b128 v[52:55], v2
	ds_read_b128 v[56:59], v2 offset:1024
	ds_read_b128 v[60:63], v2 offset:2048
	ds_read_b128 v[64:67], v2 offset:3072
	s_add_u32 s98, s0, s28
	s_addc_u32 s99, s1, s29
	s_add_i32 m0, s25, 0xc000
	ds_read_b128 v[164:167], v238
	ds_read_b128 v[168:171], v238 offset:1024
	ds_read_b128 v[184:187], v238 offset:2048
	ds_read_b128 v[188:191], v238 offset:3072
	ds_read_b128 v[198:201], v238 offset:4096
	ds_read_b128 v[202:205], v238 offset:5120
	ds_read_b128 v[206:209], v238 offset:6144
	ds_read_b128 v[210:213], v238 offset:7168
	global_load_lds_dwordx4 v172, s[98:99]
	s_add_i32 m0, s25, 0xe000
	s_nop 0
	global_load_lds_dwordx4 v176, s[98:99]
	s_waitcnt vmcnt(8)
	s_waitcnt lgkmcnt(0)
	s_barrier
	s_setprio 1
	s_waitcnt lgkmcnt(0)
	v_mfma_f32_16x16x32_bf16 v[148:151], v[36:39], v[164:167], v[148:151]
	v_mfma_f32_16x16x32_bf16 v[152:155], v[44:47], v[164:167], v[152:155]
	v_mfma_f32_16x16x32_bf16 v[132:135], v[36:39], v[184:187], v[132:135]
	v_mfma_f32_16x16x32_bf16 v[140:143], v[44:47], v[184:187], v[140:143]
	v_mfma_f32_16x16x32_bf16 v[136:139], v[36:39], v[198:201], v[136:139]
	v_mfma_f32_16x16x32_bf16 v[144:147], v[44:47], v[198:201], v[144:147]
	v_mfma_f32_16x16x32_bf16 v[160:163], v[36:39], v[206:209], v[160:163]
	v_mfma_f32_16x16x32_bf16 v[156:159], v[44:47], v[206:209], v[156:159]
	v_mfma_f32_16x16x32_bf16 v[148:151], v[40:43], v[168:171], v[148:151]
	v_mfma_f32_16x16x32_bf16 v[152:155], v[48:51], v[168:171], v[152:155]
	v_mfma_f32_16x16x32_bf16 v[132:135], v[40:43], v[188:191], v[132:135]
	v_mfma_f32_16x16x32_bf16 v[140:143], v[48:51], v[188:191], v[140:143]
	v_mfma_f32_16x16x32_bf16 v[136:139], v[40:43], v[202:205], v[136:139]
	v_mfma_f32_16x16x32_bf16 v[144:147], v[48:51], v[202:205], v[144:147]
	v_mfma_f32_16x16x32_bf16 v[160:163], v[40:43], v[210:213], v[160:163]
	v_mfma_f32_16x16x32_bf16 v[156:159], v[48:51], v[210:213], v[156:159]
	s_setprio 0
	s_setprio 1
	v_mfma_f32_16x16x32_bf16 v[124:127], v[52:55], v[164:167], v[124:127]
	v_mfma_f32_16x16x32_bf16 v[128:131], v[60:63], v[164:167], v[128:131]
	v_mfma_f32_16x16x32_bf16 v[116:119], v[52:55], v[184:187], v[116:119]
	v_mfma_f32_16x16x32_bf16 v[120:123], v[60:63], v[184:187], v[120:123]
	v_mfma_f32_16x16x32_bf16 v[112:115], v[52:55], v[198:201], v[112:115]
	v_mfma_f32_16x16x32_bf16 v[108:111], v[60:63], v[198:201], v[108:111]
	v_mfma_f32_16x16x32_bf16 v[104:107], v[52:55], v[206:209], v[104:107]
	v_mfma_f32_16x16x32_bf16 v[100:103], v[60:63], v[206:209], v[100:103]
	v_mfma_f32_16x16x32_bf16 v[124:127], v[56:59], v[168:171], v[124:127]
	v_mfma_f32_16x16x32_bf16 v[128:131], v[64:67], v[168:171], v[128:131]
	v_mfma_f32_16x16x32_bf16 v[116:119], v[56:59], v[188:191], v[116:119]
	v_mfma_f32_16x16x32_bf16 v[120:123], v[64:67], v[188:191], v[120:123]
	v_mfma_f32_16x16x32_bf16 v[112:115], v[56:59], v[202:205], v[112:115]
	v_mfma_f32_16x16x32_bf16 v[108:111], v[64:67], v[202:205], v[108:111]
	v_mfma_f32_16x16x32_bf16 v[104:107], v[56:59], v[210:213], v[104:107]
	v_mfma_f32_16x16x32_bf16 v[100:103], v[64:67], v[210:213], v[100:103]
	s_setprio 0
	s_barrier
; #define PG8_STAGE(bufoff, gbase, voff) do { _Pragma("unroll") for (int _i = 0; _i < 2; ++_i) \
;         __builtin_amdgcn_global_load_lds((const unsigned*)((const char*)(gbase) + (voff)[_i]), (PG8_LAS unsigned*)(lds + (bufoff) + ldsw + _i * 8192), 16, 0, 0); } while (0)
; #define PG8_LDA(dst, b, h) do { _Pragma("unroll") for (int m = 0; m < 4; ++m) _Pragma("unroll") for (int k = 0; k < 2; ++k) dst[m][k] = *(const PG8_LAS bf16x8*)(lds + PG8_SA(b, h) + aoff + m * 2048 + k * 1024); } while (0)
; #define PG8_LDB(dst, b, h) do { _Pragma("unroll") for (int n = 0; n < 2; ++n) _Pragma("unroll") for (int k = 0; k < 2; ++k) dst[n][k] = *(const PG8_LAS bf16x8*)(lds + PG8_SB(b, h) + boff + n * 2048 + k * 1024); } while (0)
; #define PG8_MMA(ai, bj, At, Bt) do { __builtin_amdgcn_s_setprio(1); _Pragma("unroll") for (int m = 0; m < 4; ++m) _Pragma("unroll") for (int n = 0; n < 2; ++n) _Pragma("unroll") for (int k = 0; k < 2; ++k) \
;         acc[ai][bj][m][n] = __builtin_amdgcn_mfma_f32_16x16x32_bf16(Bt[n][k], At[m][k], acc[ai][bj][m][n], 0, 0, 0); __builtin_amdgcn_s_setprio(0); } while (0)
; #define PG8_WAIT_V(n) asm volatile("s_waitcnt vmcnt(" #n ")" ::: "memory")
; #define PG8_WAIT_L(n) asm volatile("s_waitcnt lgkmcnt(" #n ")" ::: "memory")
; #define PG8_BAR __builtin_amdgcn_s_barrier()
; #define PG8_SCHED __builtin_amdgcn_sched_barrier(0)
; template <class Epi, class Sched, bool ALIGN_EPI = false, bool SP2 = false, bool ACHUNK = false>
; __device__ __forceinline__ void gemm_phase(PG8_LAS unsigned char* lds, const Gemm g, const Sched& S, const Epi& E) {
;     ...
;             PG8_LDA(At, 0, 1); PG8_STAGE(PG8_SB(0, 0), b2, voffB); PG8_STAGE(PG8_SB(0, 1), b2 + hstepB, voffB); PG8_STAGE(PG8_SA(0, 0), a2, voffA);
;             PG8_WAIT_V(8); PG8_WAIT_L(0); PG8_BAR; PG8_MMA(1, 0, At, B0); PG8_MMA(1, 1, At, B1); PG8_BAR; PG8_SCHED;
;             PG8_LDB(B0, 1, 0); PG8_LDB(B1, 1, 1); PG8_SCHED; PG8_LDA(At, 1, 0); PG8_STAGE(PG8_SA(0, 1), a2 + hstepA, voffA);
;             PG8_WAIT_V(8); PG8_WAIT_L(0); PG8_BAR; PG8_MMA(0, 0, At, B0); PG8_MMA(0, 1, At, B1); PG8_BAR; PG8_SCHED;
	s_add_i32 s77, s77, s17
	s_add_u32 s98, s78, s18
	s_addc_u32 s99, s79, s19
	s_mov_b32 m0, s77
	ds_read_b128 v[164:167], v238 offset:16384
	ds_read_b128 v[168:171], v238 offset:17408
	ds_read_b128 v[184:187], v238 offset:18432
	ds_read_b128 v[188:191], v238 offset:19456
	ds_read_b128 v[198:201], v238 offset:20480
	ds_read_b128 v[202:205], v238 offset:21504
	ds_read_b128 v[206:209], v238 offset:22528
	ds_read_b128 v[210:213], v238 offset:23552
	global_load_lds_dwordx4 v174, s[78:79]
	s_add_i32 m0, s77, 0x2000
	s_add_i32 s7, s7, s17
	global_load_lds_dwordx4 v178, s[78:79]
	s_mov_b32 m0, s7
	s_nop 0
	global_load_lds_dwordx4 v174, s[98:99]
	s_add_i32 m0, s7, 0x2000
	s_nop 0
	global_load_lds_dwordx4 v178, s[98:99]
	s_mov_b32 m0, s25
	s_nop 0
	global_load_lds_dwordx4 v172, s[4:5]
	s_mov_b32 m0, s26
	s_nop 0
	global_load_lds_dwordx4 v176, s[4:5]
	s_waitcnt vmcnt(8)
	s_waitcnt lgkmcnt(0)
	s_barrier
	s_setprio 1
	s_waitcnt lgkmcnt(0)
	v_mfma_f32_16x16x32_bf16 v[96:99], v[36:39], v[164:167], v[96:99]
	v_mfma_f32_16x16x32_bf16 v[92:95], v[44:47], v[164:167], v[92:95]
	v_mfma_f32_16x16x32_bf16 v[88:91], v[36:39], v[184:187], v[88:91]
	v_mfma_f32_16x16x32_bf16 v[84:87], v[44:47], v[184:187], v[84:87]
	v_mfma_f32_16x16x32_bf16 v[80:83], v[36:39], v[198:201], v[80:83]
	v_mfma_f32_16x16x32_bf16 v[76:79], v[44:47], v[198:201], v[76:79]
	v_mfma_f32_16x16x32_bf16 v[36:39], v[36:39], v[206:209], v[72:75]
	v_mfma_f32_16x16x32_bf16 v[96:99], v[40:43], v[168:171], v[96:99]
	v_mfma_f32_16x16x32_bf16 v[92:95], v[48:51], v[168:171], v[92:95]
	v_mfma_f32_16x16x32_bf16 v[88:91], v[40:43], v[188:191], v[88:91]
	v_mfma_f32_16x16x32_bf16 v[84:87], v[48:51], v[188:191], v[84:87]
	v_mfma_f32_16x16x32_bf16 v[80:83], v[40:43], v[202:205], v[80:83]
	v_mfma_f32_16x16x32_bf16 v[76:79], v[48:51], v[202:205], v[76:79]
	v_mfma_f32_16x16x32_bf16 v[36:39], v[40:43], v[210:213], v[36:39]
	v_mfma_f32_16x16x32_bf16 v[40:43], v[44:47], v[206:209], v[68:71]
	v_mfma_f32_16x16x32_bf16 v[40:43], v[48:51], v[210:213], v[40:43]
	s_setprio 0
	s_setprio 1
	v_mfma_f32_16x16x32_bf16 v[28:31], v[52:55], v[164:167], v[28:31]
	v_mfma_f32_16x16x32_bf16 v[32:35], v[60:63], v[164:167], v[32:35]
	v_mfma_f32_16x16x32_bf16 v[20:23], v[52:55], v[184:187], v[20:23]
	v_mfma_f32_16x16x32_bf16 v[24:27], v[60:63], v[184:187], v[24:27]
	v_mfma_f32_16x16x32_bf16 v[16:19], v[52:55], v[198:201], v[16:19]
	v_mfma_f32_16x16x32_bf16 v[12:15], v[60:63], v[198:201], v[12:15]
	v_mfma_f32_16x16x32_bf16 v[8:11], v[52:55], v[206:209], v[8:11]
	v_mfma_f32_16x16x32_bf16 v[4:7], v[60:63], v[206:209], v[4:7]
	v_mfma_f32_16x16x32_bf16 v[28:31], v[56:59], v[168:171], v[28:31]
	v_mfma_f32_16x16x32_bf16 v[32:35], v[64:67], v[168:171], v[32:35]
	v_mfma_f32_16x16x32_bf16 v[20:23], v[56:59], v[188:191], v[20:23]
	v_mfma_f32_16x16x32_bf16 v[24:27], v[64:67], v[188:191], v[24:27]
	v_mfma_f32_16x16x32_bf16 v[16:19], v[56:59], v[202:205], v[16:19]
	v_mfma_f32_16x16x32_bf16 v[12:15], v[64:67], v[202:205], v[12:15]
	v_mfma_f32_16x16x32_bf16 v[8:11], v[56:59], v[210:213], v[8:11]
	v_mfma_f32_16x16x32_bf16 v[4:7], v[64:67], v[210:213], v[4:7]
	s_setprio 0
	s_barrier
	s_add_i32 s7, 0, 0x18000
	v_add_u32_e32 v2, s7, v224
	s_add_i32 s77, 0, 0x1c000
	ds_read_b128 v[44:47], v2
	ds_read_b128 v[48:51], v2 offset:1024
	ds_read_b128 v[52:55], v2 offset:2048
	ds_read_b128 v[56:59], v2 offset:3072
	v_add_u32_e32 v2, s77, v224
	ds_read_b128 v[60:63], v2
	ds_read_b128 v[64:67], v2 offset:1024
	ds_read_b128 v[164:167], v2 offset:2048
	ds_read_b128 v[168:171], v2 offset:3072
	s_add_u32 s4, s4, s28
	s_addc_u32 s5, s5, s29
	s_mov_b32 m0, s27
	ds_read_b128 v[68:71], v238 offset:32768
	ds_read_b128 v[72:75], v238 offset:33792
	ds_read_b128 v[184:187], v238 offset:34816
	ds_read_b128 v[188:191], v238 offset:35840
	ds_read_b128 v[198:201], v238 offset:36864
	ds_read_b128 v[202:205], v238 offset:37888
	ds_read_b128 v[206:209], v238 offset:38912
	ds_read_b128 v[210:213], v238 offset:39936
	global_load_lds_dwordx4 v172, s[4:5]
	s_mov_b32 m0, s36
	s_nop 0
	global_load_lds_dwordx4 v176, s[4:5]
	s_waitcnt vmcnt(8)
	s_waitcnt lgkmcnt(0)
	s_barrier
; #define PG8_STAGE(bufoff, gbase, voff) do { _Pragma("unroll") for (int _i = 0; _i < 2; ++_i) \
;         __builtin_amdgcn_global_load_lds((const unsigned*)((const char*)(gbase) + (voff)[_i]), (PG8_LAS unsigned*)(lds + (bufoff) + ldsw + _i * 8192), 16, 0, 0); } while (0)
; #define PG8_LDA(dst, b, h) do { _Pragma("unroll") for (int m = 0; m < 4; ++m) _Pragma("unroll") for (int k = 0; k < 2; ++k) dst[m][k] = *(const PG8_LAS bf16x8*)(lds + PG8_SA(b, h) + aoff + m * 2048 + k * 1024); } while (0)
; #define PG8_MMA(ai, bj, At, Bt) do { __builtin_amdgcn_s_setprio(1); _Pragma("unroll") for (int m = 0; m < 4; ++m) _Pragma("unroll") for (int n = 0; n < 2; ++n) _Pragma("unroll") for (int k = 0; k < 2; ++k) \
;         acc[ai][bj][m][n] = __builtin_amdgcn_mfma_f32_16x16x32_bf16(Bt[n][k], At[m][k], acc[ai][bj][m][n], 0, 0, 0); __builtin_amdgcn_s_setprio(0); } while (0)
; #define PG8_WAIT_V(n) asm volatile("s_waitcnt vmcnt(" #n ")" ::: "memory")
; #define PG8_WAIT_L(n) asm volatile("s_waitcnt lgkmcnt(" #n ")" ::: "memory")
; #define PG8_BAR __builtin_amdgcn_s_barrier()
; #define PG8_SCHED __builtin_amdgcn_sched_barrier(0)
; template <class Epi, class Sched, bool ALIGN_EPI = false, bool SP2 = false, bool ACHUNK = false>
; __device__ __forceinline__ void gemm_phase(PG8_LAS unsigned char* lds, const Gemm g, const Sched& S, const Epi& E) {
;     ...
;             PG8_WAIT_V(8); PG8_WAIT_L(0); PG8_BAR; PG8_MMA(0, 0, At, B0); PG8_MMA(0, 1, At, B1); PG8_BAR; PG8_SCHED;
;             PG8_LDA(At, 1, 1); PG8_STAGE(PG8_SB(1, 0), b3, voffB); PG8_STAGE(PG8_SB(1, 1), b3 + hstepB, voffB); PG8_STAGE(PG8_SA(1, 0), a3, voffA);
;             PG8_WAIT_V(8); PG8_WAIT_L(0); PG8_BAR; PG8_MMA(1, 0, At, B0); PG8_MMA(1, 1, At, B1); PG8_BAR; PG8_SCHED;
	s_setprio 1
	s_waitcnt lgkmcnt(0)
	v_mfma_f32_16x16x32_bf16 v[148:151], v[44:47], v[68:71], v[148:151]
	v_mfma_f32_16x16x32_bf16 v[152:155], v[52:55], v[68:71], v[152:155]
	v_mfma_f32_16x16x32_bf16 v[132:135], v[44:47], v[184:187], v[132:135]
	v_mfma_f32_16x16x32_bf16 v[140:143], v[52:55], v[184:187], v[140:143]
	v_mfma_f32_16x16x32_bf16 v[136:139], v[44:47], v[198:201], v[136:139]
	v_mfma_f32_16x16x32_bf16 v[144:147], v[52:55], v[198:201], v[144:147]
	v_mfma_f32_16x16x32_bf16 v[160:163], v[44:47], v[206:209], v[160:163]
	v_mfma_f32_16x16x32_bf16 v[156:159], v[52:55], v[206:209], v[156:159]
	v_mfma_f32_16x16x32_bf16 v[148:151], v[48:51], v[72:75], v[148:151]
	v_mfma_f32_16x16x32_bf16 v[152:155], v[56:59], v[72:75], v[152:155]
	v_mfma_f32_16x16x32_bf16 v[132:135], v[48:51], v[188:191], v[132:135]
	v_mfma_f32_16x16x32_bf16 v[140:143], v[56:59], v[188:191], v[140:143]
	v_mfma_f32_16x16x32_bf16 v[136:139], v[48:51], v[202:205], v[136:139]
	v_mfma_f32_16x16x32_bf16 v[144:147], v[56:59], v[202:205], v[144:147]
	v_mfma_f32_16x16x32_bf16 v[160:163], v[48:51], v[210:213], v[160:163]
	v_mfma_f32_16x16x32_bf16 v[156:159], v[56:59], v[210:213], v[156:159]
	s_setprio 0
	s_setprio 1
	v_mfma_f32_16x16x32_bf16 v[124:127], v[60:63], v[68:71], v[124:127]
	v_mfma_f32_16x16x32_bf16 v[68:71], v[164:167], v[68:71], v[128:131]
	v_mfma_f32_16x16x32_bf16 v[128:131], v[168:171], v[72:75], v[68:71]
	v_mfma_f32_16x16x32_bf16 v[68:71], v[60:63], v[184:187], v[116:119]
	v_mfma_f32_16x16x32_bf16 v[116:119], v[64:67], v[188:191], v[68:71]
	v_mfma_f32_16x16x32_bf16 v[68:71], v[164:167], v[184:187], v[120:123]
	v_mfma_f32_16x16x32_bf16 v[120:123], v[168:171], v[188:191], v[68:71]
	v_mfma_f32_16x16x32_bf16 v[68:71], v[60:63], v[198:201], v[112:115]
	v_mfma_f32_16x16x32_bf16 v[112:115], v[64:67], v[202:205], v[68:71]
	v_mfma_f32_16x16x32_bf16 v[68:71], v[164:167], v[198:201], v[108:111]
	v_mfma_f32_16x16x32_bf16 v[108:111], v[168:171], v[202:205], v[68:71]
	v_mfma_f32_16x16x32_bf16 v[68:71], v[60:63], v[206:209], v[104:107]
	v_mfma_f32_16x16x32_bf16 v[104:107], v[64:67], v[210:213], v[68:71]
	v_mfma_f32_16x16x32_bf16 v[68:71], v[164:167], v[206:209], v[100:103]
	v_mfma_f32_16x16x32_bf16 v[124:127], v[64:67], v[72:75], v[124:127]
	v_mfma_f32_16x16x32_bf16 v[100:103], v[168:171], v[210:213], v[68:71]
	s_setprio 0
	s_barrier
	s_sub_u32 s4, s4, s28
	s_subb_u32 s5, s5, s29
	s_add_u32 s4, s4, s10
	s_addc_u32 s5, s5, s11
	s_add_u32 s78, s78, s10
	s_addc_u32 s79, s79, s11
	s_add_u32 s98, s98, s10
	s_addc_u32 s99, s99, s11
	s_add_i32 m0, s7, s17
	ds_read_b128 v[184:187], v238 offset:49152
	ds_read_b128 v[188:191], v238 offset:50176
	ds_read_b128 v[198:201], v238 offset:51200
	ds_read_b128 v[202:205], v238 offset:52224
	ds_read_b128 v[206:209], v238 offset:53248
	ds_read_b128 v[210:213], v238 offset:54272
	ds_read_b128 v[214:217], v238 offset:55296
	ds_read_b128 v[218:221], v238 offset:56320
	global_load_lds_dwordx4 v174, s[78:79]
	s_add_i32 m0, m0, 0x2000
	s_nop 0
	global_load_lds_dwordx4 v178, s[78:79]
	s_add_i32 m0, s77, s17
	s_nop 0
	global_load_lds_dwordx4 v174, s[98:99]
	s_add_i32 m0, m0, 0x2000
	s_nop 0
	global_load_lds_dwordx4 v178, s[98:99]
	s_mov_b32 m0, s52
	s_nop 0
	global_load_lds_dwordx4 v172, s[4:5]
	s_mov_b32 m0, s53
	s_nop 0
	global_load_lds_dwordx4 v176, s[4:5]
	s_waitcnt vmcnt(8)
	s_waitcnt lgkmcnt(0)
	s_barrier
	s_setprio 1
	s_waitcnt lgkmcnt(0)
	v_mfma_f32_16x16x32_bf16 v[68:71], v[44:47], v[184:187], v[96:99]
	v_mfma_f32_16x16x32_bf16 v[96:99], v[48:51], v[188:191], v[68:71]
	v_mfma_f32_16x16x32_bf16 v[68:71], v[52:55], v[184:187], v[92:95]
	v_mfma_f32_16x16x32_bf16 v[92:95], v[56:59], v[188:191], v[68:71]
	v_mfma_f32_16x16x32_bf16 v[68:71], v[44:47], v[198:201], v[88:91]
	v_mfma_f32_16x16x32_bf16 v[88:91], v[48:51], v[202:205], v[68:71]
	v_mfma_f32_16x16x32_bf16 v[68:71], v[52:55], v[198:201], v[84:87]
	v_mfma_f32_16x16x32_bf16 v[84:87], v[56:59], v[202:205], v[68:71]
	v_mfma_f32_16x16x32_bf16 v[68:71], v[44:47], v[206:209], v[80:83]
	v_mfma_f32_16x16x32_bf16 v[36:39], v[44:47], v[214:217], v[36:39]
	v_mfma_f32_16x16x32_bf16 v[80:83], v[48:51], v[210:213], v[68:71]
	v_mfma_f32_16x16x32_bf16 v[68:71], v[52:55], v[206:209], v[76:79]
	v_mfma_f32_16x16x32_bf16 v[72:75], v[48:51], v[218:221], v[36:39]
	v_mfma_f32_16x16x32_bf16 v[36:39], v[52:55], v[214:217], v[40:43]
	v_mfma_f32_16x16x32_bf16 v[76:79], v[56:59], v[210:213], v[68:71]
	v_mfma_f32_16x16x32_bf16 v[68:71], v[56:59], v[218:221], v[36:39]
	s_setprio 0
	s_setprio 1
	v_mfma_f32_16x16x32_bf16 v[28:31], v[60:63], v[184:187], v[28:31]
	v_mfma_f32_16x16x32_bf16 v[32:35], v[164:167], v[184:187], v[32:35]
	v_mfma_f32_16x16x32_bf16 v[20:23], v[60:63], v[198:201], v[20:23]
	v_mfma_f32_16x16x32_bf16 v[24:27], v[164:167], v[198:201], v[24:27]
	v_mfma_f32_16x16x32_bf16 v[16:19], v[60:63], v[206:209], v[16:19]
	v_mfma_f32_16x16x32_bf16 v[12:15], v[164:167], v[206:209], v[12:15]
	v_mfma_f32_16x16x32_bf16 v[8:11], v[60:63], v[214:217], v[8:11]
	v_mfma_f32_16x16x32_bf16 v[4:7], v[164:167], v[214:217], v[4:7]
	v_mfma_f32_16x16x32_bf16 v[28:31], v[64:67], v[188:191], v[28:31]
	v_mfma_f32_16x16x32_bf16 v[32:35], v[168:171], v[188:191], v[32:35]
	v_mfma_f32_16x16x32_bf16 v[20:23], v[64:67], v[202:205], v[20:23]
	v_mfma_f32_16x16x32_bf16 v[24:27], v[168:171], v[202:205], v[24:27]
	v_mfma_f32_16x16x32_bf16 v[16:19], v[64:67], v[210:213], v[16:19]
	v_mfma_f32_16x16x32_bf16 v[12:15], v[168:171], v[210:213], v[12:15]
	v_mfma_f32_16x16x32_bf16 v[8:11], v[64:67], v[218:221], v[8:11]
	v_mfma_f32_16x16x32_bf16 v[4:7], v[168:171], v[218:221], v[4:7]
	s_setprio 0
	s_barrier
	s_add_u32 s8, s8, 0x100
	s_addc_u32 s9, s9, 0
	s_add_u32 s0, s0, 0x100
	s_addc_u32 s1, s1, 0
	s_cmp_ge_i32 s6, s37
	s_mov_b32 s4, s6
	s_cbranch_scc0 .LBB0_108
	v_readlane_b32 s78, v254, 23
	v_readlane_b32 s79, v254, 24

; #define PG8_STAGE(bufoff, gbase, voff) do { _Pragma("unroll") for (int _i = 0; _i < 2; ++_i) \
;         __builtin_amdgcn_global_load_lds((const unsigned*)((const char*)(gbase) + (voff)[_i]), (PG8_LAS unsigned*)(lds + (bufoff) + ldsw + _i * 8192), 16, 0, 0); } while (0)
; #define PG8_LDA(dst, b, h) do { _Pragma("unroll") for (int m = 0; m < 4; ++m) _Pragma("unroll") for (int k = 0; k < 2; ++k) dst[m][k] = *(const PG8_LAS bf16x8*)(lds + PG8_SA(b, h) + aoff + m * 2048 + k * 1024); } while (0)
; #define PG8_LDB(dst, b, h) do { _Pragma("unroll") for (int n = 0; n < 2; ++n) _Pragma("unroll") for (int k = 0; k < 2; ++k) dst[n][k] = *(const PG8_LAS bf16x8*)(lds + PG8_SB(b, h) + boff + n * 2048 + k * 1024); } while (0)
; #define PG8_WAIT_V(n) asm volatile("s_waitcnt vmcnt(" #n ")" ::: "memory")
; #define PG8_WAIT_L(n) asm volatile("s_waitcnt lgkmcnt(" #n ")" ::: "memory")
; template <class Epi, class Sched, bool ALIGN_EPI = false, bool SP2 = false, bool ACHUNK = false>
; __device__ __forceinline__ void gemm_phase(PG8_LAS unsigned char* lds, const Gemm g, const Sched& S, const Epi& E) {
;     ...
;         const bool has_next = S.next(ui + 1, nxt);
;         const char* nA = has_next ? (const char*)g.A + (size_t)nxt.pm * tstepA : cA; const char* nB = has_next ? (const char*)g.Bt + (size_t)nxt.pn * tstepB : cB;
;         for (int t = 0; t < nt; t += 2) {
;             const bool last = (t == nt - 2);
;             if constexpr (Epi::HAS_MID) { if (t == Epi::MID_T) E.mid(acc, cur, wr, wc, fr, fq, ShflDev{}); }
;             const char* a1 = cA + (size_t)(t + 1) * kstep;
;             const char* a2 = last ? nA : cA + (size_t)(t + 2) * kstep; const char* b2 = last ? nB : cB + (size_t)(t + 2) * kstep;
;             const char* a3 = a2 + kstep; const char* b3 = b2 + kstep;
;             if (last && has_next) S.a_ready(nxt);
;             if constexpr (SP2) {
;             PG8_LDB(B0, 0, 0); PG8_LDB(B1, 0, 1); PG8_SCHED; PG8_LDA(At, 0, 0); PG8_STAGE(PG8_SA(1, 1), a1 + hstepA, voffA);
;             PG8_WAIT_V(8); PG8_WAIT_L(0); PG8_BAR; PG8_MMA(0, 0, At, B0); PG8_MMA(0, 1, At, B1); PG8_BAR; PG8_SCHED;
;             PG8_LDA(At, 0, 1); PG8_STAGE(PG8_SB(0, 0), b2, voffB); PG8_STAGE(PG8_SB(0, 1), b2 + hstepB, voffB); PG8_STAGE(PG8_SA(0, 0), a2, voffA);
;             PG8_WAIT_V(8); PG8_WAIT_L(0); PG8_BAR; PG8_MMA(1, 0, At, B0); PG8_MMA(1, 1, At, B1); PG8_BAR; PG8_SCHED;
.LBB0_216:
	s_add_i32 s50, s22, 2
	s_add_u32 s51, s20, 0x80
	s_addc_u32 s23, s21, 0
	s_add_i32 s54, 0, 0x10000
	s_cmp_eq_u32 s35, s22
	s_cselect_b32 s23, s1, s23
	s_cselect_b32 s22, s0, s51
	v_add_u32_e32 v151, s54, v147
	s_cselect_b32 s53, s19, s49
	s_cselect_b32 s52, s18, s48
	s_cbranch_scc0 .Lnl_wo
	s_cmpk_lg_u32 s87, 0x100
	s_cbranch_scc1 .Lnl_wo
	v_mov_b32_e32 v2, 0
	v_mov_b32_e32 v136, 0
	v_mov_b32_e32 v132, 0
	v_mov_b32_e32 v134, 0
.Lnl_wo:
	s_add_i32 s51, 0, 0x14000
	ds_read_b128 v[142:145], v151
	ds_read_b128 v[152:155], v151 offset:1024
	ds_read_b128 v[156:159], v151 offset:2048
	ds_read_b128 v[160:163], v151 offset:3072
	v_add_u32_e32 v151, s51, v147
	ds_read_b128 v[164:167], v151
	ds_read_b128 v[168:171], v151 offset:1024
	ds_read_b128 v[172:175], v151 offset:2048
	ds_read_b128 v[176:179], v151 offset:3072
	v_lshl_add_u64 v[192:193], s[20:21], 0, v[138:139]
	s_add_i32 m0, s27, 0xc000
	ds_read_b128 v[180:183], v149
	ds_read_b128 v[184:187], v149 offset:1024
	ds_read_b128 v[188:191], v149 offset:2048
	ds_read_b128 v[198:201], v149 offset:3072
	ds_read_b128 v[202:205], v149 offset:4096
	ds_read_b128 v[206:209], v149 offset:5120
	ds_read_b128 v[210:213], v149 offset:6144
	ds_read_b128 v[214:217], v149 offset:7168
	global_load_lds_dwordx4 v[192:193], off
	v_lshl_add_u64 v[192:193], s[20:21], 0, v[140:141]
	s_add_i32 m0, s27, 0xe000
	s_nop 0
	global_load_lds_dwordx4 v[192:193], off
	s_waitcnt vmcnt(8)
	s_waitcnt lgkmcnt(0)
	s_barrier
	s_setprio 1
	s_waitcnt lgkmcnt(0)
	v_mfma_f32_16x16x32_bf16 v[120:123], v[142:145], v[180:183], v[120:123]
	v_mfma_f32_16x16x32_bf16 v[128:131], v[156:159], v[180:183], v[128:131]
	v_mfma_f32_16x16x32_bf16 v[104:107], v[142:145], v[188:191], v[104:107]
	v_mfma_f32_16x16x32_bf16 v[112:115], v[156:159], v[188:191], v[112:115]
	v_mfma_f32_16x16x32_bf16 v[88:91], v[142:145], v[202:205], v[88:91]
	v_mfma_f32_16x16x32_bf16 v[96:99], v[156:159], v[202:205], v[96:99]
	v_mfma_f32_16x16x32_bf16 v[72:75], v[142:145], v[210:213], v[72:75]
	v_mfma_f32_16x16x32_bf16 v[80:83], v[156:159], v[210:213], v[80:83]
	v_mfma_f32_16x16x32_bf16 v[120:123], v[152:155], v[184:187], v[120:123]
	v_mfma_f32_16x16x32_bf16 v[128:131], v[160:163], v[184:187], v[128:131]
	v_mfma_f32_16x16x32_bf16 v[104:107], v[152:155], v[198:201], v[104:107]
	v_mfma_f32_16x16x32_bf16 v[112:115], v[160:163], v[198:201], v[112:115]
	v_mfma_f32_16x16x32_bf16 v[88:91], v[152:155], v[206:209], v[88:91]
	v_mfma_f32_16x16x32_bf16 v[96:99], v[160:163], v[206:209], v[96:99]
	v_mfma_f32_16x16x32_bf16 v[72:75], v[152:155], v[214:217], v[72:75]
	v_mfma_f32_16x16x32_bf16 v[80:83], v[160:163], v[214:217], v[80:83]
	s_setprio 0
	s_setprio 1
	v_mfma_f32_16x16x32_bf16 v[116:119], v[164:167], v[180:183], v[116:119]
	v_mfma_f32_16x16x32_bf16 v[124:127], v[172:175], v[180:183], v[124:127]
	v_mfma_f32_16x16x32_bf16 v[100:103], v[164:167], v[188:191], v[100:103]
	v_mfma_f32_16x16x32_bf16 v[108:111], v[172:175], v[188:191], v[108:111]
	v_mfma_f32_16x16x32_bf16 v[84:87], v[164:167], v[202:205], v[84:87]
	v_mfma_f32_16x16x32_bf16 v[92:95], v[172:175], v[202:205], v[92:95]
	v_mfma_f32_16x16x32_bf16 v[68:71], v[164:167], v[210:213], v[68:71]
	v_mfma_f32_16x16x32_bf16 v[76:79], v[172:175], v[210:213], v[76:79]
	v_mfma_f32_16x16x32_bf16 v[116:119], v[168:171], v[184:187], v[116:119]
	v_mfma_f32_16x16x32_bf16 v[124:127], v[176:179], v[184:187], v[124:127]
	v_mfma_f32_16x16x32_bf16 v[100:103], v[168:171], v[198:201], v[100:103]
	v_mfma_f32_16x16x32_bf16 v[108:111], v[176:179], v[198:201], v[108:111]
	v_mfma_f32_16x16x32_bf16 v[84:87], v[168:171], v[206:209], v[84:87]
	v_mfma_f32_16x16x32_bf16 v[92:95], v[176:179], v[206:209], v[92:95]
	v_mfma_f32_16x16x32_bf16 v[68:71], v[168:171], v[214:217], v[68:71]
	v_mfma_f32_16x16x32_bf16 v[76:79], v[176:179], v[214:217], v[76:79]
	s_setprio 0
	s_barrier
	s_add_i32 s54, s54, s26
	v_lshl_add_u64 v[192:193], s[52:53], 0, v[2:3]
	s_mov_b32 m0, s54
	ds_read_b128 v[180:183], v149 offset:16384
	ds_read_b128 v[184:187], v149 offset:17408
	ds_read_b128 v[188:191], v149 offset:18432
	ds_read_b128 v[198:201], v149 offset:19456
	ds_read_b128 v[202:205], v149 offset:20480
	ds_read_b128 v[206:209], v149 offset:21504
	ds_read_b128 v[210:213], v149 offset:22528
	ds_read_b128 v[214:217], v149 offset:23552
	global_load_lds_dwordx4 v[192:193], off
	s_add_i32 m0, s54, 0x2000
	v_lshl_add_u64 v[218:219], s[52:53], 0, v[136:137]
	s_add_u32 s52, s52, s4
	s_addc_u32 s53, s53, s5
	s_add_i32 s51, s51, s26
	global_load_lds_dwordx4 v[218:219], off
	v_lshl_add_u64 v[220:221], s[52:53], 0, v[2:3]
	s_mov_b32 m0, s51
	v_lshl_add_u64 v[222:223], s[52:53], 0, v[136:137]
	global_load_lds_dwordx4 v[220:221], off
	s_add_i32 m0, s51, 0x2000
	v_lshl_add_u64 v[224:225], s[22:23], 0, v[132:133]
	global_load_lds_dwordx4 v[222:223], off
	s_mov_b32 m0, s27
	v_lshl_add_u64 v[232:233], s[22:23], 0, v[134:135]
	global_load_lds_dwordx4 v[224:225], off
	s_mov_b32 m0, s28
	s_nop 0
	global_load_lds_dwordx4 v[232:233], off
	s_waitcnt vmcnt(8)
	s_waitcnt lgkmcnt(0)
	s_barrier
; #define PG8_STAGE(bufoff, gbase, voff) do { _Pragma("unroll") for (int _i = 0; _i < 2; ++_i) \
;         __builtin_amdgcn_global_load_lds((const unsigned*)((const char*)(gbase) + (voff)[_i]), (PG8_LAS unsigned*)(lds + (bufoff) + ldsw + _i * 8192), 16, 0, 0); } while (0)
; #define PG8_LDA(dst, b, h) do { _Pragma("unroll") for (int m = 0; m < 4; ++m) _Pragma("unroll") for (int k = 0; k < 2; ++k) dst[m][k] = *(const PG8_LAS bf16x8*)(lds + PG8_SA(b, h) + aoff + m * 2048 + k * 1024); } while (0)
; #define PG8_LDB(dst, b, h) do { _Pragma("unroll") for (int n = 0; n < 2; ++n) _Pragma("unroll") for (int k = 0; k < 2; ++k) dst[n][k] = *(const PG8_LAS bf16x8*)(lds + PG8_SB(b, h) + boff + n * 2048 + k * 1024); } while (0)
; #define PG8_MMA(ai, bj, At, Bt) do { __builtin_amdgcn_s_setprio(1); _Pragma("unroll") for (int m = 0; m < 4; ++m) _Pragma("unroll") for (int n = 0; n < 2; ++n) _Pragma("unroll") for (int k = 0; k < 2; ++k) \
;         acc[ai][bj][m][n] = __builtin_amdgcn_mfma_f32_16x16x32_bf16(Bt[n][k], At[m][k], acc[ai][bj][m][n], 0, 0, 0); __builtin_amdgcn_s_setprio(0); } while (0)
; #define PG8_WAIT_V(n) asm volatile("s_waitcnt vmcnt(" #n ")" ::: "memory")
; #define PG8_WAIT_L(n) asm volatile("s_waitcnt lgkmcnt(" #n ")" ::: "memory")
; #define PG8_BAR __builtin_amdgcn_s_barrier()
; #define PG8_SCHED __builtin_amdgcn_sched_barrier(0)
; template <class Epi, class Sched, bool ALIGN_EPI = false, bool SP2 = false, bool ACHUNK = false>
; __device__ __forceinline__ void gemm_phase(PG8_LAS unsigned char* lds, const Gemm g, const Sched& S, const Epi& E) {
;     ...
;             PG8_WAIT_V(8); PG8_WAIT_L(0); PG8_BAR; PG8_MMA(1, 0, At, B0); PG8_MMA(1, 1, At, B1); PG8_BAR; PG8_SCHED;
;             PG8_LDB(B0, 1, 0); PG8_LDB(B1, 1, 1); PG8_SCHED; PG8_LDA(At, 1, 0); PG8_STAGE(PG8_SA(0, 1), a2 + hstepA, voffA);
;             PG8_WAIT_V(8); PG8_WAIT_L(0); PG8_BAR; PG8_MMA(0, 0, At, B0); PG8_MMA(0, 1, At, B1); PG8_BAR; PG8_SCHED;
	s_setprio 1
	s_waitcnt lgkmcnt(0)
	v_mfma_f32_16x16x32_bf16 v[56:59], v[142:145], v[180:183], v[56:59]
	v_mfma_f32_16x16x32_bf16 v[64:67], v[156:159], v[180:183], v[64:67]
	v_mfma_f32_16x16x32_bf16 v[40:43], v[142:145], v[188:191], v[40:43]
	v_mfma_f32_16x16x32_bf16 v[48:51], v[156:159], v[188:191], v[48:51]
	v_mfma_f32_16x16x32_bf16 v[24:27], v[142:145], v[202:205], v[24:27]
	v_mfma_f32_16x16x32_bf16 v[32:35], v[156:159], v[202:205], v[32:35]
	v_mfma_f32_16x16x32_bf16 v[8:11], v[142:145], v[210:213], v[8:11]
	v_mfma_f32_16x16x32_bf16 v[16:19], v[156:159], v[210:213], v[16:19]
	v_mfma_f32_16x16x32_bf16 v[56:59], v[152:155], v[184:187], v[56:59]
	v_mfma_f32_16x16x32_bf16 v[64:67], v[160:163], v[184:187], v[64:67]
	v_mfma_f32_16x16x32_bf16 v[40:43], v[152:155], v[198:201], v[40:43]
	v_mfma_f32_16x16x32_bf16 v[48:51], v[160:163], v[198:201], v[48:51]
	v_mfma_f32_16x16x32_bf16 v[24:27], v[152:155], v[206:209], v[24:27]
	v_mfma_f32_16x16x32_bf16 v[32:35], v[160:163], v[206:209], v[32:35]
	v_mfma_f32_16x16x32_bf16 v[8:11], v[152:155], v[214:217], v[8:11]
	v_mfma_f32_16x16x32_bf16 v[16:19], v[160:163], v[214:217], v[16:19]
	s_setprio 0
	s_setprio 1
	v_mfma_f32_16x16x32_bf16 v[52:55], v[164:167], v[180:183], v[52:55]
	v_mfma_f32_16x16x32_bf16 v[60:63], v[172:175], v[180:183], v[60:63]
	v_mfma_f32_16x16x32_bf16 v[36:39], v[164:167], v[188:191], v[36:39]
	v_mfma_f32_16x16x32_bf16 v[44:47], v[172:175], v[188:191], v[44:47]
	v_mfma_f32_16x16x32_bf16 v[20:23], v[164:167], v[202:205], v[20:23]
	v_mfma_f32_16x16x32_bf16 v[28:31], v[172:175], v[202:205], v[28:31]
	v_mfma_f32_16x16x32_bf16 v[4:7], v[164:167], v[210:213], v[4:7]
	v_mfma_f32_16x16x32_bf16 v[12:15], v[172:175], v[210:213], v[12:15]
	v_mfma_f32_16x16x32_bf16 v[52:55], v[168:171], v[184:187], v[52:55]
	v_mfma_f32_16x16x32_bf16 v[60:63], v[176:179], v[184:187], v[60:63]
	v_mfma_f32_16x16x32_bf16 v[36:39], v[168:171], v[198:201], v[36:39]
	v_mfma_f32_16x16x32_bf16 v[44:47], v[176:179], v[198:201], v[44:47]
	v_mfma_f32_16x16x32_bf16 v[20:23], v[168:171], v[206:209], v[20:23]
	v_mfma_f32_16x16x32_bf16 v[28:31], v[176:179], v[206:209], v[28:31]
	v_mfma_f32_16x16x32_bf16 v[4:7], v[168:171], v[214:217], v[4:7]
	v_mfma_f32_16x16x32_bf16 v[12:15], v[176:179], v[214:217], v[12:15]
	s_setprio 0
	s_barrier
	s_add_i32 s51, 0, 0x18000
	v_add_u32_e32 v151, s51, v147
	s_add_i32 s52, 0, 0x1c000
	ds_read_b128 v[142:145], v151
	ds_read_b128 v[152:155], v151 offset:1024
	ds_read_b128 v[156:159], v151 offset:2048
	ds_read_b128 v[160:163], v151 offset:3072
	v_add_u32_e32 v151, s52, v147
	ds_read_b128 v[164:167], v151
	ds_read_b128 v[168:171], v151 offset:1024
	ds_read_b128 v[172:175], v151 offset:2048
	ds_read_b128 v[176:179], v151 offset:3072
	s_add_u32 s22, s22, s4
	s_addc_u32 s23, s23, s5
	s_mov_b32 m0, s29
	v_lshl_add_u64 v[234:235], s[22:23], 0, v[132:133]
	ds_read_b128 v[180:183], v149 offset:32768
	ds_read_b128 v[184:187], v149 offset:33792
	ds_read_b128 v[188:191], v149 offset:34816
	ds_read_b128 v[198:201], v149 offset:35840
	ds_read_b128 v[202:205], v149 offset:36864
	ds_read_b128 v[206:209], v149 offset:37888
	ds_read_b128 v[210:213], v149 offset:38912
	ds_read_b128 v[214:217], v149 offset:39936
	global_load_lds_dwordx4 v[234:235], off
	v_lshl_add_u64 v[234:235], s[22:23], 0, v[134:135]
	s_mov_b32 m0, s30
	s_nop 0
	global_load_lds_dwordx4 v[234:235], off
	s_waitcnt vmcnt(8)
	s_waitcnt lgkmcnt(0)
	s_barrier
	s_setprio 1
	s_waitcnt lgkmcnt(0)
	v_mfma_f32_16x16x32_bf16 v[120:123], v[142:145], v[180:183], v[120:123]
	v_mfma_f32_16x16x32_bf16 v[128:131], v[156:159], v[180:183], v[128:131]
	v_mfma_f32_16x16x32_bf16 v[104:107], v[142:145], v[188:191], v[104:107]
	v_mfma_f32_16x16x32_bf16 v[112:115], v[156:159], v[188:191], v[112:115]
	v_mfma_f32_16x16x32_bf16 v[88:91], v[142:145], v[202:205], v[88:91]
	v_mfma_f32_16x16x32_bf16 v[96:99], v[156:159], v[202:205], v[96:99]
	v_mfma_f32_16x16x32_bf16 v[72:75], v[142:145], v[210:213], v[72:75]
	v_mfma_f32_16x16x32_bf16 v[80:83], v[156:159], v[210:213], v[80:83]
	v_mfma_f32_16x16x32_bf16 v[120:123], v[152:155], v[184:187], v[120:123]
	v_mfma_f32_16x16x32_bf16 v[128:131], v[160:163], v[184:187], v[128:131]
	v_mfma_f32_16x16x32_bf16 v[104:107], v[152:155], v[198:201], v[104:107]
	v_mfma_f32_16x16x32_bf16 v[112:115], v[160:163], v[198:201], v[112:115]
	v_mfma_f32_16x16x32_bf16 v[88:91], v[152:155], v[206:209], v[88:91]
	v_mfma_f32_16x16x32_bf16 v[96:99], v[160:163], v[206:209], v[96:99]
	v_mfma_f32_16x16x32_bf16 v[72:75], v[152:155], v[214:217], v[72:75]
	v_mfma_f32_16x16x32_bf16 v[80:83], v[160:163], v[214:217], v[80:83]
	s_setprio 0
	s_setprio 1
	v_mfma_f32_16x16x32_bf16 v[116:119], v[164:167], v[180:183], v[116:119]
	v_mfma_f32_16x16x32_bf16 v[124:127], v[172:175], v[180:183], v[124:127]
	v_mfma_f32_16x16x32_bf16 v[100:103], v[164:167], v[188:191], v[100:103]
	v_mfma_f32_16x16x32_bf16 v[108:111], v[172:175], v[188:191], v[108:111]
	v_mfma_f32_16x16x32_bf16 v[84:87], v[164:167], v[202:205], v[84:87]
	v_mfma_f32_16x16x32_bf16 v[92:95], v[172:175], v[202:205], v[92:95]
	v_mfma_f32_16x16x32_bf16 v[68:71], v[164:167], v[210:213], v[68:71]
	v_mfma_f32_16x16x32_bf16 v[76:79], v[172:175], v[210:213], v[76:79]
	v_mfma_f32_16x16x32_bf16 v[116:119], v[168:171], v[184:187], v[116:119]
	v_mfma_f32_16x16x32_bf16 v[124:127], v[176:179], v[184:187], v[124:127]
	v_mfma_f32_16x16x32_bf16 v[100:103], v[168:171], v[198:201], v[100:103]
	v_mfma_f32_16x16x32_bf16 v[108:111], v[176:179], v[198:201], v[108:111]
	v_mfma_f32_16x16x32_bf16 v[84:87], v[168:171], v[206:209], v[84:87]
	v_mfma_f32_16x16x32_bf16 v[92:95], v[176:179], v[206:209], v[92:95]
	v_mfma_f32_16x16x32_bf16 v[68:71], v[168:171], v[214:217], v[68:71]
	v_mfma_f32_16x16x32_bf16 v[76:79], v[176:179], v[214:217], v[76:79]
	s_setprio 0
	s_barrier
; #define PG8_STAGE(bufoff, gbase, voff) do { _Pragma("unroll") for (int _i = 0; _i < 2; ++_i) \
;         __builtin_amdgcn_global_load_lds((const unsigned*)((const char*)(gbase) + (voff)[_i]), (PG8_LAS unsigned*)(lds + (bufoff) + ldsw + _i * 8192), 16, 0, 0); } while (0)
; #define PG8_LDA(dst, b, h) do { _Pragma("unroll") for (int m = 0; m < 4; ++m) _Pragma("unroll") for (int k = 0; k < 2; ++k) dst[m][k] = *(const PG8_LAS bf16x8*)(lds + PG8_SA(b, h) + aoff + m * 2048 + k * 1024); } while (0)
; #define PG8_MMA(ai, bj, At, Bt) do { __builtin_amdgcn_s_setprio(1); _Pragma("unroll") for (int m = 0; m < 4; ++m) _Pragma("unroll") for (int n = 0; n < 2; ++n) _Pragma("unroll") for (int k = 0; k < 2; ++k) \
;         acc[ai][bj][m][n] = __builtin_amdgcn_mfma_f32_16x16x32_bf16(Bt[n][k], At[m][k], acc[ai][bj][m][n], 0, 0, 0); __builtin_amdgcn_s_setprio(0); } while (0)
; #define PG8_WAIT_V(n) asm volatile("s_waitcnt vmcnt(" #n ")" ::: "memory")
; #define PG8_WAIT_L(n) asm volatile("s_waitcnt lgkmcnt(" #n ")" ::: "memory")
; #define PG8_BAR __builtin_amdgcn_s_barrier()
; #define PG8_SCHED __builtin_amdgcn_sched_barrier(0)
; template <class Epi, class Sched, bool ALIGN_EPI = false, bool SP2 = false, bool ACHUNK = false>
; __device__ __forceinline__ void gemm_phase(PG8_LAS unsigned char* lds, const Gemm g, const Sched& S, const Epi& E) {
;     ...
;         const bool has_next = S.next(ui + 1, nxt);
;         const char* nA = has_next ? (const char*)g.A + (size_t)nxt.pm * tstepA : cA; const char* nB = has_next ? (const char*)g.Bt + (size_t)nxt.pn * tstepB : cB;
;         for (int t = 0; t < nt; t += 2) {
;     ...
;             PG8_LDA(At, 1, 1); PG8_STAGE(PG8_SB(1, 0), b3, voffB); PG8_STAGE(PG8_SB(1, 1), b3 + hstepB, voffB); PG8_STAGE(PG8_SA(1, 0), a3, voffA);
;             PG8_WAIT_V(8); PG8_WAIT_L(0); PG8_BAR; PG8_MMA(1, 0, At, B0); PG8_MMA(1, 1, At, B1); PG8_BAR; PG8_SCHED;
	s_add_i32 s22, s51, s26
	v_lshl_add_u64 v[192:193], v[192:193], 0, s[10:11]
	s_mov_b32 m0, s22
	ds_read_b128 v[180:183], v149 offset:49152
	ds_read_b128 v[184:187], v149 offset:50176
	ds_read_b128 v[188:191], v149 offset:51200
	ds_read_b128 v[198:201], v149 offset:52224
	ds_read_b128 v[202:205], v149 offset:53248
	ds_read_b128 v[206:209], v149 offset:54272
	ds_read_b128 v[210:213], v149 offset:55296
	ds_read_b128 v[214:217], v149 offset:56320
	global_load_lds_dwordx4 v[192:193], off
	v_lshl_add_u64 v[192:193], v[218:219], 0, s[10:11]
	s_add_i32 m0, s22, 0x2000
	s_add_i32 s22, s52, s26
	global_load_lds_dwordx4 v[192:193], off
	v_lshl_add_u64 v[192:193], v[220:221], 0, s[10:11]
	s_mov_b32 m0, s22
	s_nop 0
	global_load_lds_dwordx4 v[192:193], off
	v_lshl_add_u64 v[192:193], v[222:223], 0, s[10:11]
	s_add_i32 m0, s22, 0x2000
	s_nop 0
	global_load_lds_dwordx4 v[192:193], off
	v_lshl_add_u64 v[192:193], v[224:225], 0, s[10:11]
	s_mov_b32 m0, s31
	s_nop 0
	global_load_lds_dwordx4 v[192:193], off
	v_lshl_add_u64 v[192:193], v[232:233], 0, s[10:11]
	s_mov_b32 m0, s33
	s_nop 0
	global_load_lds_dwordx4 v[192:193], off
	s_waitcnt vmcnt(8)
	s_waitcnt lgkmcnt(0)
	s_barrier
	s_setprio 1
	s_waitcnt lgkmcnt(0)
	v_mfma_f32_16x16x32_bf16 v[56:59], v[142:145], v[180:183], v[56:59]
	v_mfma_f32_16x16x32_bf16 v[64:67], v[156:159], v[180:183], v[64:67]
	v_mfma_f32_16x16x32_bf16 v[40:43], v[142:145], v[188:191], v[40:43]
	v_mfma_f32_16x16x32_bf16 v[48:51], v[156:159], v[188:191], v[48:51]
	v_mfma_f32_16x16x32_bf16 v[24:27], v[142:145], v[202:205], v[24:27]
	v_mfma_f32_16x16x32_bf16 v[32:35], v[156:159], v[202:205], v[32:35]
	v_mfma_f32_16x16x32_bf16 v[8:11], v[142:145], v[210:213], v[8:11]
	v_mfma_f32_16x16x32_bf16 v[16:19], v[156:159], v[210:213], v[16:19]
	v_mfma_f32_16x16x32_bf16 v[56:59], v[152:155], v[184:187], v[56:59]
	v_mfma_f32_16x16x32_bf16 v[64:67], v[160:163], v[184:187], v[64:67]
	v_mfma_f32_16x16x32_bf16 v[40:43], v[152:155], v[198:201], v[40:43]
	v_mfma_f32_16x16x32_bf16 v[48:51], v[160:163], v[198:201], v[48:51]
	v_mfma_f32_16x16x32_bf16 v[24:27], v[152:155], v[206:209], v[24:27]
	v_mfma_f32_16x16x32_bf16 v[32:35], v[160:163], v[206:209], v[32:35]
	v_mfma_f32_16x16x32_bf16 v[8:11], v[152:155], v[214:217], v[8:11]
	v_mfma_f32_16x16x32_bf16 v[16:19], v[160:163], v[214:217], v[16:19]
	s_setprio 0
	s_setprio 1
	v_mfma_f32_16x16x32_bf16 v[52:55], v[164:167], v[180:183], v[52:55]
	v_mfma_f32_16x16x32_bf16 v[60:63], v[172:175], v[180:183], v[60:63]
	v_mfma_f32_16x16x32_bf16 v[36:39], v[164:167], v[188:191], v[36:39]
	v_mfma_f32_16x16x32_bf16 v[44:47], v[172:175], v[188:191], v[44:47]
	v_mfma_f32_16x16x32_bf16 v[20:23], v[164:167], v[202:205], v[20:23]
	v_mfma_f32_16x16x32_bf16 v[28:31], v[172:175], v[202:205], v[28:31]
	v_mfma_f32_16x16x32_bf16 v[4:7], v[164:167], v[210:213], v[4:7]
	v_mfma_f32_16x16x32_bf16 v[12:15], v[172:175], v[210:213], v[12:15]
	v_mfma_f32_16x16x32_bf16 v[52:55], v[168:171], v[184:187], v[52:55]
	v_mfma_f32_16x16x32_bf16 v[60:63], v[176:179], v[184:187], v[60:63]
	v_mfma_f32_16x16x32_bf16 v[36:39], v[168:171], v[198:201], v[36:39]
	v_mfma_f32_16x16x32_bf16 v[44:47], v[176:179], v[198:201], v[44:47]
	v_mfma_f32_16x16x32_bf16 v[20:23], v[168:171], v[206:209], v[20:23]
	v_mfma_f32_16x16x32_bf16 v[28:31], v[176:179], v[206:209], v[28:31]
	v_mfma_f32_16x16x32_bf16 v[4:7], v[168:171], v[214:217], v[4:7]
	v_mfma_f32_16x16x32_bf16 v[12:15], v[176:179], v[214:217], v[12:15]
	s_setprio 0
	s_barrier
	s_add_u32 s48, s48, 0x100
	s_addc_u32 s49, s49, 0
	s_add_u32 s20, s20, 0x100
	s_addc_u32 s21, s21, 0
	s_cmp_ge_i32 s50, s34
	s_mov_b32 s22, s50
	s_cbranch_scc0 .LBB0_216
	v_readlane_b32 s54, v254, 25
	v_readlane_b32 s52, v254, 27
	v_readlane_b32 s55, v254, 26
	v_readlane_b32 s53, v254, 28
	s_mov_b32 s50, s94
	s_and_b64 vcc, exec, s[16:17]
	s_cbranch_vccnz .LBB0_221
	s_branch .LBB0_222

; template <class Epi, class Sched, bool ALIGN_EPI = false, bool SP2 = false, bool ACHUNK = false>
; __device__ __forceinline__ void gemm_phase(PG8_LAS unsigned char* lds, const Gemm g, const Sched& S, const Epi& E) {
;     ...
;         const bool has_next = S.next(ui + 1, nxt);
;         const char* nA = has_next ? (const char*)g.A + (size_t)nxt.pm * tstepA : cA; const char* nB = has_next ? (const char*)g.Bt + (size_t)nxt.pn * tstepB : cB;
;         for (int t = 0; t < nt; t += 2) {
;             const bool last = (t == nt - 2);
;             if constexpr (Epi::HAS_MID) { if (t == Epi::MID_T) E.mid(acc, cur, wr, wc, fr, fq, ShflDev{}); }
;             const char* a1 = cA + (size_t)(t + 1) * kstep;
;             const char* a2 = last ? nA : cA + (size_t)(t + 2) * kstep; const char* b2 = last ? nB : cB + (size_t)(t + 2) * kstep;
;     ...
;         else {
; #pragma unroll
;         for (int a = 0; a < 2; ++a)
; #pragma unroll
;             for (int b = 0; b < 2; ++b)
; #pragma unroll
;                 for (int m = 0; m < 4; ++m)
; #pragma unroll
;                     for (int n = 0; n < 2; ++n) acc[a][b][m][n] = (f32x4){0.f, 0.f, 0.f, 0.f};
;         }
;         cur = nxt; cA = nA; cB = nB; ++ui;
.LBB0_264:
	s_nop 0
	v_mov_b32_e32 v129, 0
	s_andn2_b64 vcc, exec, s[30:31]
	v_mov_b32_e32 v128, 0
	v_mov_b32_e32 v127, 0
	v_mov_b32_e32 v126, 0
	v_mov_b32_e32 v133, 0
	v_mov_b32_e32 v132, 0
	v_mov_b32_e32 v131, 0
	v_mov_b32_e32 v130, 0
	v_mov_b32_e32 v117, 0
	v_mov_b32_e32 v116, 0
	v_mov_b32_e32 v115, 0
	v_mov_b32_e32 v114, 0
	v_mov_b32_e32 v113, 0
	v_mov_b32_e32 v112, 0
	v_mov_b32_e32 v111, 0
	v_mov_b32_e32 v110, 0
	v_mov_b32_e32 v101, 0
	v_mov_b32_e32 v100, 0
	v_mov_b32_e32 v99, 0
	v_mov_b32_e32 v98, 0
	v_mov_b32_e32 v97, 0
	v_mov_b32_e32 v96, 0
	v_mov_b32_e32 v95, 0
	v_mov_b32_e32 v94, 0
	v_mov_b32_e32 v85, 0
	v_mov_b32_e32 v84, 0
	v_mov_b32_e32 v83, 0
	v_mov_b32_e32 v82, 0
	v_mov_b32_e32 v81, 0
	v_mov_b32_e32 v80, 0
	v_mov_b32_e32 v79, 0
	v_mov_b32_e32 v78, 0
	v_mov_b32_e32 v125, 0
	v_mov_b32_e32 v124, 0
	v_mov_b32_e32 v123, 0
	v_mov_b32_e32 v122, 0
	v_mov_b32_e32 v121, 0
	v_mov_b32_e32 v120, 0
	v_mov_b32_e32 v119, 0
	v_mov_b32_e32 v118, 0
	v_mov_b32_e32 v109, 0
	v_mov_b32_e32 v108, 0
	v_mov_b32_e32 v107, 0
	v_mov_b32_e32 v106, 0
	v_mov_b32_e32 v105, 0
	v_mov_b32_e32 v104, 0
	v_mov_b32_e32 v103, 0
	v_mov_b32_e32 v102, 0
	v_mov_b32_e32 v93, 0
	v_mov_b32_e32 v92, 0
	v_mov_b32_e32 v91, 0
	v_mov_b32_e32 v90, 0
	v_mov_b32_e32 v89, 0
	v_mov_b32_e32 v88, 0
	v_mov_b32_e32 v87, 0
	v_mov_b32_e32 v86, 0
	v_mov_b32_e32 v77, 0
	v_mov_b32_e32 v76, 0
	v_mov_b32_e32 v75, 0
	v_mov_b32_e32 v74, 0
	v_mov_b32_e32 v73, 0
	v_mov_b32_e32 v72, 0
	v_mov_b32_e32 v71, 0
	v_mov_b32_e32 v70, 0
	v_mov_b32_e32 v69, 0
	v_mov_b32_e32 v68, 0
	v_mov_b32_e32 v67, 0
	v_mov_b32_e32 v66, 0
	v_mov_b32_e32 v65, 0
	v_mov_b32_e32 v64, 0
	v_mov_b32_e32 v63, 0
	v_mov_b32_e32 v62, 0
	v_mov_b32_e32 v53, 0
	v_mov_b32_e32 v52, 0
	v_mov_b32_e32 v51, 0
	v_mov_b32_e32 v50, 0
	v_mov_b32_e32 v49, 0
	v_mov_b32_e32 v48, 0
	v_mov_b32_e32 v47, 0
	v_mov_b32_e32 v46, 0
	v_mov_b32_e32 v37, 0
	v_mov_b32_e32 v36, 0
	v_mov_b32_e32 v35, 0
	v_mov_b32_e32 v34, 0
	v_mov_b32_e32 v33, 0
	v_mov_b32_e32 v32, 0
	v_mov_b32_e32 v31, 0
	v_mov_b32_e32 v30, 0
	v_mov_b32_e32 v21, 0
	v_mov_b32_e32 v20, 0
	v_mov_b32_e32 v19, 0
	v_mov_b32_e32 v18, 0
	v_mov_b32_e32 v17, 0
	v_mov_b32_e32 v16, 0
	v_mov_b32_e32 v15, 0
	v_mov_b32_e32 v14, 0
	v_mov_b32_e32 v61, 0
	v_mov_b32_e32 v60, 0
	v_mov_b32_e32 v59, 0
	v_mov_b32_e32 v58, 0
	v_mov_b32_e32 v57, 0
	v_mov_b32_e32 v56, 0
	v_mov_b32_e32 v55, 0
	v_mov_b32_e32 v54, 0
	v_mov_b32_e32 v45, 0
	v_mov_b32_e32 v44, 0
	v_mov_b32_e32 v43, 0
	v_mov_b32_e32 v42, 0
	v_mov_b32_e32 v41, 0
	v_mov_b32_e32 v40, 0
	v_mov_b32_e32 v39, 0
	v_mov_b32_e32 v38, 0
	v_mov_b32_e32 v29, 0
	v_mov_b32_e32 v28, 0
	v_mov_b32_e32 v27, 0
	v_mov_b32_e32 v26, 0
	v_mov_b32_e32 v25, 0
	v_mov_b32_e32 v24, 0
	v_mov_b32_e32 v23, 0
	v_mov_b32_e32 v22, 0
	v_mov_b32_e32 v13, 0
	v_mov_b32_e32 v12, 0
	v_mov_b32_e32 v11, 0
	v_mov_b32_e32 v10, 0
	v_mov_b32_e32 v9, 0
	v_mov_b32_e32 v8, 0
	v_mov_b32_e32 v7, 0
	v_mov_b32_e32 v6, 0
	s_cbranch_vccnz .LBB0_270
	s_lshl_b32 s8, s46, 8
	s_lshl_b32 s48, s45, 8
	s_or_b32 s47, s8, s25
	s_add_i32 s48, s48, s24
	s_add_u32 s49, s6, 0x100
	s_addc_u32 s50, s7, 0
	s_add_u32 s6, s4, 0x80
	v_mov_b32_e32 v4, v3
	v_mov_b32_e32 v5, v3
	s_addc_u32 s7, s5, 0
	v_mov_b32_e32 v2, v3
	v_mov_b64_e32 v[8:9], v[4:5]
	v_mov_b64_e32 v[12:13], v[4:5]
	v_mov_b64_e32 v[24:25], v[4:5]
	v_mov_b64_e32 v[28:29], v[4:5]
	v_mov_b64_e32 v[40:41], v[4:5]
	v_mov_b64_e32 v[44:45], v[4:5]
	v_mov_b64_e32 v[56:57], v[4:5]
	v_mov_b64_e32 v[60:61], v[4:5]
	v_mov_b64_e32 v[16:17], v[4:5]
	v_mov_b64_e32 v[20:21], v[4:5]
	v_mov_b64_e32 v[32:33], v[4:5]
	v_mov_b64_e32 v[36:37], v[4:5]
	v_mov_b64_e32 v[48:49], v[4:5]
	v_mov_b64_e32 v[52:53], v[4:5]
	v_mov_b64_e32 v[64:65], v[4:5]
	v_mov_b64_e32 v[68:69], v[4:5]
	v_mov_b64_e32 v[72:73], v[4:5]
	v_mov_b64_e32 v[76:77], v[4:5]
	v_mov_b64_e32 v[88:89], v[4:5]
	v_mov_b64_e32 v[92:93], v[4:5]
	v_mov_b64_e32 v[104:105], v[4:5]
	v_mov_b64_e32 v[108:109], v[4:5]
	v_mov_b64_e32 v[120:121], v[4:5]
	v_mov_b64_e32 v[124:125], v[4:5]
	v_mov_b64_e32 v[80:81], v[4:5]
	v_mov_b64_e32 v[84:85], v[4:5]
	v_mov_b64_e32 v[96:97], v[4:5]
	v_mov_b64_e32 v[100:101], v[4:5]
	v_mov_b64_e32 v[112:113], v[4:5]
	v_mov_b64_e32 v[116:117], v[4:5]
	v_mov_b64_e32 v[132:133], v[4:5]
	v_mov_b64_e32 v[128:129], v[4:5]
	v_lshl_add_u64 v[210:211], s[6:7], 0, v[206:207]
	v_lshl_add_u64 v[212:213], s[6:7], 0, v[208:209]
	s_mov_b32 s8, 0
	s_mov_b64 s[6:7], 0
	v_mov_b64_e32 v[6:7], v[2:3]
	v_mov_b64_e32 v[10:11], v[2:3]
	v_mov_b64_e32 v[22:23], v[2:3]
	v_mov_b64_e32 v[26:27], v[2:3]
	v_mov_b64_e32 v[38:39], v[2:3]
	v_mov_b64_e32 v[42:43], v[2:3]
	v_mov_b64_e32 v[54:55], v[2:3]
	v_mov_b64_e32 v[58:59], v[2:3]
	v_mov_b64_e32 v[14:15], v[2:3]
	v_mov_b64_e32 v[18:19], v[2:3]
	v_mov_b64_e32 v[30:31], v[2:3]
	v_mov_b64_e32 v[34:35], v[2:3]
	v_mov_b64_e32 v[46:47], v[2:3]
	v_mov_b64_e32 v[50:51], v[2:3]
	v_mov_b64_e32 v[62:63], v[2:3]
	v_mov_b64_e32 v[66:67], v[2:3]
	v_mov_b64_e32 v[70:71], v[2:3]
	v_mov_b64_e32 v[74:75], v[2:3]
	v_mov_b64_e32 v[86:87], v[2:3]
	v_mov_b64_e32 v[90:91], v[2:3]
	v_mov_b64_e32 v[102:103], v[2:3]
	v_mov_b64_e32 v[106:107], v[2:3]
	v_mov_b64_e32 v[118:119], v[2:3]
	v_mov_b64_e32 v[122:123], v[2:3]
	v_mov_b64_e32 v[78:79], v[2:3]
	v_mov_b64_e32 v[82:83], v[2:3]
	v_mov_b64_e32 v[94:95], v[2:3]
	v_mov_b64_e32 v[98:99], v[2:3]
	v_mov_b64_e32 v[110:111], v[2:3]
	v_mov_b64_e32 v[114:115], v[2:3]
	v_mov_b64_e32 v[130:131], v[2:3]
	v_mov_b64_e32 v[126:127], v[2:3]
	s_cmp_lg_u32 s8, 8
	s_cbranch_scc1 .LBB0_268
	s_branch .LBB0_267

; #define PG8_STAGE(bufoff, gbase, voff) do { _Pragma("unroll") for (int _i = 0; _i < 2; ++_i) \
;         __builtin_amdgcn_global_load_lds((const unsigned*)((const char*)(gbase) + (voff)[_i]), (PG8_LAS unsigned*)(lds + (bufoff) + ldsw + _i * 8192), 16, 0, 0); } while (0)
; #define PG8_LDA(dst, b, h) do { _Pragma("unroll") for (int m = 0; m < 4; ++m) _Pragma("unroll") for (int k = 0; k < 2; ++k) dst[m][k] = *(const PG8_LAS bf16x8*)(lds + PG8_SA(b, h) + aoff + m * 2048 + k * 1024); } while (0)
; #define PG8_LDB(dst, b, h) do { _Pragma("unroll") for (int n = 0; n < 2; ++n) _Pragma("unroll") for (int k = 0; k < 2; ++k) dst[n][k] = *(const PG8_LAS bf16x8*)(lds + PG8_SB(b, h) + boff + n * 2048 + k * 1024); } while (0)
; #define PG8_MMA(ai, bj, At, Bt) do { __builtin_amdgcn_s_setprio(1); _Pragma("unroll") for (int m = 0; m < 4; ++m) _Pragma("unroll") for (int n = 0; n < 2; ++n) _Pragma("unroll") for (int k = 0; k < 2; ++k) \
;         acc[ai][bj][m][n] = __builtin_amdgcn_mfma_f32_16x16x32_bf16(Bt[n][k], At[m][k], acc[ai][bj][m][n], 0, 0, 0); __builtin_amdgcn_s_setprio(0); } while (0)
; #define PG8_BAR __builtin_amdgcn_s_barrier()
; template <class Epi, class Sched, bool ALIGN_EPI = false, bool SP2 = false, bool ACHUNK = false>
; __device__ __forceinline__ void gemm_phase(PG8_LAS unsigned char* lds, const Gemm g, const Sched& S, const Epi& E) {
;     ...
;             const bool last = (t == nt - 2);
;             if constexpr (Epi::HAS_MID) { if (t == Epi::MID_T) E.mid(acc, cur, wr, wc, fr, fq, ShflDev{}); }
;             const char* a1 = cA + (size_t)(t + 1) * kstep;
;             const char* a2 = last ? nA : cA + (size_t)(t + 2) * kstep; const char* b2 = last ? nB : cB + (size_t)(t + 2) * kstep;
;             const char* a3 = a2 + kstep; const char* b3 = b2 + kstep;
;             if (last && has_next) S.a_ready(nxt);
;             if constexpr (SP2) {
;             PG8_LDB(B0, 0, 0); PG8_LDB(B1, 0, 1); PG8_SCHED; PG8_LDA(At, 0, 0); PG8_STAGE(PG8_SA(1, 1), a1 + hstepA, voffA);
;             PG8_WAIT_V(8); PG8_WAIT_L(0); PG8_BAR; PG8_MMA(0, 0, At, B0); PG8_MMA(0, 1, At, B1); PG8_BAR; PG8_SCHED;
;             PG8_LDA(At, 0, 1); PG8_STAGE(PG8_SB(0, 0), b2, voffB); PG8_STAGE(PG8_SB(0, 1), b2 + hstepB, voffB); PG8_STAGE(PG8_SA(0, 0), a2, voffA);
;             PG8_WAIT_V(8); PG8_WAIT_L(0); PG8_BAR; PG8_MMA(1, 0, At, B0); PG8_MMA(1, 1, At, B1); PG8_BAR; PG8_SCHED;
.LBB0_268:
	s_add_i32 s51, s8, 2
	s_add_u32 s9, s4, s6
	s_addc_u32 s52, s5, s7
	s_add_u32 s53, s9, 0x100
	s_addc_u32 s9, s52, 0
	s_add_u32 s52, s49, s6
	s_addc_u32 s54, s50, s7
	s_add_i32 s55, 0, 0x10000
	s_cmp_eq_u32 s33, s8
	s_cselect_b32 s9, s1, s9
	s_cselect_b32 s8, s0, s53
	v_add_u32_e32 v2, s55, v235
	s_cselect_b32 s53, s41, s54
	s_cselect_b32 s52, s40, s52
	s_cbranch_scc0 .Lnl_mg
	s_cmpk_lg_u32 s87, 0x100
	s_cbranch_scc1 .Lnl_mg
	v_mov_b32_e32 v200, 0
	v_mov_b32_e32 v204, 0
	v_mov_b32_e32 v198, 0
	v_mov_b32_e32 v202, 0
.Lnl_mg:
	s_add_i32 s54, 0, 0x14000
	ds_read_b128 v[134:137], v2
	ds_read_b128 v[138:141], v2 offset:1024
	ds_read_b128 v[142:145], v2 offset:2048
	ds_read_b128 v[146:149], v2 offset:3072
	v_add_u32_e32 v2, s54, v235
	ds_read_b128 v[150:153], v2
	ds_read_b128 v[154:157], v2 offset:1024
	ds_read_b128 v[158:161], v2 offset:2048
	ds_read_b128 v[162:165], v2 offset:3072
	v_lshl_add_u64 v[4:5], v[210:211], 0, s[6:7]
	s_add_i32 m0, s17, 0xc000
	ds_read_b128 v[166:169], v237
	ds_read_b128 v[170:173], v237 offset:1024
	ds_read_b128 v[174:177], v237 offset:2048
	ds_read_b128 v[178:181], v237 offset:3072
	ds_read_b128 v[182:185], v237 offset:4096
	ds_read_b128 v[186:189], v237 offset:5120
	ds_read_b128 v[190:193], v237 offset:6144
	ds_read_b128 v[214:217], v237 offset:7168
	global_load_lds_dwordx4 v[4:5], off
	v_lshl_add_u64 v[4:5], v[212:213], 0, s[6:7]
	s_add_i32 m0, s17, 0xe000
	s_nop 0
	global_load_lds_dwordx4 v[4:5], off
	s_waitcnt vmcnt(8)
	s_waitcnt lgkmcnt(0)
	s_barrier
	s_setprio 1
	s_waitcnt lgkmcnt(0)
	v_mfma_f32_16x16x32_bf16 v[126:129], v[134:137], v[166:169], v[126:129]
	v_mfma_f32_16x16x32_bf16 v[130:133], v[142:145], v[166:169], v[130:133]
	v_mfma_f32_16x16x32_bf16 v[114:117], v[134:137], v[174:177], v[114:117]
	v_mfma_f32_16x16x32_bf16 v[110:113], v[142:145], v[174:177], v[110:113]
	v_mfma_f32_16x16x32_bf16 v[98:101], v[134:137], v[182:185], v[98:101]
	v_mfma_f32_16x16x32_bf16 v[94:97], v[142:145], v[182:185], v[94:97]
	v_mfma_f32_16x16x32_bf16 v[82:85], v[134:137], v[190:193], v[82:85]
	v_mfma_f32_16x16x32_bf16 v[78:81], v[142:145], v[190:193], v[78:81]
	v_mfma_f32_16x16x32_bf16 v[126:129], v[138:141], v[170:173], v[126:129]
	v_mfma_f32_16x16x32_bf16 v[130:133], v[146:149], v[170:173], v[130:133]
	v_mfma_f32_16x16x32_bf16 v[114:117], v[138:141], v[178:181], v[114:117]
	v_mfma_f32_16x16x32_bf16 v[110:113], v[146:149], v[178:181], v[110:113]
	v_mfma_f32_16x16x32_bf16 v[98:101], v[138:141], v[186:189], v[98:101]
	v_mfma_f32_16x16x32_bf16 v[94:97], v[146:149], v[186:189], v[94:97]
	v_mfma_f32_16x16x32_bf16 v[82:85], v[138:141], v[214:217], v[82:85]
	v_mfma_f32_16x16x32_bf16 v[78:81], v[146:149], v[214:217], v[78:81]
	s_setprio 0
	s_setprio 1
	v_mfma_f32_16x16x32_bf16 v[122:125], v[150:153], v[166:169], v[122:125]
	v_mfma_f32_16x16x32_bf16 v[118:121], v[158:161], v[166:169], v[118:121]
	v_mfma_f32_16x16x32_bf16 v[106:109], v[150:153], v[174:177], v[106:109]
	v_mfma_f32_16x16x32_bf16 v[102:105], v[158:161], v[174:177], v[102:105]
	v_mfma_f32_16x16x32_bf16 v[90:93], v[150:153], v[182:185], v[90:93]
	v_mfma_f32_16x16x32_bf16 v[86:89], v[158:161], v[182:185], v[86:89]
	v_mfma_f32_16x16x32_bf16 v[74:77], v[150:153], v[190:193], v[74:77]
	v_mfma_f32_16x16x32_bf16 v[70:73], v[158:161], v[190:193], v[70:73]
	v_mfma_f32_16x16x32_bf16 v[122:125], v[154:157], v[170:173], v[122:125]
	v_mfma_f32_16x16x32_bf16 v[118:121], v[162:165], v[170:173], v[118:121]
	v_mfma_f32_16x16x32_bf16 v[106:109], v[154:157], v[178:181], v[106:109]
	v_mfma_f32_16x16x32_bf16 v[102:105], v[162:165], v[178:181], v[102:105]
	v_mfma_f32_16x16x32_bf16 v[90:93], v[154:157], v[186:189], v[90:93]
	v_mfma_f32_16x16x32_bf16 v[86:89], v[162:165], v[186:189], v[86:89]
	v_mfma_f32_16x16x32_bf16 v[74:77], v[154:157], v[214:217], v[74:77]
	v_mfma_f32_16x16x32_bf16 v[70:73], v[162:165], v[214:217], v[70:73]
	s_setprio 0
	s_barrier
	s_add_i32 s55, s55, s16
	v_lshl_add_u64 v[218:219], s[52:53], 0, v[200:201]
	s_mov_b32 m0, s55
	ds_read_b128 v[166:169], v237 offset:16384
	ds_read_b128 v[170:173], v237 offset:17408
	ds_read_b128 v[174:177], v237 offset:18432
	ds_read_b128 v[178:181], v237 offset:19456
	ds_read_b128 v[182:185], v237 offset:20480
	ds_read_b128 v[186:189], v237 offset:21504
	ds_read_b128 v[190:193], v237 offset:22528
	ds_read_b128 v[214:217], v237 offset:23552
	global_load_lds_dwordx4 v[218:219], off
	s_add_i32 m0, s55, 0x2000
	v_lshl_add_u64 v[220:221], s[52:53], 0, v[204:205]
	s_add_u32 s52, s52, s2
	s_addc_u32 s53, s53, s3
	s_add_i32 s54, s54, s16
	global_load_lds_dwordx4 v[220:221], off
	v_lshl_add_u64 v[222:223], s[52:53], 0, v[200:201]
	s_mov_b32 m0, s54
	v_lshl_add_u64 v[224:225], s[52:53], 0, v[204:205]
	global_load_lds_dwordx4 v[222:223], off
	s_add_i32 m0, s54, 0x2000
	v_lshl_add_u64 v[238:239], s[8:9], 0, v[198:199]
	global_load_lds_dwordx4 v[224:225], off
	s_mov_b32 m0, s17
	v_lshl_add_u64 v[240:241], s[8:9], 0, v[202:203]
	global_load_lds_dwordx4 v[238:239], off
	s_mov_b32 m0, s20
	s_nop 0
	global_load_lds_dwordx4 v[240:241], off
	s_waitcnt vmcnt(8)
	s_waitcnt lgkmcnt(0)
	s_barrier
; #define PG8_STAGE(bufoff, gbase, voff) do { _Pragma("unroll") for (int _i = 0; _i < 2; ++_i) \
;         __builtin_amdgcn_global_load_lds((const unsigned*)((const char*)(gbase) + (voff)[_i]), (PG8_LAS unsigned*)(lds + (bufoff) + ldsw + _i * 8192), 16, 0, 0); } while (0)
; #define PG8_LDA(dst, b, h) do { _Pragma("unroll") for (int m = 0; m < 4; ++m) _Pragma("unroll") for (int k = 0; k < 2; ++k) dst[m][k] = *(const PG8_LAS bf16x8*)(lds + PG8_SA(b, h) + aoff + m * 2048 + k * 1024); } while (0)
; #define PG8_LDB(dst, b, h) do { _Pragma("unroll") for (int n = 0; n < 2; ++n) _Pragma("unroll") for (int k = 0; k < 2; ++k) dst[n][k] = *(const PG8_LAS bf16x8*)(lds + PG8_SB(b, h) + boff + n * 2048 + k * 1024); } while (0)
; #define PG8_MMA(ai, bj, At, Bt) do { __builtin_amdgcn_s_setprio(1); _Pragma("unroll") for (int m = 0; m < 4; ++m) _Pragma("unroll") for (int n = 0; n < 2; ++n) _Pragma("unroll") for (int k = 0; k < 2; ++k) \
;         acc[ai][bj][m][n] = __builtin_amdgcn_mfma_f32_16x16x32_bf16(Bt[n][k], At[m][k], acc[ai][bj][m][n], 0, 0, 0); __builtin_amdgcn_s_setprio(0); } while (0)
; #define PG8_WAIT_V(n) asm volatile("s_waitcnt vmcnt(" #n ")" ::: "memory")
; #define PG8_WAIT_L(n) asm volatile("s_waitcnt lgkmcnt(" #n ")" ::: "memory")
; #define PG8_BAR __builtin_amdgcn_s_barrier()
; #define PG8_SCHED __builtin_amdgcn_sched_barrier(0)
; template <class Epi, class Sched, bool ALIGN_EPI = false, bool SP2 = false, bool ACHUNK = false>
; __device__ __forceinline__ void gemm_phase(PG8_LAS unsigned char* lds, const Gemm g, const Sched& S, const Epi& E) {
;     ...
;             PG8_WAIT_V(8); PG8_WAIT_L(0); PG8_BAR; PG8_MMA(1, 0, At, B0); PG8_MMA(1, 1, At, B1); PG8_BAR; PG8_SCHED;
;             PG8_LDB(B0, 1, 0); PG8_LDB(B1, 1, 1); PG8_SCHED; PG8_LDA(At, 1, 0); PG8_STAGE(PG8_SA(0, 1), a2 + hstepA, voffA);
;             PG8_WAIT_V(8); PG8_WAIT_L(0); PG8_BAR; PG8_MMA(0, 0, At, B0); PG8_MMA(0, 1, At, B1); PG8_BAR; PG8_SCHED;
	s_setprio 1
	s_waitcnt lgkmcnt(0)
	v_mfma_f32_16x16x32_bf16 v[66:69], v[134:137], v[166:169], v[66:69]
	v_mfma_f32_16x16x32_bf16 v[62:65], v[142:145], v[166:169], v[62:65]
	v_mfma_f32_16x16x32_bf16 v[50:53], v[134:137], v[174:177], v[50:53]
	v_mfma_f32_16x16x32_bf16 v[46:49], v[142:145], v[174:177], v[46:49]
	v_mfma_f32_16x16x32_bf16 v[34:37], v[134:137], v[182:185], v[34:37]
	v_mfma_f32_16x16x32_bf16 v[30:33], v[142:145], v[182:185], v[30:33]
	v_mfma_f32_16x16x32_bf16 v[18:21], v[134:137], v[190:193], v[18:21]
	v_mfma_f32_16x16x32_bf16 v[14:17], v[142:145], v[190:193], v[14:17]
	v_mfma_f32_16x16x32_bf16 v[66:69], v[138:141], v[170:173], v[66:69]
	v_mfma_f32_16x16x32_bf16 v[62:65], v[146:149], v[170:173], v[62:65]
	v_mfma_f32_16x16x32_bf16 v[50:53], v[138:141], v[178:181], v[50:53]
	v_mfma_f32_16x16x32_bf16 v[46:49], v[146:149], v[178:181], v[46:49]
	v_mfma_f32_16x16x32_bf16 v[34:37], v[138:141], v[186:189], v[34:37]
	v_mfma_f32_16x16x32_bf16 v[30:33], v[146:149], v[186:189], v[30:33]
	v_mfma_f32_16x16x32_bf16 v[18:21], v[138:141], v[214:217], v[18:21]
	v_mfma_f32_16x16x32_bf16 v[14:17], v[146:149], v[214:217], v[14:17]
	s_setprio 0
	s_setprio 1
	v_mfma_f32_16x16x32_bf16 v[58:61], v[150:153], v[166:169], v[58:61]
	v_mfma_f32_16x16x32_bf16 v[54:57], v[158:161], v[166:169], v[54:57]
	v_mfma_f32_16x16x32_bf16 v[42:45], v[150:153], v[174:177], v[42:45]
	v_mfma_f32_16x16x32_bf16 v[38:41], v[158:161], v[174:177], v[38:41]
	v_mfma_f32_16x16x32_bf16 v[26:29], v[150:153], v[182:185], v[26:29]
	v_mfma_f32_16x16x32_bf16 v[22:25], v[158:161], v[182:185], v[22:25]
	v_mfma_f32_16x16x32_bf16 v[10:13], v[150:153], v[190:193], v[10:13]
	v_mfma_f32_16x16x32_bf16 v[4:7], v[158:161], v[190:193], v[6:9]
	v_mfma_f32_16x16x32_bf16 v[58:61], v[154:157], v[170:173], v[58:61]
	v_mfma_f32_16x16x32_bf16 v[54:57], v[162:165], v[170:173], v[54:57]
	v_mfma_f32_16x16x32_bf16 v[42:45], v[154:157], v[178:181], v[42:45]
	v_mfma_f32_16x16x32_bf16 v[38:41], v[162:165], v[178:181], v[38:41]
	v_mfma_f32_16x16x32_bf16 v[26:29], v[154:157], v[186:189], v[26:29]
	v_mfma_f32_16x16x32_bf16 v[22:25], v[162:165], v[186:189], v[22:25]
	v_mfma_f32_16x16x32_bf16 v[10:13], v[154:157], v[214:217], v[10:13]
	v_mfma_f32_16x16x32_bf16 v[4:7], v[162:165], v[214:217], v[4:7]
	s_setprio 0
	s_barrier
	s_add_i32 s52, 0, 0x18000
	v_add_u32_e32 v2, s52, v235
	s_add_i32 s53, 0, 0x1c000
	ds_read_b128 v[134:137], v2
	ds_read_b128 v[138:141], v2 offset:1024
	ds_read_b128 v[142:145], v2 offset:2048
	ds_read_b128 v[146:149], v2 offset:3072
	v_add_u32_e32 v2, s53, v235
	ds_read_b128 v[150:153], v2
	ds_read_b128 v[154:157], v2 offset:1024
	ds_read_b128 v[158:161], v2 offset:2048
	ds_read_b128 v[162:165], v2 offset:3072
	s_add_u32 s8, s8, s2
	s_addc_u32 s9, s9, s3
	s_mov_b32 m0, s21
	v_lshl_add_u64 v[8:9], s[8:9], 0, v[198:199]
	ds_read_b128 v[166:169], v237 offset:32768
	ds_read_b128 v[170:173], v237 offset:33792
	ds_read_b128 v[174:177], v237 offset:34816
	ds_read_b128 v[178:181], v237 offset:35840
	ds_read_b128 v[182:185], v237 offset:36864
	ds_read_b128 v[186:189], v237 offset:37888
	ds_read_b128 v[190:193], v237 offset:38912
	ds_read_b128 v[214:217], v237 offset:39936
	global_load_lds_dwordx4 v[8:9], off
	v_lshl_add_u64 v[8:9], s[8:9], 0, v[202:203]
	s_mov_b32 m0, s22
	s_nop 0
	global_load_lds_dwordx4 v[8:9], off
	s_waitcnt vmcnt(8)
	s_waitcnt lgkmcnt(0)
	s_barrier
	s_setprio 1
	s_waitcnt lgkmcnt(0)
	v_mfma_f32_16x16x32_bf16 v[126:129], v[134:137], v[166:169], v[126:129]
	v_mfma_f32_16x16x32_bf16 v[130:133], v[142:145], v[166:169], v[130:133]
	v_mfma_f32_16x16x32_bf16 v[114:117], v[134:137], v[174:177], v[114:117]
	v_mfma_f32_16x16x32_bf16 v[110:113], v[142:145], v[174:177], v[110:113]
	v_mfma_f32_16x16x32_bf16 v[98:101], v[134:137], v[182:185], v[98:101]
	v_mfma_f32_16x16x32_bf16 v[94:97], v[142:145], v[182:185], v[94:97]
	v_mfma_f32_16x16x32_bf16 v[82:85], v[134:137], v[190:193], v[82:85]
	v_mfma_f32_16x16x32_bf16 v[78:81], v[142:145], v[190:193], v[78:81]
	v_mfma_f32_16x16x32_bf16 v[126:129], v[138:141], v[170:173], v[126:129]
	v_mfma_f32_16x16x32_bf16 v[130:133], v[146:149], v[170:173], v[130:133]
	v_mfma_f32_16x16x32_bf16 v[114:117], v[138:141], v[178:181], v[114:117]
	v_mfma_f32_16x16x32_bf16 v[110:113], v[146:149], v[178:181], v[110:113]
	v_mfma_f32_16x16x32_bf16 v[98:101], v[138:141], v[186:189], v[98:101]
	v_mfma_f32_16x16x32_bf16 v[94:97], v[146:149], v[186:189], v[94:97]
	v_mfma_f32_16x16x32_bf16 v[82:85], v[138:141], v[214:217], v[82:85]
	v_mfma_f32_16x16x32_bf16 v[78:81], v[146:149], v[214:217], v[78:81]
	s_setprio 0
	s_setprio 1
	v_mfma_f32_16x16x32_bf16 v[122:125], v[150:153], v[166:169], v[122:125]
	v_mfma_f32_16x16x32_bf16 v[118:121], v[158:161], v[166:169], v[118:121]
	v_mfma_f32_16x16x32_bf16 v[106:109], v[150:153], v[174:177], v[106:109]
	v_mfma_f32_16x16x32_bf16 v[102:105], v[158:161], v[174:177], v[102:105]
	v_mfma_f32_16x16x32_bf16 v[90:93], v[150:153], v[182:185], v[90:93]
	v_mfma_f32_16x16x32_bf16 v[86:89], v[158:161], v[182:185], v[86:89]
	v_mfma_f32_16x16x32_bf16 v[74:77], v[150:153], v[190:193], v[74:77]
	v_mfma_f32_16x16x32_bf16 v[70:73], v[158:161], v[190:193], v[70:73]
	v_mfma_f32_16x16x32_bf16 v[122:125], v[154:157], v[170:173], v[122:125]
	v_mfma_f32_16x16x32_bf16 v[118:121], v[162:165], v[170:173], v[118:121]
	v_mfma_f32_16x16x32_bf16 v[106:109], v[154:157], v[178:181], v[106:109]
	v_mfma_f32_16x16x32_bf16 v[102:105], v[162:165], v[178:181], v[102:105]
	v_mfma_f32_16x16x32_bf16 v[90:93], v[154:157], v[186:189], v[90:93]
	v_mfma_f32_16x16x32_bf16 v[86:89], v[162:165], v[186:189], v[86:89]
	v_mfma_f32_16x16x32_bf16 v[74:77], v[154:157], v[214:217], v[74:77]
	v_mfma_f32_16x16x32_bf16 v[70:73], v[162:165], v[214:217], v[70:73]
	s_setprio 0
	s_barrier
; #define PG8_STAGE(bufoff, gbase, voff) do { _Pragma("unroll") for (int _i = 0; _i < 2; ++_i) \
;         __builtin_amdgcn_global_load_lds((const unsigned*)((const char*)(gbase) + (voff)[_i]), (PG8_LAS unsigned*)(lds + (bufoff) + ldsw + _i * 8192), 16, 0, 0); } while (0)
; #define PG8_LDA(dst, b, h) do { _Pragma("unroll") for (int m = 0; m < 4; ++m) _Pragma("unroll") for (int k = 0; k < 2; ++k) dst[m][k] = *(const PG8_LAS bf16x8*)(lds + PG8_SA(b, h) + aoff + m * 2048 + k * 1024); } while (0)
; #define PG8_MMA(ai, bj, At, Bt) do { __builtin_amdgcn_s_setprio(1); _Pragma("unroll") for (int m = 0; m < 4; ++m) _Pragma("unroll") for (int n = 0; n < 2; ++n) _Pragma("unroll") for (int k = 0; k < 2; ++k) \
;         acc[ai][bj][m][n] = __builtin_amdgcn_mfma_f32_16x16x32_bf16(Bt[n][k], At[m][k], acc[ai][bj][m][n], 0, 0, 0); __builtin_amdgcn_s_setprio(0); } while (0)
; #define PG8_WAIT_V(n) asm volatile("s_waitcnt vmcnt(" #n ")" ::: "memory")
; #define PG8_WAIT_L(n) asm volatile("s_waitcnt lgkmcnt(" #n ")" ::: "memory")
; #define PG8_BAR __builtin_amdgcn_s_barrier()
; #define PG8_SCHED __builtin_amdgcn_sched_barrier(0)
; template <class Epi, class Sched, bool ALIGN_EPI = false, bool SP2 = false, bool ACHUNK = false>
; __device__ __forceinline__ void gemm_phase(PG8_LAS unsigned char* lds, const Gemm g, const Sched& S, const Epi& E) {
;     ...
;         for (int t = 0; t < nt; t += 2) {
;     ...
;             PG8_LDA(At, 1, 1); PG8_STAGE(PG8_SB(1, 0), b3, voffB); PG8_STAGE(PG8_SB(1, 1), b3 + hstepB, voffB); PG8_STAGE(PG8_SA(1, 0), a3, voffA);
;             PG8_WAIT_V(8); PG8_WAIT_L(0); PG8_BAR; PG8_MMA(1, 0, At, B0); PG8_MMA(1, 1, At, B1); PG8_BAR; PG8_SCHED;
	s_add_i32 s8, s52, s16
	v_lshl_add_u64 v[8:9], v[218:219], 0, s[10:11]
	s_mov_b32 m0, s8
	ds_read_b128 v[166:169], v237 offset:49152
	ds_read_b128 v[170:173], v237 offset:50176
	ds_read_b128 v[174:177], v237 offset:51200
	ds_read_b128 v[178:181], v237 offset:52224
	ds_read_b128 v[182:185], v237 offset:53248
	ds_read_b128 v[186:189], v237 offset:54272
	ds_read_b128 v[190:193], v237 offset:55296
	ds_read_b128 v[214:217], v237 offset:56320
	global_load_lds_dwordx4 v[8:9], off
	v_lshl_add_u64 v[8:9], v[220:221], 0, s[10:11]
	s_add_i32 m0, s8, 0x2000
	s_add_i32 s8, s53, s16
	global_load_lds_dwordx4 v[8:9], off
	v_lshl_add_u64 v[8:9], v[222:223], 0, s[10:11]
	s_mov_b32 m0, s8
	s_nop 0
	global_load_lds_dwordx4 v[8:9], off
	v_lshl_add_u64 v[8:9], v[224:225], 0, s[10:11]
	s_add_i32 m0, s8, 0x2000
	s_nop 0
	global_load_lds_dwordx4 v[8:9], off
	v_lshl_add_u64 v[8:9], v[238:239], 0, s[10:11]
	s_mov_b32 m0, s26
	s_nop 0
	global_load_lds_dwordx4 v[8:9], off
	v_lshl_add_u64 v[8:9], v[240:241], 0, s[10:11]
	s_mov_b32 m0, s27
	s_nop 0
	global_load_lds_dwordx4 v[8:9], off
	s_waitcnt vmcnt(8)
	s_waitcnt lgkmcnt(0)
	s_barrier
	s_setprio 1
	s_waitcnt lgkmcnt(0)
	v_mfma_f32_16x16x32_bf16 v[66:69], v[134:137], v[166:169], v[66:69]
	v_mfma_f32_16x16x32_bf16 v[62:65], v[142:145], v[166:169], v[62:65]
	v_mfma_f32_16x16x32_bf16 v[50:53], v[134:137], v[174:177], v[50:53]
	v_mfma_f32_16x16x32_bf16 v[46:49], v[142:145], v[174:177], v[46:49]
	v_mfma_f32_16x16x32_bf16 v[34:37], v[134:137], v[182:185], v[34:37]
	v_mfma_f32_16x16x32_bf16 v[30:33], v[142:145], v[182:185], v[30:33]
	v_mfma_f32_16x16x32_bf16 v[18:21], v[134:137], v[190:193], v[18:21]
	v_mfma_f32_16x16x32_bf16 v[14:17], v[142:145], v[190:193], v[14:17]
	v_mfma_f32_16x16x32_bf16 v[66:69], v[138:141], v[170:173], v[66:69]
	v_mfma_f32_16x16x32_bf16 v[62:65], v[146:149], v[170:173], v[62:65]
	v_mfma_f32_16x16x32_bf16 v[50:53], v[138:141], v[178:181], v[50:53]
	v_mfma_f32_16x16x32_bf16 v[46:49], v[146:149], v[178:181], v[46:49]
	v_mfma_f32_16x16x32_bf16 v[34:37], v[138:141], v[186:189], v[34:37]
	v_mfma_f32_16x16x32_bf16 v[30:33], v[146:149], v[186:189], v[30:33]
	v_mfma_f32_16x16x32_bf16 v[18:21], v[138:141], v[214:217], v[18:21]
	v_mfma_f32_16x16x32_bf16 v[14:17], v[146:149], v[214:217], v[14:17]
	s_setprio 0
	s_setprio 1
	v_mfma_f32_16x16x32_bf16 v[58:61], v[150:153], v[166:169], v[58:61]
	v_mfma_f32_16x16x32_bf16 v[54:57], v[158:161], v[166:169], v[54:57]
	v_mfma_f32_16x16x32_bf16 v[42:45], v[150:153], v[174:177], v[42:45]
	v_mfma_f32_16x16x32_bf16 v[38:41], v[158:161], v[174:177], v[38:41]
	v_mfma_f32_16x16x32_bf16 v[26:29], v[150:153], v[182:185], v[26:29]
	v_mfma_f32_16x16x32_bf16 v[22:25], v[158:161], v[182:185], v[22:25]
	v_mfma_f32_16x16x32_bf16 v[8:11], v[150:153], v[190:193], v[10:13]
	v_mfma_f32_16x16x32_bf16 v[4:7], v[158:161], v[190:193], v[4:7]
	v_mfma_f32_16x16x32_bf16 v[58:61], v[154:157], v[170:173], v[58:61]
	v_mfma_f32_16x16x32_bf16 v[54:57], v[162:165], v[170:173], v[54:57]
	v_mfma_f32_16x16x32_bf16 v[42:45], v[154:157], v[178:181], v[42:45]
	v_mfma_f32_16x16x32_bf16 v[38:41], v[162:165], v[178:181], v[38:41]
	v_mfma_f32_16x16x32_bf16 v[26:29], v[154:157], v[186:189], v[26:29]
	v_mfma_f32_16x16x32_bf16 v[22:25], v[162:165], v[186:189], v[22:25]
	v_mfma_f32_16x16x32_bf16 v[10:13], v[154:157], v[214:217], v[8:11]
	v_mfma_f32_16x16x32_bf16 v[6:9], v[162:165], v[214:217], v[4:7]
	s_setprio 0
	s_barrier
	s_add_u32 s6, s6, 0x100
	s_addc_u32 s7, s7, 0
	s_cmp_ge_i32 s51, s23
	s_cbranch_scc0 .LBB0_266
	v_readlane_b32 s54, v254, 25
	v_readlane_b32 s52, v254, 27
	v_readlane_b32 s55, v254, 26
	v_readlane_b32 s53, v254, 28
	v_readlane_b32 s47, v255, 0
	s_mov_b32 s50, s94

; #define LAS __attribute__((address_space(3)))
; __device__ __forceinline__ void co_phase(Frame& F, int layer, const float* cwa_, const float* cba_, const float* lng_, const float* lnb_, const float* cwb_, const float* p_) {
;     ...
;         {
;             float vals[2 * CO_R];
; #pragma unroll
;             for (int r = 0; r < CO_R; ++r) { vals[r] = acc[r].x + acc[r].y; vals[CO_R + r] = acc[r].x * acc[r].x + acc[r].y * acc[r].y; }
; #pragma unroll
;             for (int half = CO_R, bit = 32; half >= 1; half >>= 1, bit >>= 1) {
;                 const bool up = (F.lane & bit) != 0;
; #pragma unroll
;                 for (int i = 0; i < half; ++i) { const float send = up ? vals[i] : vals[i + half], keep = up ? vals[i + half] : vals[i]; vals[i] = keep + __shfl_xor(send, bit, 64); }
;             }
;             static_assert(CO_R == 16 || CO_R == 32, "the butterfly below ends with 2 (CO_R = 16) or 1 (CO_R = 32) lanes per value");
;             const float tot = CO_R == 16 ? vals[0] + __shfl_xor(vals[0], 1, 64) : vals[0];
;             const int idx = CO_R == 16 ? ((F.lane >> 1) & 31) : F.lane;
;             if (CO_R == 32 || (F.lane & 1) == 0) ((LAS float*)part)[((idx & (CO_R - 1)) * 4 + wv) * 2 + (idx >= CO_R ? 1 : 0)] = tot;
;         }
;     ...
;             unsigned cvr[CO_R + 2], bsr[CO_R];
; #pragma unroll
;             for (int r = 0; r < CO_R + 2; ++r) { const int gr = (t0 - 2 + r >= 0) ? g0 - 2 + r : g0; cvr[r] = CVp[(size_t)gr * (DSC / 2) + (c0 >> 1)]; }
; #pragma unroll
;             for (int r = 0; r < CO_R; ++r) bsr[r] = BSp[(size_t)(g0 + r) * (DSC / 2) + (c0 >> 1)];
.LBB0_285:
	v_lshl_add_u64 v[164:165], v[82:83], 0, s[20:21]
	global_load_dword v130, v[164:165], off
	v_lshl_add_u64 v[164:165], v[82:83], 0, s[82:83]
	global_load_dword v131, v[164:165], off
	v_lshl_add_u64 v[164:165], v[82:83], 0, s[84:85]
	global_load_dword v132, v[164:165], off
	v_lshl_add_u64 v[164:165], v[82:83], 0, s[86:87]
	global_load_dword v133, v[164:165], off
	v_lshl_add_u64 v[164:165], v[82:83], 0, s[90:91]
	global_load_dword v134, v[164:165], off
	v_lshl_add_u64 v[164:165], v[82:83], 0, s[48:49]
	global_load_dword v135, v[164:165], off
	v_lshl_add_u64 v[164:165], v[82:83], 0, s[46:47]
	global_load_dword v136, v[164:165], off
	v_lshl_add_u64 v[164:165], v[82:83], 0, s[24:25]
	global_load_dword v137, v[164:165], off
	v_lshl_add_u64 v[164:165], v[82:83], 0, s[88:89]
	global_load_dword v138, v[164:165], off
	v_lshl_add_u64 v[164:165], v[82:83], 0, s[4:5]
	global_load_dword v139, v[164:165], off
	v_lshl_add_u64 v[164:165], v[82:83], 0, s[16:17]
	global_load_dword v140, v[164:165], off
	v_lshl_add_u64 v[164:165], v[82:83], 0, s[30:31]
	global_load_dword v141, v[164:165], off
	v_lshl_add_u64 v[164:165], v[82:83], 0, s[18:19]
	global_load_dword v142, v[164:165], off
	v_lshl_add_u64 v[164:165], v[82:83], 0, s[28:29]
	global_load_dword v143, v[164:165], off
	v_lshl_add_u64 v[164:165], v[82:83], 0, s[26:27]
	global_load_dword v144, v[164:165], off
	v_lshl_add_u64 v[164:165], v[82:83], 0, s[8:9]
	global_load_dword v145, v[164:165], off
	v_lshl_add_u64 v[164:165], v[84:85], 0, s[20:21]
	global_load_dword v146, v[164:165], off
	s_mov_b32 s98, s60
	s_ashr_i32 s99, s60, 31
	s_lshl_b64 s[98:99], s[98:99], 10
	v_lshl_add_u64 v[164:165], v[84:85], 0, s[98:99]
	global_load_dword v147, v[164:165], off
	s_mov_b32 s98, s6
	s_ashr_i32 s99, s6, 31
	s_lshl_b64 s[98:99], s[98:99], 10
	v_lshl_add_u64 v[164:165], v[84:85], 0, s[98:99]
	global_load_dword v148, v[164:165], off
	s_mov_b32 s98, s76
	s_ashr_i32 s99, s76, 31
	s_lshl_b64 s[98:99], s[98:99], 10
	v_lshl_add_u64 v[164:165], v[84:85], 0, s[98:99]
	global_load_dword v149, v[164:165], off
	s_mov_b32 s98, s36
	s_ashr_i32 s99, s36, 31
	s_lshl_b64 s[98:99], s[98:99], 10
	v_lshl_add_u64 v[164:165], v[84:85], 0, s[98:99]
	global_load_dword v150, v[164:165], off
	s_mov_b32 s98, s22
	s_ashr_i32 s99, s22, 31
	s_lshl_b64 s[98:99], s[98:99], 10
	v_lshl_add_u64 v[164:165], v[84:85], 0, s[98:99]
	global_load_dword v151, v[164:165], off
	s_mov_b32 s98, s78
	s_ashr_i32 s99, s78, 31
	s_lshl_b64 s[98:99], s[98:99], 10
	v_lshl_add_u64 v[164:165], v[84:85], 0, s[98:99]
	global_load_dword v152, v[164:165], off
	s_mov_b32 s98, s80
	s_ashr_i32 s99, s80, 31
	s_lshl_b64 s[98:99], s[98:99], 10
	v_lshl_add_u64 v[164:165], v[84:85], 0, s[98:99]
	global_load_dword v153, v[164:165], off
	s_mov_b32 s98, s34
	s_ashr_i32 s99, s34, 31
	s_lshl_b64 s[98:99], s[98:99], 10
	v_lshl_add_u64 v[164:165], v[84:85], 0, s[98:99]
	global_load_dword v154, v[164:165], off
	s_mov_b32 s98, s52
	s_ashr_i32 s99, s52, 31
	s_lshl_b64 s[98:99], s[98:99], 10
	v_lshl_add_u64 v[164:165], v[84:85], 0, s[98:99]
	global_load_dword v155, v[164:165], off
	s_mov_b32 s98, s54
	s_ashr_i32 s99, s54, 31
	s_lshl_b64 s[98:99], s[98:99], 10
	v_lshl_add_u64 v[164:165], v[84:85], 0, s[98:99]
	global_load_dword v156, v[164:165], off
	s_mov_b32 s98, s92
	s_ashr_i32 s99, s92, 31
	s_lshl_b64 s[98:99], s[98:99], 10
	v_lshl_add_u64 v[164:165], v[84:85], 0, s[98:99]
	global_load_dword v157, v[164:165], off
	s_mov_b32 s98, s96
	s_ashr_i32 s99, s96, 31
	s_lshl_b64 s[98:99], s[98:99], 10
	v_lshl_add_u64 v[164:165], v[84:85], 0, s[98:99]
	global_load_dword v158, v[164:165], off
	s_mov_b32 s98, s58
	s_ashr_i32 s99, s58, 31
	s_lshl_b64 s[98:99], s[98:99], 10
	v_lshl_add_u64 v[164:165], v[84:85], 0, s[98:99]
	global_load_dword v159, v[164:165], off
	s_mov_b32 s98, s56
	s_ashr_i32 s99, s56, 31
	s_lshl_b64 s[98:99], s[98:99], 10
	v_lshl_add_u64 v[164:165], v[84:85], 0, s[98:99]
	global_load_dword v162, v[164:165], off
	s_mov_b32 s98, s12
	s_ashr_i32 s99, s12, 31
	s_lshl_b64 s[98:99], s[98:99], 10
	v_lshl_add_u64 v[164:165], v[84:85], 0, s[98:99]
	global_load_dword v163, v[164:165], off
	v_mul_f32_e32 v97, v183, v183
	v_mul_f32_e32 v99, v187, v187
	v_add_f32_e32 v96, v182, v183
	v_fmac_f32_e32 v97, v182, v182
	v_add_f32_e32 v98, v186, v187
	v_fmac_f32_e32 v99, v186, v186
	v_mul_f32_e32 v101, v191, v191
	v_add_f32_e32 v100, v190, v191
	v_fmac_f32_e32 v101, v190, v190
	v_cndmask_b32_e64 v126, v96, v97, s[38:39]
	v_cndmask_b32_e64 v96, v97, v96, s[38:39]
	v_cndmask_b32_e64 v97, v98, v99, s[38:39]
	v_cndmask_b32_e64 v98, v99, v98, s[38:39]
	ds_bpermute_b32 v97, v2, v97
	v_cndmask_b32_e64 v99, v100, v101, s[38:39]
	ds_bpermute_b32 v126, v2, v126
	ds_bpermute_b32 v99, v2, v99
	v_mul_f32_e32 v105, v189, v189
	v_mul_f32_e32 v103, v193, v193
	v_add_f32_e32 v104, v188, v189
	v_fmac_f32_e32 v105, v188, v188
	v_mul_f32_e32 v107, v185, v185
	v_add_f32_e32 v102, v192, v193
	v_fmac_f32_e32 v103, v192, v192
	v_add_f32_e32 v106, v184, v185
	v_fmac_f32_e32 v107, v184, v184
	v_mul_f32_e32 v109, v181, v181
	s_waitcnt lgkmcnt(2)
	v_add_f32_e32 v97, v98, v97
	v_cndmask_b32_e64 v98, v101, v100, s[38:39]
	v_cndmask_b32_e64 v100, v104, v105, s[38:39]
	v_add_f32_e32 v108, v180, v181
	v_fmac_f32_e32 v109, v180, v180
	s_waitcnt lgkmcnt(1)
	v_add_f32_e32 v96, v96, v126
	v_cndmask_b32_e64 v126, v102, v103, s[38:39]
	s_waitcnt lgkmcnt(0)
	v_add_f32_e32 v98, v98, v99
	v_cndmask_b32_e64 v99, v103, v102, s[38:39]
	ds_bpermute_b32 v100, v2, v100
	v_cndmask_b32_e64 v102, v106, v107, s[38:39]
	ds_bpermute_b32 v102, v2, v102
	v_cndmask_b32_e64 v103, v108, v109, s[38:39]
	ds_bpermute_b32 v103, v2, v103
	v_cndmask_b32_e64 v101, v105, v104, s[38:39]
	v_mul_f32_e32 v111, v179, v179
	s_waitcnt lgkmcnt(2)
; #define LAS __attribute__((address_space(3)))
; #define LDS_WAIT() asm volatile("s_waitcnt lgkmcnt(0)" ::: "memory")
; __device__ __forceinline__ void co_phase(Frame& F, int layer, const float* cwa_, const float* cba_, const float* lng_, const float* lnb_, const float* cwb_, const float* p_) {
;     ...
;         {
;             float vals[2 * CO_R];
; #pragma unroll
;             for (int r = 0; r < CO_R; ++r) { vals[r] = acc[r].x + acc[r].y; vals[CO_R + r] = acc[r].x * acc[r].x + acc[r].y * acc[r].y; }
; #pragma unroll
;             for (int half = CO_R, bit = 32; half >= 1; half >>= 1, bit >>= 1) {
;                 const bool up = (F.lane & bit) != 0;
; #pragma unroll
;                 for (int i = 0; i < half; ++i) { const float send = up ? vals[i] : vals[i + half], keep = up ? vals[i + half] : vals[i]; vals[i] = keep + __shfl_xor(send, bit, 64); }
;             }
;             static_assert(CO_R == 16 || CO_R == 32, "the butterfly below ends with 2 (CO_R = 16) or 1 (CO_R = 32) lanes per value");
;             const float tot = CO_R == 16 ? vals[0] + __shfl_xor(vals[0], 1, 64) : vals[0];
;             const int idx = CO_R == 16 ? ((F.lane >> 1) & 31) : F.lane;
;             if (CO_R == 32 || (F.lane & 1) == 0) ((LAS float*)part)[((idx & (CO_R - 1)) * 4 + wv) * 2 + (idx >= CO_R ? 1 : 0)] = tot;
;         }
;         LDS_WAIT(); __builtin_amdgcn_s_barrier();
	v_add_f32_e32 v100, v101, v100
	v_cndmask_b32_e64 v101, v107, v106, s[38:39]
	v_add_f32_e32 v110, v178, v179
	v_fmac_f32_e32 v111, v178, v178
	v_mul_f32_e32 v113, v177, v177
	s_waitcnt lgkmcnt(1)
	v_add_f32_e32 v101, v101, v102
	v_cndmask_b32_e64 v102, v109, v108, s[38:39]
	v_add_f32_e32 v112, v176, v177
	v_fmac_f32_e32 v113, v176, v176
	v_mul_f32_e32 v115, v175, v175
	s_waitcnt lgkmcnt(0)
	v_add_f32_e32 v102, v102, v103
	v_cndmask_b32_e64 v103, v110, v111, s[38:39]
	v_add_f32_e32 v114, v174, v175
	v_fmac_f32_e32 v115, v174, v174
	ds_bpermute_b32 v103, v2, v103
	v_cndmask_b32_e64 v105, v112, v113, s[38:39]
	ds_bpermute_b32 v105, v2, v105
	v_cndmask_b32_e64 v106, v114, v115, s[38:39]
	ds_bpermute_b32 v106, v2, v106
	v_cndmask_b32_e64 v104, v111, v110, s[38:39]
	v_mul_f32_e32 v117, v173, v173
	s_waitcnt lgkmcnt(2)
	v_add_f32_e32 v103, v104, v103
	v_cndmask_b32_e64 v104, v113, v112, s[38:39]
	v_add_f32_e32 v116, v172, v173
	v_fmac_f32_e32 v117, v172, v172
	v_mul_f32_e32 v119, v171, v171
	s_waitcnt lgkmcnt(1)
	v_add_f32_e32 v104, v104, v105
	v_cndmask_b32_e64 v105, v115, v114, s[38:39]
	v_add_f32_e32 v118, v170, v171
	v_fmac_f32_e32 v119, v170, v170
	v_mul_f32_e32 v121, v169, v169
	s_waitcnt lgkmcnt(0)
	v_add_f32_e32 v105, v105, v106
	v_cndmask_b32_e64 v106, v116, v117, s[38:39]
	v_add_f32_e32 v120, v168, v169
	v_fmac_f32_e32 v121, v168, v168
	ds_bpermute_b32 v106, v2, v106
	v_cndmask_b32_e64 v108, v118, v119, s[38:39]
	ds_bpermute_b32 v108, v2, v108
	v_cndmask_b32_e64 v109, v120, v121, s[38:39]
	ds_bpermute_b32 v109, v2, v109
	v_cndmask_b32_e64 v107, v117, v116, s[38:39]
	v_mul_f32_e32 v123, v167, v167
	s_waitcnt lgkmcnt(2)
	v_add_f32_e32 v106, v107, v106
	v_cndmask_b32_e64 v107, v119, v118, s[38:39]
	v_pk_fma_f32 v[94:95], v[66:67], v[202:203], v[200:201]
	v_add_f32_e32 v122, v166, v167
	v_fmac_f32_e32 v123, v166, v166
	v_mul_f32_e32 v125, v161, v161
	s_waitcnt lgkmcnt(1)
	v_add_f32_e32 v107, v107, v108
	v_cndmask_b32_e64 v108, v121, v120, s[38:39]
	v_add_f32_e32 v124, v160, v161
	v_fmac_f32_e32 v125, v160, v160
	v_mul_f32_e32 v128, v94, v94
	s_waitcnt lgkmcnt(0)
	v_add_f32_e32 v108, v108, v109
	v_cndmask_b32_e64 v109, v122, v123, s[38:39]
	v_add_f32_e32 v127, v95, v94
	v_fmac_f32_e32 v128, v95, v95
	ds_bpermute_b32 v109, v2, v109
	v_cndmask_b32_e64 v111, v124, v125, s[38:39]
	ds_bpermute_b32 v111, v2, v111
	v_cndmask_b32_e64 v112, v127, v128, s[38:39]
	ds_bpermute_b32 v112, v2, v112
	v_cndmask_b32_e64 v110, v123, v122, s[38:39]
	s_waitcnt lgkmcnt(2)
	v_add_f32_e32 v109, v110, v109
	v_cndmask_b32_e64 v110, v125, v124, s[38:39]
	s_waitcnt lgkmcnt(1)
	v_add_f32_e32 v110, v110, v111
	v_cndmask_b32_e64 v111, v128, v127, s[38:39]
	ds_bpermute_b32 v126, v2, v126
	s_waitcnt lgkmcnt(1)
	v_add_f32_e32 v111, v111, v112
	v_cndmask_b32_e64 v112, v96, v104, s[40:41]
	v_cndmask_b32_e64 v96, v104, v96, s[40:41]
	ds_bpermute_b32 v104, v205, v112
	s_waitcnt lgkmcnt(1)
	v_add_f32_e32 v99, v99, v126
	v_cndmask_b32_e64 v112, v97, v105, s[40:41]
	v_cndmask_b32_e64 v97, v105, v97, s[40:41]
	v_cndmask_b32_e64 v105, v100, v108, s[40:41]
	s_waitcnt lgkmcnt(0)
	v_add_f32_e32 v96, v96, v104
	v_cndmask_b32_e64 v104, v99, v107, s[40:41]
	ds_bpermute_b32 v104, v205, v104
	ds_bpermute_b32 v105, v205, v105
	v_cndmask_b32_e64 v99, v107, v99, s[40:41]
	v_cndmask_b32_e64 v100, v108, v100, s[40:41]
	v_cndmask_b32_e64 v113, v98, v106, s[40:41]
	v_cndmask_b32_e64 v98, v106, v98, s[40:41]
	v_cndmask_b32_e64 v106, v101, v109, s[40:41]
	s_waitcnt lgkmcnt(1)
	v_add_f32_e32 v99, v99, v104
	s_waitcnt lgkmcnt(0)
	v_add_f32_e32 v100, v100, v105
	v_cndmask_b32_e64 v104, v102, v110, s[40:41]
	v_cndmask_b32_e64 v105, v103, v111, s[40:41]
	ds_bpermute_b32 v112, v205, v112
	ds_bpermute_b32 v113, v205, v113
	ds_bpermute_b32 v106, v205, v106
	ds_bpermute_b32 v104, v205, v104
	ds_bpermute_b32 v105, v205, v105
	v_cndmask_b32_e64 v101, v109, v101, s[40:41]
	v_cndmask_b32_e64 v102, v110, v102, s[40:41]
	v_cndmask_b32_e64 v103, v111, v103, s[40:41]
	s_waitcnt lgkmcnt(4)
	v_add_f32_e32 v97, v97, v112
	s_waitcnt lgkmcnt(3)
	v_add_f32_e32 v98, v98, v113
	s_waitcnt lgkmcnt(2)
	v_add_f32_e32 v101, v101, v106
	s_waitcnt lgkmcnt(1)
	v_add_f32_e32 v102, v102, v104
	s_waitcnt lgkmcnt(0)
	v_add_f32_e32 v103, v103, v105
	v_cndmask_b32_e64 v106, v96, v100, s[42:43]
	v_cndmask_b32_e64 v96, v100, v96, s[42:43]
	v_cndmask_b32_e64 v100, v97, v101, s[42:43]
	v_cndmask_b32_e64 v97, v101, v97, s[42:43]
	v_cndmask_b32_e64 v101, v98, v102, s[42:43]
	v_cndmask_b32_e64 v104, v99, v103, s[42:43]
	ds_bpermute_b32 v106, v206, v106
	ds_bpermute_b32 v100, v206, v100
	ds_bpermute_b32 v101, v206, v101
	ds_bpermute_b32 v104, v206, v104
	v_cndmask_b32_e64 v98, v102, v98, s[42:43]
	v_cndmask_b32_e64 v99, v103, v99, s[42:43]
	s_waitcnt lgkmcnt(3)
	v_add_f32_e32 v96, v96, v106
	s_waitcnt lgkmcnt(2)
	v_add_f32_e32 v97, v97, v100
	s_waitcnt lgkmcnt(1)
	v_add_f32_e32 v98, v98, v101
	s_waitcnt lgkmcnt(0)
	v_add_f32_e32 v99, v99, v104
	v_cndmask_b32_e64 v100, v96, v98, s[44:45]
	v_cndmask_b32_e64 v101, v97, v99, s[44:45]
	ds_bpermute_b32 v100, v207, v100
	ds_bpermute_b32 v101, v207, v101
	v_cndmask_b32_e64 v96, v98, v96, s[44:45]
	v_cndmask_b32_e64 v97, v99, v97, s[44:45]
	s_waitcnt lgkmcnt(1)
	v_add_f32_e32 v96, v96, v100
	s_waitcnt lgkmcnt(0)
	v_add_f32_e32 v97, v97, v101
	v_cndmask_b32_e64 v98, v96, v97, s[62:63]
	ds_bpermute_b32 v98, v208, v98
	v_cndmask_b32_e64 v96, v97, v96, s[62:63]
	s_waitcnt lgkmcnt(0)
	v_add_f32_e32 v96, v96, v98
	ds_bpermute_b32 v97, v204, v96
	s_and_saveexec_b64 s[50:51], s[64:65]
	s_cbranch_execz .LBB0_287
	s_waitcnt lgkmcnt(0)
	v_add_f32_e32 v96, v96, v97
	ds_write_b32 v209, v96

; __device__ __forceinline__ void co_phase(Frame& F, int layer, const float* cwa_, const float* cba_, const float* lng_, const float* lnb_, const float* cwb_, const float* p_) {
;     ...
;             unsigned cvr[CO_R + 2], bsr[CO_R];
; #pragma unroll
;             for (int r = 0; r < CO_R + 2; ++r) { const int gr = (t0 - 2 + r >= 0) ? g0 - 2 + r : g0; cvr[r] = CVp[(size_t)gr * (DSC / 2) + (c0 >> 1)]; }
; #pragma unroll
;             for (int r = 0; r < CO_R; ++r) bsr[r] = BSp[(size_t)(g0 + r) * (DSC / 2) + (c0 >> 1)];
;             auto sconv = [&](auto edge_tag) {
;                 constexpr bool EDGE = decltype(edge_tag)::value;
; #pragma unroll
;                 for (int r = 0; r < CO_R; ++r) {
;                     const bool ok2 = !EDGE || t0 + r >= 2, ok1 = !EDGE || t0 + r >= 1;
;                     const f32x2 c2 = {ok2 ? bf_lo(cvr[r]) : 0.f, ok2 ? bf_hi(cvr[r]) : 0.f}, c1 = {ok1 ? bf_lo(cvr[r + 1]) : 0.f, ok1 ? bf_hi(cvr[r + 1]) : 0.f};
;                     const f32x2 cc = {bf_lo(cvr[r + 2]), bf_hi(cvr[r + 2])}, b = {bf_lo(bsr[r]), bf_hi(bsr[r])};
;                     const f32x2 o = b * (wb0 * c2 + wb1 * c1 + wb2 * cc);
;                     if (live) A2S[(size_t)(g0 + r) * (D / 2) + (DC >> 1) + (c0 >> 1)] = pk2(o.x, o.y);
;                 }
.LBB0_319:
	v_lshl_add_u64 v[94:95], v[82:83], 0, s[20:21]
	s_waitcnt vmcnt(16)
	v_mov_b32_e32 v121, v130
	v_lshl_add_u64 v[94:95], v[82:83], 0, s[82:83]
	v_mov_b32_e32 v119, v131
	v_lshl_add_u64 v[94:95], v[82:83], 0, s[84:85]
	v_mov_b32_e32 v117, v132
	v_lshl_add_u64 v[94:95], v[82:83], 0, s[86:87]
	v_mov_b32_e32 v115, v133
	v_lshl_add_u64 v[94:95], v[82:83], 0, s[90:91]
	v_mov_b32_e32 v112, v134
	v_lshl_add_u64 v[94:95], v[82:83], 0, s[48:49]
	v_mov_b32_e32 v110, v135
	v_lshl_add_u64 v[94:95], v[82:83], 0, s[46:47]
	v_mov_b32_e32 v107, v136
	v_lshl_add_u64 v[94:95], v[82:83], 0, s[24:25]
	v_mov_b32_e32 v106, v137
	v_lshl_add_u64 v[94:95], v[82:83], 0, s[88:89]
	v_mov_b32_e32 v105, v138
	v_lshl_add_u64 v[94:95], v[82:83], 0, s[4:5]
	v_mov_b32_e32 v104, v139
	v_lshl_add_u64 v[94:95], v[82:83], 0, s[16:17]
	v_mov_b32_e32 v103, v140
	v_lshl_add_u64 v[94:95], v[82:83], 0, s[30:31]
	v_mov_b32_e32 v102, v141
	v_lshl_add_u64 v[94:95], v[82:83], 0, s[18:19]
	v_mov_b32_e32 v101, v142
	v_lshl_add_u64 v[94:95], v[82:83], 0, s[28:29]
	v_mov_b32_e32 v100, v143
	v_lshl_add_u64 v[94:95], v[82:83], 0, s[26:27]
	v_mov_b32_e32 v99, v144
	v_lshl_add_u64 v[94:95], v[82:83], 0, s[8:9]
	s_ashr_i32 s61, s60, 31
	v_mov_b32_e32 v98, v145
	v_lshl_add_u64 v[94:95], v[84:85], 0, s[20:21]
	s_lshl_b64 s[4:5], s[60:61], 10
	s_ashr_i32 s7, s6, 31
	v_mov_b32_e32 v129, v146
	v_lshl_add_u64 v[94:95], v[84:85], 0, s[4:5]
	s_lshl_b64 s[4:5], s[6:7], 10
	s_ashr_i32 s77, s76, 31
	v_mov_b32_e32 v128, v147
	v_lshl_add_u64 v[94:95], v[84:85], 0, s[4:5]
	s_lshl_b64 s[4:5], s[76:77], 10
	s_ashr_i32 s37, s36, 31
	v_mov_b32_e32 v127, v148
	v_lshl_add_u64 v[94:95], v[84:85], 0, s[4:5]
	s_lshl_b64 s[4:5], s[36:37], 10
	s_ashr_i32 s23, s22, 31
	v_mov_b32_e32 v126, v149
	v_lshl_add_u64 v[94:95], v[84:85], 0, s[4:5]
	s_lshl_b64 s[4:5], s[22:23], 10
	s_ashr_i32 s79, s78, 31
	v_mov_b32_e32 v125, v150
	v_lshl_add_u64 v[94:95], v[84:85], 0, s[4:5]
	s_lshl_b64 s[4:5], s[78:79], 10
	s_ashr_i32 s81, s80, 31
	v_mov_b32_e32 v124, v151
	v_lshl_add_u64 v[94:95], v[84:85], 0, s[4:5]
	s_lshl_b64 s[4:5], s[80:81], 10
	s_ashr_i32 s35, s34, 31
	v_mov_b32_e32 v122, v152
	v_lshl_add_u64 v[94:95], v[84:85], 0, s[4:5]
	s_lshl_b64 s[4:5], s[34:35], 10
	s_ashr_i32 s53, s52, 31
	v_mov_b32_e32 v123, v153
	v_lshl_add_u64 v[94:95], v[84:85], 0, s[4:5]
	s_lshl_b64 s[4:5], s[52:53], 10
	s_ashr_i32 s55, s54, 31
	v_mov_b32_e32 v120, v154
	v_lshl_add_u64 v[94:95], v[84:85], 0, s[4:5]
	s_lshl_b64 s[4:5], s[54:55], 10
	s_ashr_i32 s93, s92, 31
	v_mov_b32_e32 v118, v155
	v_lshl_add_u64 v[94:95], v[84:85], 0, s[4:5]
	s_lshl_b64 s[4:5], s[92:93], 10
	s_ashr_i32 s97, s96, 31
	v_mov_b32_e32 v116, v156
	v_lshl_add_u64 v[94:95], v[84:85], 0, s[4:5]
	s_lshl_b64 s[4:5], s[96:97], 10
	s_ashr_i32 s59, s58, 31
	v_mov_b32_e32 v114, v157
	v_lshl_add_u64 v[94:95], v[84:85], 0, s[4:5]
	s_lshl_b64 s[4:5], s[58:59], 10
	s_ashr_i32 s57, s56, 31
	v_mov_b32_e32 v113, v158
	v_lshl_add_u64 v[94:95], v[84:85], 0, s[4:5]
	s_lshl_b64 s[4:5], s[56:57], 10
	s_ashr_i32 s13, s12, 31
	v_mov_b32_e32 v111, v159
	v_lshl_add_u64 v[94:95], v[84:85], 0, s[4:5]
	s_lshl_b64 s[4:5], s[12:13], 10
	v_mov_b32_e32 v108, v162
	v_lshl_add_u64 v[94:95], v[84:85], 0, s[4:5]
	v_mov_b32_e32 v109, v163
	s_and_b64 vcc, exec, s[72:73]
	s_cbranch_vccz .LBB0_322
	v_readlane_b32 s96, v254, 17
	v_readlane_b32 s78, v254, 23
	s_mov_b64 s[4:5], 0
	s_and_b64 vcc, s[2:3], exec
	s_mov_b64 s[6:7], 0
	v_readlane_b32 s97, v254, 18
	v_readlane_b32 s79, v254, 24
	v_readlane_b32 s8, v253, 57
	s_mov_b32 s50, s94
	v_readlane_b32 s9, v253, 58
	s_cbranch_vccz .LBB0_323
	v_lshl_add_u64 v[94:95], v[82:83], 0, s[68:69]
	global_load_dword v132, v[94:95], off
	v_lshl_add_u64 v[94:95], v[82:83], 0, s[70:71]
	global_load_dword v130, v[94:95], off
	s_waitcnt vmcnt(33)
	v_and_b32_e32 v97, 0xffff0000, v121
	v_lshlrev_b32_e32 v96, 16, v121
	s_waitcnt vmcnt(17)
	v_and_b32_e32 v95, 0xffff0000, v129
	v_lshlrev_b32_e32 v94, 16, v129
	s_ashr_i32 s1, s0, 31
	s_lshl_b64 s[6:7], s[0:1], 11
	s_waitcnt vmcnt(1)
	v_and_b32_e32 v133, 0xffff0000, v132
	v_lshlrev_b32_e32 v132, 16, v132
	s_waitcnt vmcnt(0)
	v_and_b32_e32 v131, 0xffff0000, v130
	v_lshlrev_b32_e32 v130, 16, v130
	v_pk_mul_f32 v[134:135], v[40:41], v[130:131]
	s_nop 0
	v_pk_fma_f32 v[132:133], v[38:39], v[132:133], v[134:135]
	v_pk_mul_f32 v[134:135], v[40:41], v[96:97]
	v_pk_fma_f32 v[132:133], v[76:77], v[96:97], v[132:133]
	v_pk_fma_f32 v[130:131], v[38:39], v[130:131], v[134:135]
	v_pk_mul_f32 v[94:95], v[132:133], v[94:95]
	v_and_b32_e32 v133, 0xffff0000, v119
	v_cvt_pk_bf16_f32 v132, v94, v95
	v_lshl_add_u64 v[94:95], v[80:81], 0, s[6:7]
	global_store_dword v[94:95], v132, off offset:1024
	v_lshlrev_b32_e32 v132, 16, v119
	s_add_i32 s6, s0, 1
	v_and_b32_e32 v95, 0xffff0000, v128
	v_lshlrev_b32_e32 v94, 16, v128
	v_pk_fma_f32 v[130:131], v[76:77], v[132:133], v[130:131]
	s_ashr_i32 s7, s6, 31
	v_pk_mul_f32 v[94:95], v[130:131], v[94:95]
	s_lshl_b64 s[6:7], s[6:7], 11
	v_cvt_pk_bf16_f32 v130, v94, v95
	v_lshl_add_u64 v[94:95], v[80:81], 0, s[6:7]
	v_pk_mul_f32 v[134:135], v[40:41], v[132:133]
	global_store_dword v[94:95], v130, off offset:1024
	v_and_b32_e32 v131, 0xffff0000, v117
	v_lshlrev_b32_e32 v130, 16, v117
	v_pk_fma_f32 v[96:97], v[38:39], v[96:97], v[134:135]
	s_add_i32 s6, s0, 2
	v_and_b32_e32 v95, 0xffff0000, v127
	v_lshlrev_b32_e32 v94, 16, v127
	v_pk_fma_f32 v[96:97], v[76:77], v[130:131], v[96:97]
	s_ashr_i32 s7, s6, 31
	v_pk_mul_f32 v[94:95], v[96:97], v[94:95]
	s_lshl_b64 s[6:7], s[6:7], 11
	v_cvt_pk_bf16_f32 v96, v94, v95
	v_lshl_add_u64 v[94:95], v[80:81], 0, s[6:7]
	global_store_dword v[94:95], v96, off offset:1024
; __device__ __forceinline__ void co_phase(Frame& F, int layer, const float* cwa_, const float* cba_, const float* lng_, const float* lnb_, const float* cwb_, const float* p_) {
;     ...
;             auto sconv = [&](auto edge_tag) {
;                 constexpr bool EDGE = decltype(edge_tag)::value;
; #pragma unroll
;                 for (int r = 0; r < CO_R; ++r) {
;                     const bool ok2 = !EDGE || t0 + r >= 2, ok1 = !EDGE || t0 + r >= 1;
;                     const f32x2 c2 = {ok2 ? bf_lo(cvr[r]) : 0.f, ok2 ? bf_hi(cvr[r]) : 0.f}, c1 = {ok1 ? bf_lo(cvr[r + 1]) : 0.f, ok1 ? bf_hi(cvr[r + 1]) : 0.f};
;                     const f32x2 cc = {bf_lo(cvr[r + 2]), bf_hi(cvr[r + 2])}, b = {bf_lo(bsr[r]), bf_hi(bsr[r])};
;                     const f32x2 o = b * (wb0 * c2 + wb1 * c1 + wb2 * cc);
;                     if (live) A2S[(size_t)(g0 + r) * (D / 2) + (DC >> 1) + (c0 >> 1)] = pk2(o.x, o.y);
;                 }
	v_pk_mul_f32 v[96:97], v[40:41], v[130:131]
	v_and_b32_e32 v135, 0xffff0000, v115
	v_lshlrev_b32_e32 v134, 16, v115
	v_pk_fma_f32 v[96:97], v[38:39], v[132:133], v[96:97]
	s_add_i32 s6, s0, 3
	v_and_b32_e32 v95, 0xffff0000, v126
	v_lshlrev_b32_e32 v94, 16, v126
	v_pk_fma_f32 v[96:97], v[76:77], v[134:135], v[96:97]
	s_ashr_i32 s7, s6, 31
	v_pk_mul_f32 v[94:95], v[96:97], v[94:95]
	s_lshl_b64 s[6:7], s[6:7], 11
	v_cvt_pk_bf16_f32 v96, v94, v95
	v_lshl_add_u64 v[94:95], v[80:81], 0, s[6:7]
	v_pk_mul_f32 v[132:133], v[40:41], v[134:135]
	global_store_dword v[94:95], v96, off offset:1024
	v_and_b32_e32 v95, 0xffff0000, v112
	v_lshlrev_b32_e32 v94, 16, v112
	v_pk_fma_f32 v[130:131], v[38:39], v[130:131], v[132:133]
	s_add_i32 s6, s0, 4
	v_and_b32_e32 v97, 0xffff0000, v125
	v_lshlrev_b32_e32 v96, 16, v125
	v_pk_fma_f32 v[130:131], v[76:77], v[94:95], v[130:131]
	s_ashr_i32 s7, s6, 31
	v_pk_mul_f32 v[96:97], v[130:131], v[96:97]
	s_lshl_b64 s[6:7], s[6:7], 11
	v_cvt_pk_bf16_f32 v130, v96, v97
	v_lshl_add_u64 v[96:97], v[80:81], 0, s[6:7]
	v_pk_mul_f32 v[132:133], v[40:41], v[94:95]
	global_store_dword v[96:97], v130, off offset:1024
	v_and_b32_e32 v97, 0xffff0000, v110
	v_lshlrev_b32_e32 v96, 16, v110
	v_pk_fma_f32 v[132:133], v[38:39], v[134:135], v[132:133]
	s_add_i32 s6, s0, 5
	v_and_b32_e32 v131, 0xffff0000, v124
	v_lshlrev_b32_e32 v130, 16, v124
	v_pk_fma_f32 v[132:133], v[76:77], v[96:97], v[132:133]
	s_ashr_i32 s7, s6, 31
	v_pk_mul_f32 v[130:131], v[132:133], v[130:131]
	s_lshl_b64 s[6:7], s[6:7], 11
	v_cvt_pk_bf16_f32 v132, v130, v131
	v_lshl_add_u64 v[130:131], v[80:81], 0, s[6:7]
	v_pk_mul_f32 v[134:135], v[40:41], v[96:97]
	global_store_dword v[130:131], v132, off offset:1024
	v_and_b32_e32 v133, 0xffff0000, v107
	v_lshlrev_b32_e32 v132, 16, v107
	v_pk_fma_f32 v[94:95], v[38:39], v[94:95], v[134:135]
	s_add_i32 s6, s0, 6
	v_and_b32_e32 v131, 0xffff0000, v122
	v_lshlrev_b32_e32 v130, 16, v122
	v_pk_fma_f32 v[94:95], v[76:77], v[132:133], v[94:95]
	s_ashr_i32 s7, s6, 31
	v_pk_mul_f32 v[94:95], v[94:95], v[130:131]
	s_lshl_b64 s[6:7], s[6:7], 11
	v_cvt_pk_bf16_f32 v130, v94, v95
	v_lshl_add_u64 v[94:95], v[80:81], 0, s[6:7]
	v_pk_mul_f32 v[134:135], v[40:41], v[132:133]
	global_store_dword v[94:95], v130, off offset:1024
	v_and_b32_e32 v131, 0xffff0000, v106
	v_lshlrev_b32_e32 v130, 16, v106
	v_pk_fma_f32 v[96:97], v[38:39], v[96:97], v[134:135]
	s_add_i32 s6, s0, 7
	v_and_b32_e32 v95, 0xffff0000, v123
	v_lshlrev_b32_e32 v94, 16, v123
	v_pk_fma_f32 v[96:97], v[76:77], v[130:131], v[96:97]
	s_ashr_i32 s7, s6, 31
	v_pk_mul_f32 v[94:95], v[96:97], v[94:95]
	s_lshl_b64 s[6:7], s[6:7], 11
	v_cvt_pk_bf16_f32 v96, v94, v95
	v_lshl_add_u64 v[94:95], v[80:81], 0, s[6:7]
	v_pk_mul_f32 v[134:135], v[40:41], v[130:131]
	global_store_dword v[94:95], v96, off offset:1024
	v_and_b32_e32 v97, 0xffff0000, v105
	v_lshlrev_b32_e32 v96, 16, v105
	v_pk_fma_f32 v[132:133], v[38:39], v[132:133], v[134:135]
	s_add_i32 s6, s0, 8
	v_and_b32_e32 v95, 0xffff0000, v120
	v_lshlrev_b32_e32 v94, 16, v120
	v_pk_fma_f32 v[132:133], v[76:77], v[96:97], v[132:133]
	s_ashr_i32 s7, s6, 31
	v_pk_mul_f32 v[94:95], v[132:133], v[94:95]
	s_lshl_b64 s[6:7], s[6:7], 11
	v_cvt_pk_bf16_f32 v132, v94, v95
	v_lshl_add_u64 v[94:95], v[80:81], 0, s[6:7]
	v_pk_mul_f32 v[134:135], v[40:41], v[96:97]
	global_store_dword v[94:95], v132, off offset:1024
	v_and_b32_e32 v133, 0xffff0000, v104
	v_lshlrev_b32_e32 v132, 16, v104
	v_pk_fma_f32 v[130:131], v[38:39], v[130:131], v[134:135]
	s_add_i32 s6, s0, 9
; __device__ __forceinline__ void co_phase(Frame& F, int layer, const float* cwa_, const float* cba_, const float* lng_, const float* lnb_, const float* cwb_, const float* p_) {
;     ...
;             auto sconv = [&](auto edge_tag) {
;                 constexpr bool EDGE = decltype(edge_tag)::value;
; #pragma unroll
;                 for (int r = 0; r < CO_R; ++r) {
;                     const bool ok2 = !EDGE || t0 + r >= 2, ok1 = !EDGE || t0 + r >= 1;
;                     const f32x2 c2 = {ok2 ? bf_lo(cvr[r]) : 0.f, ok2 ? bf_hi(cvr[r]) : 0.f}, c1 = {ok1 ? bf_lo(cvr[r + 1]) : 0.f, ok1 ? bf_hi(cvr[r + 1]) : 0.f};
;                     const f32x2 cc = {bf_lo(cvr[r + 2]), bf_hi(cvr[r + 2])}, b = {bf_lo(bsr[r]), bf_hi(bsr[r])};
;                     const f32x2 o = b * (wb0 * c2 + wb1 * c1 + wb2 * cc);
;                     if (live) A2S[(size_t)(g0 + r) * (D / 2) + (DC >> 1) + (c0 >> 1)] = pk2(o.x, o.y);
;                 }
;             };
;             if (t0 < 2) sconv(BoolC<true>{}); else sconv(BoolC<false>{});
	v_and_b32_e32 v95, 0xffff0000, v118
	v_lshlrev_b32_e32 v94, 16, v118
	v_pk_fma_f32 v[130:131], v[76:77], v[132:133], v[130:131]
	s_ashr_i32 s7, s6, 31
	v_pk_mul_f32 v[94:95], v[130:131], v[94:95]
	s_lshl_b64 s[6:7], s[6:7], 11
	v_cvt_pk_bf16_f32 v130, v94, v95
	v_lshl_add_u64 v[94:95], v[80:81], 0, s[6:7]
	v_pk_mul_f32 v[134:135], v[40:41], v[132:133]
	global_store_dword v[94:95], v130, off offset:1024
	v_and_b32_e32 v131, 0xffff0000, v103
	v_lshlrev_b32_e32 v130, 16, v103
	v_pk_fma_f32 v[96:97], v[38:39], v[96:97], v[134:135]
	s_add_i32 s6, s0, 10
	v_and_b32_e32 v95, 0xffff0000, v116
	v_lshlrev_b32_e32 v94, 16, v116
	v_pk_fma_f32 v[96:97], v[76:77], v[130:131], v[96:97]
	s_ashr_i32 s7, s6, 31
	v_pk_mul_f32 v[94:95], v[96:97], v[94:95]
	s_lshl_b64 s[6:7], s[6:7], 11
	v_cvt_pk_bf16_f32 v96, v94, v95
	v_lshl_add_u64 v[94:95], v[80:81], 0, s[6:7]
	v_pk_mul_f32 v[134:135], v[40:41], v[130:131]
	global_store_dword v[94:95], v96, off offset:1024
	v_and_b32_e32 v97, 0xffff0000, v102
	v_lshlrev_b32_e32 v96, 16, v102
	v_pk_fma_f32 v[132:133], v[38:39], v[132:133], v[134:135]
	s_add_i32 s6, s0, 11
	v_and_b32_e32 v95, 0xffff0000, v114
	v_lshlrev_b32_e32 v94, 16, v114
	v_pk_fma_f32 v[132:133], v[76:77], v[96:97], v[132:133]
	s_ashr_i32 s7, s6, 31
	v_pk_mul_f32 v[94:95], v[132:133], v[94:95]
	s_lshl_b64 s[6:7], s[6:7], 11
	v_cvt_pk_bf16_f32 v132, v94, v95
	v_lshl_add_u64 v[94:95], v[80:81], 0, s[6:7]
	v_pk_mul_f32 v[134:135], v[40:41], v[96:97]
	global_store_dword v[94:95], v132, off offset:1024
	v_and_b32_e32 v133, 0xffff0000, v101
	v_lshlrev_b32_e32 v132, 16, v101
	v_pk_fma_f32 v[130:131], v[38:39], v[130:131], v[134:135]
	s_add_i32 s6, s0, 12
	v_and_b32_e32 v95, 0xffff0000, v113
	v_lshlrev_b32_e32 v94, 16, v113
	v_pk_fma_f32 v[130:131], v[76:77], v[132:133], v[130:131]
	s_ashr_i32 s7, s6, 31
	v_pk_mul_f32 v[94:95], v[130:131], v[94:95]
	s_lshl_b64 s[6:7], s[6:7], 11
	v_cvt_pk_bf16_f32 v130, v94, v95
	v_lshl_add_u64 v[94:95], v[80:81], 0, s[6:7]
	v_pk_mul_f32 v[134:135], v[40:41], v[132:133]
	global_store_dword v[94:95], v130, off offset:1024
	v_and_b32_e32 v131, 0xffff0000, v100
	v_lshlrev_b32_e32 v130, 16, v100
	v_pk_fma_f32 v[96:97], v[38:39], v[96:97], v[134:135]
	s_add_i32 s6, s0, 13
	v_and_b32_e32 v95, 0xffff0000, v111
	v_lshlrev_b32_e32 v94, 16, v111
	v_pk_fma_f32 v[96:97], v[76:77], v[130:131], v[96:97]
	s_ashr_i32 s7, s6, 31
	v_pk_mul_f32 v[94:95], v[96:97], v[94:95]
	s_lshl_b64 s[6:7], s[6:7], 11
	v_cvt_pk_bf16_f32 v96, v94, v95
	v_lshl_add_u64 v[94:95], v[80:81], 0, s[6:7]
	v_pk_mul_f32 v[134:135], v[40:41], v[130:131]
	global_store_dword v[94:95], v96, off offset:1024
	v_and_b32_e32 v97, 0xffff0000, v99
	v_lshlrev_b32_e32 v96, 16, v99
	v_pk_fma_f32 v[132:133], v[38:39], v[132:133], v[134:135]
	s_add_i32 s6, s0, 14
	v_and_b32_e32 v95, 0xffff0000, v108
	v_lshlrev_b32_e32 v94, 16, v108
	v_pk_fma_f32 v[132:133], v[76:77], v[96:97], v[132:133]
	s_ashr_i32 s7, s6, 31
	v_pk_mul_f32 v[94:95], v[132:133], v[94:95]
	s_lshl_b64 s[6:7], s[6:7], 11
	v_cvt_pk_bf16_f32 v132, v94, v95
	v_lshl_add_u64 v[94:95], v[80:81], 0, s[6:7]
	v_pk_mul_f32 v[96:97], v[40:41], v[96:97]
	global_store_dword v[94:95], v132, off offset:1024
	v_and_b32_e32 v133, 0xffff0000, v98
	v_lshlrev_b32_e32 v132, 16, v98
	v_pk_fma_f32 v[96:97], v[38:39], v[130:131], v[96:97]
	v_and_b32_e32 v95, 0xffff0000, v109
	v_lshlrev_b32_e32 v94, 16, v109
	v_pk_fma_f32 v[96:97], v[76:77], v[132:133], v[96:97]
	s_mov_b64 s[6:7], -1
	v_pk_mul_f32 v[94:95], v[96:97], v[94:95]
	s_nop 0
	v_cvt_pk_bf16_f32 v94, v94, v95
	s_branch .LBB0_323

; template <class Epi, class Sched, bool ALIGN_EPI = false, bool SP2 = false, bool ACHUNK = false>
; __device__ __forceinline__ void gemm_phase(PG8_LAS unsigned char* lds, const Gemm g, const Sched& S, const Epi& E) {
;     ...
;         const bool has_next = S.next(ui + 1, nxt);
;         const char* nA = has_next ? (const char*)g.A + (size_t)nxt.pm * tstepA : cA; const char* nB = has_next ? (const char*)g.Bt + (size_t)nxt.pn * tstepB : cB;
;         for (int t = 0; t < nt; t += 2) {
;     ...
;         else {
; #pragma unroll
;         for (int a = 0; a < 2; ++a)
; #pragma unroll
;             for (int b = 0; b < 2; ++b)
; #pragma unroll
;                 for (int m = 0; m < 4; ++m)
; #pragma unroll
;                     for (int n = 0; n < 2; ++n) acc[a][b][m][n] = (f32x4){0.f, 0.f, 0.f, 0.f};
;         }
.LBB0_351:
	s_andn2_b64 vcc, exec, s[4:5]
	s_cbranch_vccnz .LBB0_342
	s_add_u32 s40, s18, 0x100
	s_addc_u32 s41, s19, 0
	s_add_u32 s18, s20, 0x80
	v_mov_b32_e32 v4, 0
	s_addc_u32 s19, s21, 0
	s_mov_b32 s20, 0
	v_mov_b32_e32 v5, v4
	v_mov_b32_e32 v6, v4
	v_mov_b32_e32 v7, v4
	v_mov_b32_e32 v8, v4
	v_mov_b32_e32 v9, v4
	v_mov_b32_e32 v10, v4
	v_mov_b32_e32 v11, v4
	v_mov_b32_e32 v20, v4
	v_mov_b32_e32 v21, v4
	v_mov_b32_e32 v22, v4
	v_mov_b32_e32 v23, v4
	v_mov_b32_e32 v24, v4
	v_mov_b32_e32 v25, v4
	v_mov_b32_e32 v26, v4
	v_mov_b32_e32 v27, v4
	v_mov_b32_e32 v36, v4
	v_mov_b32_e32 v37, v4
	v_mov_b32_e32 v38, v4
	v_mov_b32_e32 v39, v4
	v_mov_b32_e32 v40, v4
	v_mov_b32_e32 v41, v4
	v_mov_b32_e32 v42, v4
	v_mov_b32_e32 v43, v4
	v_mov_b32_e32 v52, v4
	v_mov_b32_e32 v53, v4
	v_mov_b32_e32 v54, v4
	v_mov_b32_e32 v55, v4
	v_mov_b32_e32 v56, v4
	v_mov_b32_e32 v57, v4
	v_mov_b32_e32 v58, v4
	v_mov_b32_e32 v59, v4
	v_mov_b32_e32 v12, v4
	v_mov_b32_e32 v13, v4
	v_mov_b32_e32 v14, v4
	v_mov_b32_e32 v15, v4
	v_mov_b32_e32 v16, v4
	v_mov_b32_e32 v17, v4
	v_mov_b32_e32 v18, v4
	v_mov_b32_e32 v19, v4
	v_mov_b32_e32 v28, v4
	v_mov_b32_e32 v29, v4
	v_mov_b32_e32 v30, v4
	v_mov_b32_e32 v31, v4
	v_mov_b32_e32 v32, v4
	v_mov_b32_e32 v33, v4
	v_mov_b32_e32 v34, v4
	v_mov_b32_e32 v35, v4
	v_mov_b32_e32 v44, v4
	v_mov_b32_e32 v45, v4
	v_mov_b32_e32 v46, v4
	v_mov_b32_e32 v47, v4
	v_mov_b32_e32 v48, v4
	v_mov_b32_e32 v49, v4
	v_mov_b32_e32 v50, v4
	v_mov_b32_e32 v51, v4
	v_mov_b32_e32 v60, v4
	v_mov_b32_e32 v61, v4
	v_mov_b32_e32 v62, v4
	v_mov_b32_e32 v63, v4
	v_mov_b32_e32 v64, v4
	v_mov_b32_e32 v65, v4
	v_mov_b32_e32 v66, v4
	v_mov_b32_e32 v67, v4
	v_mov_b32_e32 v68, v4
	v_mov_b32_e32 v69, v4
	v_mov_b32_e32 v70, v4
	v_mov_b32_e32 v71, v4
	v_mov_b32_e32 v72, v4
	v_mov_b32_e32 v73, v4
	v_mov_b32_e32 v74, v4
	v_mov_b32_e32 v75, v4
	v_mov_b32_e32 v84, v4
	v_mov_b32_e32 v85, v4
	v_mov_b32_e32 v86, v4
	v_mov_b32_e32 v87, v4
	v_mov_b32_e32 v88, v4
	v_mov_b32_e32 v89, v4
	v_mov_b32_e32 v90, v4
	v_mov_b32_e32 v91, v4
	v_mov_b32_e32 v100, v4
	v_mov_b32_e32 v101, v4
	v_mov_b32_e32 v102, v4
	v_mov_b32_e32 v103, v4
	v_mov_b32_e32 v104, v4
	v_mov_b32_e32 v105, v4
	v_mov_b32_e32 v106, v4
	v_mov_b32_e32 v107, v4
	v_mov_b32_e32 v116, v4
	v_mov_b32_e32 v117, v4
	v_mov_b32_e32 v118, v4
	v_mov_b32_e32 v119, v4
	v_mov_b32_e32 v120, v4
	v_mov_b32_e32 v121, v4
	v_mov_b32_e32 v122, v4
	v_mov_b32_e32 v123, v4
	v_mov_b32_e32 v76, v4
	v_mov_b32_e32 v77, v4
	v_mov_b32_e32 v78, v4
	v_mov_b32_e32 v79, v4
	v_mov_b32_e32 v80, v4
	v_mov_b32_e32 v81, v4
	v_mov_b32_e32 v82, v4
	v_mov_b32_e32 v83, v4
	v_mov_b32_e32 v92, v4
	v_mov_b32_e32 v93, v4
	v_mov_b32_e32 v94, v4
	v_mov_b32_e32 v95, v4
	v_mov_b32_e32 v96, v4
	v_mov_b32_e32 v97, v4
	v_mov_b32_e32 v98, v4
	v_mov_b32_e32 v99, v4
	v_mov_b32_e32 v108, v4
	v_mov_b32_e32 v109, v4
	v_mov_b32_e32 v110, v4
	v_mov_b32_e32 v111, v4
	v_mov_b32_e32 v112, v4
	v_mov_b32_e32 v113, v4
	v_mov_b32_e32 v114, v4
	v_mov_b32_e32 v115, v4
	v_mov_b32_e32 v128, v4
	v_mov_b32_e32 v129, v4
	v_mov_b32_e32 v130, v4
	v_mov_b32_e32 v131, v4
	v_mov_b32_e32 v124, v4
	v_mov_b32_e32 v125, v4
	v_mov_b32_e32 v126, v4
	v_mov_b32_e32 v127, v4

; template <class Epi, class Sched, bool ALIGN_EPI = false, bool SP2 = false, bool ACHUNK = false>
; __device__ __forceinline__ void gemm_phase(PG8_LAS unsigned char* lds, const Gemm g, const Sched& S, const Epi& E) {
;     ...
;         const bool has_next = S.next(ui + 1, nxt);
;         const char* nA = has_next ? (const char*)g.A + (size_t)nxt.pm * tstepA : cA; const char* nB = has_next ? (const char*)g.Bt + (size_t)nxt.pn * tstepB : cB;
;         for (int t = 0; t < nt; t += 2) {
;     ...
;         else {
; #pragma unroll
;         for (int a = 0; a < 2; ++a)
; #pragma unroll
;             for (int b = 0; b < 2; ++b)
; #pragma unroll
;                 for (int m = 0; m < 4; ++m)
; #pragma unroll
;                     for (int n = 0; n < 2; ++n) acc[a][b][m][n] = (f32x4){0.f, 0.f, 0.f, 0.f};
;         }
.LBB0_375:
	s_andn2_b64 vcc, exec, s[34:35]
	s_cbranch_vccnz .LBB0_379
	s_add_u32 s4, s4, 0x80
	s_addc_u32 s5, s5, 0
	s_add_u32 s8, s6, 0x100
	v_mov_b32_e32 v8, 0
	s_addc_u32 s9, s7, 0
	s_mov_b32 s6, 0
	v_mov_b32_e32 v9, v8
	v_mov_b32_e32 v10, v8
	v_mov_b32_e32 v11, v8
	v_mov_b32_e32 v16, v8
	v_mov_b32_e32 v17, v8
	v_mov_b32_e32 v18, v8
	v_mov_b32_e32 v19, v8
	v_mov_b32_e32 v24, v8
	v_mov_b32_e32 v25, v8
	v_mov_b32_e32 v26, v8
	v_mov_b32_e32 v27, v8
	v_mov_b32_e32 v32, v8
	v_mov_b32_e32 v33, v8
	v_mov_b32_e32 v34, v8
	v_mov_b32_e32 v35, v8
	v_mov_b32_e32 v40, v8
	v_mov_b32_e32 v41, v8
	v_mov_b32_e32 v42, v8
	v_mov_b32_e32 v43, v8
	v_mov_b32_e32 v48, v8
	v_mov_b32_e32 v49, v8
	v_mov_b32_e32 v50, v8
	v_mov_b32_e32 v51, v8
	v_mov_b32_e32 v56, v8
	v_mov_b32_e32 v57, v8
	v_mov_b32_e32 v58, v8
	v_mov_b32_e32 v59, v8
	v_mov_b32_e32 v64, v8
	v_mov_b32_e32 v65, v8
	v_mov_b32_e32 v66, v8
	v_mov_b32_e32 v67, v8
	v_mov_b32_e32 v4, v8
	v_mov_b32_e32 v5, v8
	v_mov_b32_e32 v6, v8
	v_mov_b32_e32 v7, v8
	v_mov_b32_e32 v12, v8
	v_mov_b32_e32 v13, v8
	v_mov_b32_e32 v14, v8
	v_mov_b32_e32 v15, v8
	v_mov_b32_e32 v20, v8
	v_mov_b32_e32 v21, v8
	v_mov_b32_e32 v22, v8
	v_mov_b32_e32 v23, v8
	v_mov_b32_e32 v28, v8
	v_mov_b32_e32 v29, v8
	v_mov_b32_e32 v30, v8
	v_mov_b32_e32 v31, v8
	v_mov_b32_e32 v36, v8
	v_mov_b32_e32 v37, v8
	v_mov_b32_e32 v38, v8
	v_mov_b32_e32 v39, v8
	v_mov_b32_e32 v44, v8
	v_mov_b32_e32 v45, v8
	v_mov_b32_e32 v46, v8
	v_mov_b32_e32 v47, v8
	v_mov_b32_e32 v52, v8
	v_mov_b32_e32 v53, v8
	v_mov_b32_e32 v54, v8
	v_mov_b32_e32 v55, v8
	v_mov_b32_e32 v60, v8
	v_mov_b32_e32 v61, v8
	v_mov_b32_e32 v62, v8
	v_mov_b32_e32 v63, v8
	v_mov_b32_e32 v72, v8
	v_mov_b32_e32 v73, v8
	v_mov_b32_e32 v74, v8
	v_mov_b32_e32 v75, v8
	v_mov_b32_e32 v80, v8
	v_mov_b32_e32 v81, v8
	v_mov_b32_e32 v82, v8
	v_mov_b32_e32 v83, v8
	v_mov_b32_e32 v88, v8
	v_mov_b32_e32 v89, v8
	v_mov_b32_e32 v90, v8
	v_mov_b32_e32 v91, v8
	v_mov_b32_e32 v96, v8
	v_mov_b32_e32 v97, v8
	v_mov_b32_e32 v98, v8
	v_mov_b32_e32 v99, v8
	v_mov_b32_e32 v104, v8
	v_mov_b32_e32 v105, v8
	v_mov_b32_e32 v106, v8
	v_mov_b32_e32 v107, v8
	v_mov_b32_e32 v112, v8
	v_mov_b32_e32 v113, v8
	v_mov_b32_e32 v114, v8
	v_mov_b32_e32 v115, v8
	v_mov_b32_e32 v120, v8
	v_mov_b32_e32 v121, v8
	v_mov_b32_e32 v122, v8
	v_mov_b32_e32 v123, v8
	v_mov_b32_e32 v128, v8
	v_mov_b32_e32 v129, v8
	v_mov_b32_e32 v130, v8
	v_mov_b32_e32 v131, v8
	v_mov_b32_e32 v68, v8
	v_mov_b32_e32 v69, v8
	v_mov_b32_e32 v70, v8
	v_mov_b32_e32 v71, v8
	v_mov_b32_e32 v76, v8
	v_mov_b32_e32 v77, v8
	v_mov_b32_e32 v78, v8
	v_mov_b32_e32 v79, v8
	v_mov_b32_e32 v84, v8
	v_mov_b32_e32 v85, v8
	v_mov_b32_e32 v86, v8
	v_mov_b32_e32 v87, v8
	v_mov_b32_e32 v92, v8
	v_mov_b32_e32 v93, v8
	v_mov_b32_e32 v94, v8
	v_mov_b32_e32 v95, v8
	v_mov_b32_e32 v100, v8
	v_mov_b32_e32 v101, v8
	v_mov_b32_e32 v102, v8
	v_mov_b32_e32 v103, v8
	v_mov_b32_e32 v108, v8
	v_mov_b32_e32 v109, v8
	v_mov_b32_e32 v110, v8
	v_mov_b32_e32 v111, v8
	v_mov_b32_e32 v116, v8
	v_mov_b32_e32 v117, v8
	v_mov_b32_e32 v118, v8
	v_mov_b32_e32 v119, v8
	v_mov_b32_e32 v124, v8
	v_mov_b32_e32 v125, v8
	v_mov_b32_e32 v126, v8
	v_mov_b32_e32 v127, v8

; #define PG8_STAGE(bufoff, gbase, voff) do { _Pragma("unroll") for (int _i = 0; _i < 2; ++_i) \
;         __builtin_amdgcn_global_load_lds((const unsigned*)((const char*)(gbase) + (voff)[_i]), (PG8_LAS unsigned*)(lds + (bufoff) + ldsw + _i * 8192), 16, 0, 0); } while (0)
; #define PG8_LDA(dst, b, h) do { _Pragma("unroll") for (int m = 0; m < 4; ++m) _Pragma("unroll") for (int k = 0; k < 2; ++k) dst[m][k] = *(const PG8_LAS bf16x8*)(lds + PG8_SA(b, h) + aoff + m * 2048 + k * 1024); } while (0)
; #define PG8_LDB(dst, b, h) do { _Pragma("unroll") for (int n = 0; n < 2; ++n) _Pragma("unroll") for (int k = 0; k < 2; ++k) dst[n][k] = *(const PG8_LAS bf16x8*)(lds + PG8_SB(b, h) + boff + n * 2048 + k * 1024); } while (0)
; #define PG8_WAIT_V(n) asm volatile("s_waitcnt vmcnt(" #n ")" ::: "memory")
; #define PG8_WAIT_L(n) asm volatile("s_waitcnt lgkmcnt(" #n ")" ::: "memory")
; #define PG8_BAR __builtin_amdgcn_s_barrier()
; template <class Epi, class Sched, bool ALIGN_EPI = false, bool SP2 = false, bool ACHUNK = false>
; __device__ __forceinline__ void gemm_phase(PG8_LAS unsigned char* lds, const Gemm g, const Sched& S, const Epi& E) {
;     ...
;             const bool last = (t == nt - 2);
;             if constexpr (Epi::HAS_MID) { if (t == Epi::MID_T) E.mid(acc, cur, wr, wc, fr, fq, ShflDev{}); }
;             const char* a1 = cA + (size_t)(t + 1) * kstep;
;             const char* a2 = last ? nA : cA + (size_t)(t + 2) * kstep; const char* b2 = last ? nB : cB + (size_t)(t + 2) * kstep;
;             const char* a3 = a2 + kstep; const char* b3 = b2 + kstep;
;             if (last && has_next) S.a_ready(nxt);
;             if constexpr (SP2) {
;             PG8_LDB(B0, 0, 0); PG8_LDB(B1, 0, 1); PG8_SCHED; PG8_LDA(At, 0, 0); PG8_STAGE(PG8_SA(1, 1), a1 + hstepA, voffA);
;             PG8_WAIT_V(8); PG8_WAIT_L(0); PG8_BAR; PG8_MMA(0, 0, At, B0); PG8_MMA(0, 1, At, B1); PG8_BAR; PG8_SCHED;
;             PG8_LDA(At, 0, 1); PG8_STAGE(PG8_SB(0, 0), b2, voffB); PG8_STAGE(PG8_SB(0, 1), b2 + hstepB, voffB); PG8_STAGE(PG8_SA(0, 0), a2, voffA);
;     ...
;         else {
; #pragma unroll
;         for (int a = 0; a < 2; ++a)
; #pragma unroll
;             for (int b = 0; b < 2; ++b)
; #pragma unroll
;                 for (int m = 0; m < 4; ++m)
; #pragma unroll
;                     for (int n = 0; n < 2; ++n) acc[a][b][m][n] = (f32x4){0.f, 0.f, 0.f, 0.f};
;         }
.LBB0_429:
	s_andn2_b64 vcc, exec, s[54:55]
	s_nop 0
	s_cbranch_vccnz .LBB0_432
	s_add_u32 s0, s6, 0x80
	s_addc_u32 s1, s7, 0
	s_add_u32 s6, s4, 0x100
	v_mov_b32_e32 v4, 0
	s_addc_u32 s7, s5, 0
	s_mov_b32 s4, 0
	v_mov_b32_e32 v5, v4
	v_mov_b32_e32 v6, v4
	v_mov_b32_e32 v7, v4
	v_mov_b32_e32 v8, v4
	v_mov_b32_e32 v9, v4
	v_mov_b32_e32 v10, v4
	v_mov_b32_e32 v11, v4
	v_mov_b32_e32 v20, v4
	v_mov_b32_e32 v21, v4
	v_mov_b32_e32 v22, v4
	v_mov_b32_e32 v23, v4
	v_mov_b32_e32 v24, v4
	v_mov_b32_e32 v25, v4
	v_mov_b32_e32 v26, v4
	v_mov_b32_e32 v27, v4
	v_mov_b32_e32 v36, v4
	v_mov_b32_e32 v37, v4
	v_mov_b32_e32 v38, v4
	v_mov_b32_e32 v39, v4
	v_mov_b32_e32 v40, v4
	v_mov_b32_e32 v41, v4
	v_mov_b32_e32 v42, v4
	v_mov_b32_e32 v43, v4
	v_mov_b32_e32 v52, v4
	v_mov_b32_e32 v53, v4
	v_mov_b32_e32 v54, v4
	v_mov_b32_e32 v55, v4
	v_mov_b32_e32 v56, v4
	v_mov_b32_e32 v57, v4
	v_mov_b32_e32 v58, v4
	v_mov_b32_e32 v59, v4
	v_mov_b32_e32 v12, v4
	v_mov_b32_e32 v13, v4
	v_mov_b32_e32 v14, v4
	v_mov_b32_e32 v15, v4
	v_mov_b32_e32 v16, v4
	v_mov_b32_e32 v17, v4
	v_mov_b32_e32 v18, v4
	v_mov_b32_e32 v19, v4
	v_mov_b32_e32 v28, v4
	v_mov_b32_e32 v29, v4
	v_mov_b32_e32 v30, v4
	v_mov_b32_e32 v31, v4
	v_mov_b32_e32 v32, v4
	v_mov_b32_e32 v33, v4
	v_mov_b32_e32 v34, v4
	v_mov_b32_e32 v35, v4
	v_mov_b32_e32 v44, v4
	v_mov_b32_e32 v45, v4
	v_mov_b32_e32 v46, v4
	v_mov_b32_e32 v47, v4
	v_mov_b32_e32 v48, v4
	v_mov_b32_e32 v49, v4
	v_mov_b32_e32 v50, v4
	v_mov_b32_e32 v51, v4
	v_mov_b32_e32 v60, v4
	v_mov_b32_e32 v61, v4
	v_mov_b32_e32 v62, v4
	v_mov_b32_e32 v63, v4
	v_mov_b32_e32 v64, v4
	v_mov_b32_e32 v65, v4
	v_mov_b32_e32 v66, v4
	v_mov_b32_e32 v67, v4
	v_mov_b32_e32 v68, v4
	v_mov_b32_e32 v69, v4
	v_mov_b32_e32 v70, v4
	v_mov_b32_e32 v71, v4
	v_mov_b32_e32 v72, v4
	v_mov_b32_e32 v73, v4
	v_mov_b32_e32 v74, v4
	v_mov_b32_e32 v75, v4
	v_mov_b32_e32 v84, v4
	v_mov_b32_e32 v85, v4
	v_mov_b32_e32 v86, v4
	v_mov_b32_e32 v87, v4
	v_mov_b32_e32 v88, v4
	v_mov_b32_e32 v89, v4
	v_mov_b32_e32 v90, v4
	v_mov_b32_e32 v91, v4
	v_mov_b32_e32 v100, v4
	v_mov_b32_e32 v101, v4
	v_mov_b32_e32 v102, v4
	v_mov_b32_e32 v103, v4
	v_mov_b32_e32 v104, v4
	v_mov_b32_e32 v105, v4
	v_mov_b32_e32 v106, v4
	v_mov_b32_e32 v107, v4
	v_mov_b32_e32 v116, v4
	v_mov_b32_e32 v117, v4
	v_mov_b32_e32 v118, v4
	v_mov_b32_e32 v119, v4
	v_mov_b32_e32 v120, v4
	v_mov_b32_e32 v121, v4
	v_mov_b32_e32 v122, v4
	v_mov_b32_e32 v123, v4
	v_mov_b32_e32 v76, v4
	v_mov_b32_e32 v77, v4
	v_mov_b32_e32 v78, v4
	v_mov_b32_e32 v79, v4
	v_mov_b32_e32 v80, v4
	v_mov_b32_e32 v81, v4
	v_mov_b32_e32 v82, v4
	v_mov_b32_e32 v83, v4
	v_mov_b32_e32 v92, v4
	v_mov_b32_e32 v93, v4
	v_mov_b32_e32 v94, v4
	v_mov_b32_e32 v95, v4
	v_mov_b32_e32 v96, v4
	v_mov_b32_e32 v97, v4
	v_mov_b32_e32 v98, v4
	v_mov_b32_e32 v99, v4
	v_mov_b32_e32 v108, v4
	v_mov_b32_e32 v109, v4
	v_mov_b32_e32 v110, v4
	v_mov_b32_e32 v111, v4
	v_mov_b32_e32 v112, v4
	v_mov_b32_e32 v113, v4
	v_mov_b32_e32 v114, v4
	v_mov_b32_e32 v115, v4
	v_mov_b32_e32 v124, v4
	v_mov_b32_e32 v125, v4
	v_mov_b32_e32 v126, v4
	v_mov_b32_e32 v127, v4
	v_mov_b32_e32 v128, v4
	v_mov_b32_e32 v129, v4
	v_mov_b32_e32 v130, v4
	v_mov_b32_e32 v131, v4
.LBB0_431:
	s_add_i32 s8, s4, 2
	s_add_u32 s9, s0, 0x80
	s_addc_u32 s5, s1, 0
	s_add_i32 s15, 0, 0x10000
	s_cmp_eq_u32 s81, s4
	s_cselect_b32 s5, s31, s5
	s_cselect_b32 s4, s30, s9
	s_cselect_b32 s17, s93, s7
	s_cselect_b32 s16, s92, s6
	s_cbranch_scc0 .Lnl_pl
	s_cmpk_lg_u32 s87, 0x100
	s_cbranch_scc1 .Lnl_pl
	v_mov_b32_e32 v2, 0
	v_mov_b32_e32 v168, 0
	v_mov_b32_e32 v164, 0
	v_mov_b32_e32 v166, 0
.Lnl_pl:
	s_add_i32 s9, 0, 0x14000
	v_add_u32_e32 v144, s15, v221
	v_add_u32_e32 v160, s9, v221
	ds_read_b128 v[132:135], v144
	ds_read_b128 v[136:139], v144 offset:1024
	ds_read_b128 v[140:143], v144 offset:2048
	ds_read_b128 v[144:147], v144 offset:3072
	ds_read_b128 v[148:151], v160
	ds_read_b128 v[152:155], v160 offset:1024
	ds_read_b128 v[156:159], v160 offset:2048
	ds_read_b128 v[160:163], v160 offset:3072
	v_lshl_add_u64 v[214:215], s[0:1], 0, v[174:175]
	s_add_i32 m0, s27, 0xc000
	ds_read_b128 v[178:181], v223
	ds_read_b128 v[182:185], v223 offset:1024
	ds_read_b128 v[186:189], v223 offset:2048
	ds_read_b128 v[190:193], v223 offset:3072
	ds_read_b128 v[198:201], v223 offset:4096
	ds_read_b128 v[202:205], v223 offset:5120
	ds_read_b128 v[206:209], v223 offset:6144
	ds_read_b128 v[210:213], v223 offset:7168
	global_load_lds_dwordx4 v[214:215], off
	v_lshl_add_u64 v[214:215], s[0:1], 0, v[176:177]
	s_add_i32 m0, s27, 0xe000
	s_nop 0
	global_load_lds_dwordx4 v[214:215], off
	s_waitcnt vmcnt(8)
	s_waitcnt lgkmcnt(0)
	s_barrier
; #define PG8_STAGE(bufoff, gbase, voff) do { _Pragma("unroll") for (int _i = 0; _i < 2; ++_i) \
;         __builtin_amdgcn_global_load_lds((const unsigned*)((const char*)(gbase) + (voff)[_i]), (PG8_LAS unsigned*)(lds + (bufoff) + ldsw + _i * 8192), 16, 0, 0); } while (0)
; #define PG8_LDA(dst, b, h) do { _Pragma("unroll") for (int m = 0; m < 4; ++m) _Pragma("unroll") for (int k = 0; k < 2; ++k) dst[m][k] = *(const PG8_LAS bf16x8*)(lds + PG8_SA(b, h) + aoff + m * 2048 + k * 1024); } while (0)
; #define PG8_MMA(ai, bj, At, Bt) do { __builtin_amdgcn_s_setprio(1); _Pragma("unroll") for (int m = 0; m < 4; ++m) _Pragma("unroll") for (int n = 0; n < 2; ++n) _Pragma("unroll") for (int k = 0; k < 2; ++k) \
;         acc[ai][bj][m][n] = __builtin_amdgcn_mfma_f32_16x16x32_bf16(Bt[n][k], At[m][k], acc[ai][bj][m][n], 0, 0, 0); __builtin_amdgcn_s_setprio(0); } while (0)
; #define PG8_WAIT_V(n) asm volatile("s_waitcnt vmcnt(" #n ")" ::: "memory")
; #define PG8_WAIT_L(n) asm volatile("s_waitcnt lgkmcnt(" #n ")" ::: "memory")
; #define PG8_BAR __builtin_amdgcn_s_barrier()
; #define PG8_SCHED __builtin_amdgcn_sched_barrier(0)
; template <class Epi, class Sched, bool ALIGN_EPI = false, bool SP2 = false, bool ACHUNK = false>
; __device__ __forceinline__ void gemm_phase(PG8_LAS unsigned char* lds, const Gemm g, const Sched& S, const Epi& E) {
;     ...
;             PG8_WAIT_V(8); PG8_WAIT_L(0); PG8_BAR; PG8_MMA(0, 0, At, B0); PG8_MMA(0, 1, At, B1); PG8_BAR; PG8_SCHED;
;             PG8_LDA(At, 0, 1); PG8_STAGE(PG8_SB(0, 0), b2, voffB); PG8_STAGE(PG8_SB(0, 1), b2 + hstepB, voffB); PG8_STAGE(PG8_SA(0, 0), a2, voffA);
;             PG8_WAIT_V(8); PG8_WAIT_L(0); PG8_BAR; PG8_MMA(1, 0, At, B0); PG8_MMA(1, 1, At, B1); PG8_BAR; PG8_SCHED;
	s_setprio 1
	s_waitcnt lgkmcnt(0)
	v_mfma_f32_16x16x32_bf16 v[128:131], v[132:135], v[178:181], v[128:131]
	v_mfma_f32_16x16x32_bf16 v[124:127], v[140:143], v[178:181], v[124:127]
	v_mfma_f32_16x16x32_bf16 v[112:115], v[132:135], v[186:189], v[112:115]
	v_mfma_f32_16x16x32_bf16 v[108:111], v[140:143], v[186:189], v[108:111]
	v_mfma_f32_16x16x32_bf16 v[96:99], v[132:135], v[198:201], v[96:99]
	v_mfma_f32_16x16x32_bf16 v[92:95], v[140:143], v[198:201], v[92:95]
	v_mfma_f32_16x16x32_bf16 v[80:83], v[132:135], v[206:209], v[80:83]
	v_mfma_f32_16x16x32_bf16 v[76:79], v[140:143], v[206:209], v[76:79]
	v_mfma_f32_16x16x32_bf16 v[128:131], v[136:139], v[182:185], v[128:131]
	v_mfma_f32_16x16x32_bf16 v[124:127], v[144:147], v[182:185], v[124:127]
	v_mfma_f32_16x16x32_bf16 v[112:115], v[136:139], v[190:193], v[112:115]
	v_mfma_f32_16x16x32_bf16 v[108:111], v[144:147], v[190:193], v[108:111]
	v_mfma_f32_16x16x32_bf16 v[96:99], v[136:139], v[202:205], v[96:99]
	v_mfma_f32_16x16x32_bf16 v[92:95], v[144:147], v[202:205], v[92:95]
	v_mfma_f32_16x16x32_bf16 v[80:83], v[136:139], v[210:213], v[80:83]
	v_mfma_f32_16x16x32_bf16 v[76:79], v[144:147], v[210:213], v[76:79]
	s_setprio 0
	s_setprio 1
	v_mfma_f32_16x16x32_bf16 v[120:123], v[148:151], v[178:181], v[120:123]
	v_mfma_f32_16x16x32_bf16 v[116:119], v[156:159], v[178:181], v[116:119]
	v_mfma_f32_16x16x32_bf16 v[104:107], v[148:151], v[186:189], v[104:107]
	v_mfma_f32_16x16x32_bf16 v[100:103], v[156:159], v[186:189], v[100:103]
	v_mfma_f32_16x16x32_bf16 v[88:91], v[148:151], v[198:201], v[88:91]
	v_mfma_f32_16x16x32_bf16 v[84:87], v[156:159], v[198:201], v[84:87]
	v_mfma_f32_16x16x32_bf16 v[72:75], v[148:151], v[206:209], v[72:75]
	v_mfma_f32_16x16x32_bf16 v[68:71], v[156:159], v[206:209], v[68:71]
	v_mfma_f32_16x16x32_bf16 v[120:123], v[152:155], v[182:185], v[120:123]
	v_mfma_f32_16x16x32_bf16 v[116:119], v[160:163], v[182:185], v[116:119]
	v_mfma_f32_16x16x32_bf16 v[104:107], v[152:155], v[190:193], v[104:107]
	v_mfma_f32_16x16x32_bf16 v[100:103], v[160:163], v[190:193], v[100:103]
	v_mfma_f32_16x16x32_bf16 v[88:91], v[152:155], v[202:205], v[88:91]
	v_mfma_f32_16x16x32_bf16 v[84:87], v[160:163], v[202:205], v[84:87]
	v_mfma_f32_16x16x32_bf16 v[72:75], v[152:155], v[210:213], v[72:75]
	v_mfma_f32_16x16x32_bf16 v[68:71], v[160:163], v[210:213], v[68:71]
	s_setprio 0
	s_barrier
	s_add_i32 s15, s15, s26
	v_lshl_add_u64 v[214:215], s[16:17], 0, v[2:3]
	s_mov_b32 m0, s15
	ds_read_b128 v[178:181], v223 offset:16384
	ds_read_b128 v[182:185], v223 offset:17408
	ds_read_b128 v[186:189], v223 offset:18432
	ds_read_b128 v[190:193], v223 offset:19456
	ds_read_b128 v[198:201], v223 offset:20480
	ds_read_b128 v[202:205], v223 offset:21504
	ds_read_b128 v[206:209], v223 offset:22528
	ds_read_b128 v[210:213], v223 offset:23552
	global_load_lds_dwordx4 v[214:215], off
	s_add_i32 m0, s15, 0x2000
	v_lshl_add_u64 v[216:217], s[16:17], 0, v[168:169]
	s_add_u32 s16, s16, s18
	s_addc_u32 s17, s17, s19
	s_add_i32 s9, s9, s26
	global_load_lds_dwordx4 v[216:217], off
	v_lshl_add_u64 v[218:219], s[16:17], 0, v[2:3]
	s_mov_b32 m0, s9
	v_lshl_add_u64 v[232:233], s[16:17], 0, v[168:169]
	global_load_lds_dwordx4 v[218:219], off
	s_add_i32 m0, s9, 0x2000
	v_lshl_add_u64 v[234:235], s[4:5], 0, v[164:165]
	global_load_lds_dwordx4 v[232:233], off
	s_mov_b32 m0, s27
	v_lshl_add_u64 v[236:237], s[4:5], 0, v[166:167]
	global_load_lds_dwordx4 v[234:235], off
	s_mov_b32 m0, s36
	s_nop 0
	global_load_lds_dwordx4 v[236:237], off
	s_waitcnt vmcnt(8)
	s_waitcnt lgkmcnt(0)
	s_barrier
	s_setprio 1
	s_waitcnt lgkmcnt(0)
	v_mfma_f32_16x16x32_bf16 v[64:67], v[132:135], v[178:181], v[64:67]
	v_mfma_f32_16x16x32_bf16 v[60:63], v[140:143], v[178:181], v[60:63]
	v_mfma_f32_16x16x32_bf16 v[48:51], v[132:135], v[186:189], v[48:51]
	v_mfma_f32_16x16x32_bf16 v[44:47], v[140:143], v[186:189], v[44:47]
	v_mfma_f32_16x16x32_bf16 v[32:35], v[132:135], v[198:201], v[32:35]
	v_mfma_f32_16x16x32_bf16 v[28:31], v[140:143], v[198:201], v[28:31]
	v_mfma_f32_16x16x32_bf16 v[16:19], v[132:135], v[206:209], v[16:19]
	v_mfma_f32_16x16x32_bf16 v[12:15], v[140:143], v[206:209], v[12:15]
	v_mfma_f32_16x16x32_bf16 v[64:67], v[136:139], v[182:185], v[64:67]
	v_mfma_f32_16x16x32_bf16 v[60:63], v[144:147], v[182:185], v[60:63]
	v_mfma_f32_16x16x32_bf16 v[48:51], v[136:139], v[190:193], v[48:51]
	v_mfma_f32_16x16x32_bf16 v[44:47], v[144:147], v[190:193], v[44:47]
	v_mfma_f32_16x16x32_bf16 v[32:35], v[136:139], v[202:205], v[32:35]
	v_mfma_f32_16x16x32_bf16 v[28:31], v[144:147], v[202:205], v[28:31]
	v_mfma_f32_16x16x32_bf16 v[16:19], v[136:139], v[210:213], v[16:19]
	v_mfma_f32_16x16x32_bf16 v[12:15], v[144:147], v[210:213], v[12:15]
	s_setprio 0
	s_setprio 1
	v_mfma_f32_16x16x32_bf16 v[56:59], v[148:151], v[178:181], v[56:59]
	v_mfma_f32_16x16x32_bf16 v[52:55], v[156:159], v[178:181], v[52:55]
	v_mfma_f32_16x16x32_bf16 v[40:43], v[148:151], v[186:189], v[40:43]
	v_mfma_f32_16x16x32_bf16 v[36:39], v[156:159], v[186:189], v[36:39]
	v_mfma_f32_16x16x32_bf16 v[24:27], v[148:151], v[198:201], v[24:27]
	v_mfma_f32_16x16x32_bf16 v[20:23], v[156:159], v[198:201], v[20:23]
	v_mfma_f32_16x16x32_bf16 v[8:11], v[148:151], v[206:209], v[8:11]
	v_mfma_f32_16x16x32_bf16 v[4:7], v[156:159], v[206:209], v[4:7]
	v_mfma_f32_16x16x32_bf16 v[56:59], v[152:155], v[182:185], v[56:59]
	v_mfma_f32_16x16x32_bf16 v[52:55], v[160:163], v[182:185], v[52:55]
	v_mfma_f32_16x16x32_bf16 v[40:43], v[152:155], v[190:193], v[40:43]
	v_mfma_f32_16x16x32_bf16 v[36:39], v[160:163], v[190:193], v[36:39]
	v_mfma_f32_16x16x32_bf16 v[24:27], v[152:155], v[202:205], v[24:27]
	v_mfma_f32_16x16x32_bf16 v[20:23], v[160:163], v[202:205], v[20:23]
	v_mfma_f32_16x16x32_bf16 v[8:11], v[152:155], v[210:213], v[8:11]
	v_mfma_f32_16x16x32_bf16 v[4:7], v[160:163], v[210:213], v[4:7]
	s_setprio 0
	s_barrier
; #define PG8_STAGE(bufoff, gbase, voff) do { _Pragma("unroll") for (int _i = 0; _i < 2; ++_i) \
;         __builtin_amdgcn_global_load_lds((const unsigned*)((const char*)(gbase) + (voff)[_i]), (PG8_LAS unsigned*)(lds + (bufoff) + ldsw + _i * 8192), 16, 0, 0); } while (0)
; #define PG8_LDA(dst, b, h) do { _Pragma("unroll") for (int m = 0; m < 4; ++m) _Pragma("unroll") for (int k = 0; k < 2; ++k) dst[m][k] = *(const PG8_LAS bf16x8*)(lds + PG8_SA(b, h) + aoff + m * 2048 + k * 1024); } while (0)
; #define PG8_LDB(dst, b, h) do { _Pragma("unroll") for (int n = 0; n < 2; ++n) _Pragma("unroll") for (int k = 0; k < 2; ++k) dst[n][k] = *(const PG8_LAS bf16x8*)(lds + PG8_SB(b, h) + boff + n * 2048 + k * 1024); } while (0)
; #define PG8_MMA(ai, bj, At, Bt) do { __builtin_amdgcn_s_setprio(1); _Pragma("unroll") for (int m = 0; m < 4; ++m) _Pragma("unroll") for (int n = 0; n < 2; ++n) _Pragma("unroll") for (int k = 0; k < 2; ++k) \
;         acc[ai][bj][m][n] = __builtin_amdgcn_mfma_f32_16x16x32_bf16(Bt[n][k], At[m][k], acc[ai][bj][m][n], 0, 0, 0); __builtin_amdgcn_s_setprio(0); } while (0)
; #define PG8_WAIT_V(n) asm volatile("s_waitcnt vmcnt(" #n ")" ::: "memory")
; #define PG8_WAIT_L(n) asm volatile("s_waitcnt lgkmcnt(" #n ")" ::: "memory")
; #define PG8_BAR __builtin_amdgcn_s_barrier()
; #define PG8_SCHED __builtin_amdgcn_sched_barrier(0)
; template <class Epi, class Sched, bool ALIGN_EPI = false, bool SP2 = false, bool ACHUNK = false>
; __device__ __forceinline__ void gemm_phase(PG8_LAS unsigned char* lds, const Gemm g, const Sched& S, const Epi& E) {
;     ...
;             PG8_LDB(B0, 1, 0); PG8_LDB(B1, 1, 1); PG8_SCHED; PG8_LDA(At, 1, 0); PG8_STAGE(PG8_SA(0, 1), a2 + hstepA, voffA);
;             PG8_WAIT_V(8); PG8_WAIT_L(0); PG8_BAR; PG8_MMA(0, 0, At, B0); PG8_MMA(0, 1, At, B1); PG8_BAR; PG8_SCHED;
	s_add_i32 s9, 0, 0x18000
	s_add_i32 s15, 0, 0x1c000
	v_add_u32_e32 v144, s9, v221
	v_add_u32_e32 v160, s15, v221
	ds_read_b128 v[132:135], v144
	ds_read_b128 v[136:139], v144 offset:1024
	ds_read_b128 v[140:143], v144 offset:2048
	ds_read_b128 v[144:147], v144 offset:3072
	ds_read_b128 v[148:151], v160
	ds_read_b128 v[152:155], v160 offset:1024
	ds_read_b128 v[156:159], v160 offset:2048
	ds_read_b128 v[160:163], v160 offset:3072
	s_add_u32 s4, s4, s18
	s_addc_u32 s5, s5, s19
	s_mov_b32 m0, s37
	v_lshl_add_u64 v[238:239], s[4:5], 0, v[164:165]
	ds_read_b128 v[178:181], v223 offset:32768
	ds_read_b128 v[182:185], v223 offset:33792
	ds_read_b128 v[186:189], v223 offset:34816
	ds_read_b128 v[190:193], v223 offset:35840
	ds_read_b128 v[198:201], v223 offset:36864
	ds_read_b128 v[202:205], v223 offset:37888
	ds_read_b128 v[206:209], v223 offset:38912
	ds_read_b128 v[210:213], v223 offset:39936
	global_load_lds_dwordx4 v[238:239], off
	v_lshl_add_u64 v[238:239], s[4:5], 0, v[166:167]
	s_mov_b32 m0, s76
	s_nop 0
	global_load_lds_dwordx4 v[238:239], off
	s_waitcnt vmcnt(8)
	s_waitcnt lgkmcnt(0)
	s_barrier
	s_setprio 1
	s_waitcnt lgkmcnt(0)
	v_mfma_f32_16x16x32_bf16 v[128:131], v[132:135], v[178:181], v[128:131]
	v_mfma_f32_16x16x32_bf16 v[124:127], v[140:143], v[178:181], v[124:127]
	v_mfma_f32_16x16x32_bf16 v[112:115], v[132:135], v[186:189], v[112:115]
	v_mfma_f32_16x16x32_bf16 v[108:111], v[140:143], v[186:189], v[108:111]
	v_mfma_f32_16x16x32_bf16 v[96:99], v[132:135], v[198:201], v[96:99]
	v_mfma_f32_16x16x32_bf16 v[92:95], v[140:143], v[198:201], v[92:95]
	v_mfma_f32_16x16x32_bf16 v[80:83], v[132:135], v[206:209], v[80:83]
	v_mfma_f32_16x16x32_bf16 v[76:79], v[140:143], v[206:209], v[76:79]
	v_mfma_f32_16x16x32_bf16 v[128:131], v[136:139], v[182:185], v[128:131]
	v_mfma_f32_16x16x32_bf16 v[124:127], v[144:147], v[182:185], v[124:127]
	v_mfma_f32_16x16x32_bf16 v[112:115], v[136:139], v[190:193], v[112:115]
	v_mfma_f32_16x16x32_bf16 v[108:111], v[144:147], v[190:193], v[108:111]
	v_mfma_f32_16x16x32_bf16 v[96:99], v[136:139], v[202:205], v[96:99]
	v_mfma_f32_16x16x32_bf16 v[92:95], v[144:147], v[202:205], v[92:95]
	v_mfma_f32_16x16x32_bf16 v[80:83], v[136:139], v[210:213], v[80:83]
	v_mfma_f32_16x16x32_bf16 v[76:79], v[144:147], v[210:213], v[76:79]
	s_setprio 0
	s_setprio 1
	v_mfma_f32_16x16x32_bf16 v[120:123], v[148:151], v[178:181], v[120:123]
	v_mfma_f32_16x16x32_bf16 v[116:119], v[156:159], v[178:181], v[116:119]
	v_mfma_f32_16x16x32_bf16 v[104:107], v[148:151], v[186:189], v[104:107]
	v_mfma_f32_16x16x32_bf16 v[100:103], v[156:159], v[186:189], v[100:103]
	v_mfma_f32_16x16x32_bf16 v[88:91], v[148:151], v[198:201], v[88:91]
	v_mfma_f32_16x16x32_bf16 v[84:87], v[156:159], v[198:201], v[84:87]
	v_mfma_f32_16x16x32_bf16 v[72:75], v[148:151], v[206:209], v[72:75]
	v_mfma_f32_16x16x32_bf16 v[68:71], v[156:159], v[206:209], v[68:71]
	v_mfma_f32_16x16x32_bf16 v[120:123], v[152:155], v[182:185], v[120:123]
	v_mfma_f32_16x16x32_bf16 v[116:119], v[160:163], v[182:185], v[116:119]
	v_mfma_f32_16x16x32_bf16 v[104:107], v[152:155], v[190:193], v[104:107]
	v_mfma_f32_16x16x32_bf16 v[100:103], v[160:163], v[190:193], v[100:103]
	v_mfma_f32_16x16x32_bf16 v[88:91], v[152:155], v[202:205], v[88:91]
	v_mfma_f32_16x16x32_bf16 v[84:87], v[160:163], v[202:205], v[84:87]
	v_mfma_f32_16x16x32_bf16 v[72:75], v[152:155], v[210:213], v[72:75]
	v_mfma_f32_16x16x32_bf16 v[68:71], v[160:163], v[210:213], v[68:71]
	s_setprio 0
	s_barrier
; #define PG8_STAGE(bufoff, gbase, voff) do { _Pragma("unroll") for (int _i = 0; _i < 2; ++_i) \
;         __builtin_amdgcn_global_load_lds((const unsigned*)((const char*)(gbase) + (voff)[_i]), (PG8_LAS unsigned*)(lds + (bufoff) + ldsw + _i * 8192), 16, 0, 0); } while (0)
; #define PG8_LDA(dst, b, h) do { _Pragma("unroll") for (int m = 0; m < 4; ++m) _Pragma("unroll") for (int k = 0; k < 2; ++k) dst[m][k] = *(const PG8_LAS bf16x8*)(lds + PG8_SA(b, h) + aoff + m * 2048 + k * 1024); } while (0)
; #define PG8_MMA(ai, bj, At, Bt) do { __builtin_amdgcn_s_setprio(1); _Pragma("unroll") for (int m = 0; m < 4; ++m) _Pragma("unroll") for (int n = 0; n < 2; ++n) _Pragma("unroll") for (int k = 0; k < 2; ++k) \
;         acc[ai][bj][m][n] = __builtin_amdgcn_mfma_f32_16x16x32_bf16(Bt[n][k], At[m][k], acc[ai][bj][m][n], 0, 0, 0); __builtin_amdgcn_s_setprio(0); } while (0)
; #define PG8_WAIT_V(n) asm volatile("s_waitcnt vmcnt(" #n ")" ::: "memory")
; #define PG8_WAIT_L(n) asm volatile("s_waitcnt lgkmcnt(" #n ")" ::: "memory")
; #define PG8_BAR __builtin_amdgcn_s_barrier()
; #define PG8_SCHED __builtin_amdgcn_sched_barrier(0)
; template <class Epi, class Sched, bool ALIGN_EPI = false, bool SP2 = false, bool ACHUNK = false>
; __device__ __forceinline__ void gemm_phase(PG8_LAS unsigned char* lds, const Gemm g, const Sched& S, const Epi& E) {
;     ...
;         for (int t = 0; t < nt; t += 2) {
;     ...
;             PG8_LDA(At, 1, 1); PG8_STAGE(PG8_SB(1, 0), b3, voffB); PG8_STAGE(PG8_SB(1, 1), b3 + hstepB, voffB); PG8_STAGE(PG8_SA(1, 0), a3, voffA);
;             PG8_WAIT_V(8); PG8_WAIT_L(0); PG8_BAR; PG8_MMA(1, 0, At, B0); PG8_MMA(1, 1, At, B1); PG8_BAR; PG8_SCHED;
	s_add_i32 s4, s9, s26
	v_lshl_add_u64 v[214:215], v[214:215], 0, s[10:11]
	s_mov_b32 m0, s4
	ds_read_b128 v[178:181], v223 offset:49152
	ds_read_b128 v[182:185], v223 offset:50176
	ds_read_b128 v[186:189], v223 offset:51200
	ds_read_b128 v[190:193], v223 offset:52224
	ds_read_b128 v[198:201], v223 offset:53248
	ds_read_b128 v[202:205], v223 offset:54272
	ds_read_b128 v[206:209], v223 offset:55296
	ds_read_b128 v[210:213], v223 offset:56320
	global_load_lds_dwordx4 v[214:215], off
	v_lshl_add_u64 v[214:215], v[216:217], 0, s[10:11]
	s_add_i32 m0, s4, 0x2000
	s_add_i32 s4, s15, s26
	global_load_lds_dwordx4 v[214:215], off
	v_lshl_add_u64 v[214:215], v[218:219], 0, s[10:11]
	s_mov_b32 m0, s4
	s_nop 0
	global_load_lds_dwordx4 v[214:215], off
	v_lshl_add_u64 v[214:215], v[232:233], 0, s[10:11]
	s_add_i32 m0, s4, 0x2000
	s_nop 0
	global_load_lds_dwordx4 v[214:215], off
	v_lshl_add_u64 v[214:215], v[234:235], 0, s[10:11]
	s_mov_b32 m0, s77
	s_nop 0
	global_load_lds_dwordx4 v[214:215], off
	v_lshl_add_u64 v[214:215], v[236:237], 0, s[10:11]
	s_mov_b32 m0, s78
	s_nop 0
	global_load_lds_dwordx4 v[214:215], off
	s_waitcnt vmcnt(8)
	s_waitcnt lgkmcnt(0)
	s_barrier
	s_setprio 1
	s_waitcnt lgkmcnt(0)
	v_mfma_f32_16x16x32_bf16 v[64:67], v[132:135], v[178:181], v[64:67]
	v_mfma_f32_16x16x32_bf16 v[60:63], v[140:143], v[178:181], v[60:63]
	v_mfma_f32_16x16x32_bf16 v[48:51], v[132:135], v[186:189], v[48:51]
	v_mfma_f32_16x16x32_bf16 v[44:47], v[140:143], v[186:189], v[44:47]
	v_mfma_f32_16x16x32_bf16 v[32:35], v[132:135], v[198:201], v[32:35]
	v_mfma_f32_16x16x32_bf16 v[28:31], v[140:143], v[198:201], v[28:31]
	v_mfma_f32_16x16x32_bf16 v[16:19], v[132:135], v[206:209], v[16:19]
	v_mfma_f32_16x16x32_bf16 v[12:15], v[140:143], v[206:209], v[12:15]
	v_mfma_f32_16x16x32_bf16 v[64:67], v[136:139], v[182:185], v[64:67]
	v_mfma_f32_16x16x32_bf16 v[60:63], v[144:147], v[182:185], v[60:63]
	v_mfma_f32_16x16x32_bf16 v[48:51], v[136:139], v[190:193], v[48:51]
	v_mfma_f32_16x16x32_bf16 v[44:47], v[144:147], v[190:193], v[44:47]
	v_mfma_f32_16x16x32_bf16 v[32:35], v[136:139], v[202:205], v[32:35]
	v_mfma_f32_16x16x32_bf16 v[28:31], v[144:147], v[202:205], v[28:31]
	v_mfma_f32_16x16x32_bf16 v[16:19], v[136:139], v[210:213], v[16:19]
	v_mfma_f32_16x16x32_bf16 v[12:15], v[144:147], v[210:213], v[12:15]
	s_setprio 0
	s_setprio 1
	v_mfma_f32_16x16x32_bf16 v[56:59], v[148:151], v[178:181], v[56:59]
	v_mfma_f32_16x16x32_bf16 v[52:55], v[156:159], v[178:181], v[52:55]
	v_mfma_f32_16x16x32_bf16 v[40:43], v[148:151], v[186:189], v[40:43]
	v_mfma_f32_16x16x32_bf16 v[36:39], v[156:159], v[186:189], v[36:39]
	v_mfma_f32_16x16x32_bf16 v[24:27], v[148:151], v[198:201], v[24:27]
	v_mfma_f32_16x16x32_bf16 v[20:23], v[156:159], v[198:201], v[20:23]
	v_mfma_f32_16x16x32_bf16 v[8:11], v[148:151], v[206:209], v[8:11]
	v_mfma_f32_16x16x32_bf16 v[4:7], v[156:159], v[206:209], v[4:7]
	v_mfma_f32_16x16x32_bf16 v[56:59], v[152:155], v[182:185], v[56:59]
	v_mfma_f32_16x16x32_bf16 v[52:55], v[160:163], v[182:185], v[52:55]
	v_mfma_f32_16x16x32_bf16 v[40:43], v[152:155], v[190:193], v[40:43]
	v_mfma_f32_16x16x32_bf16 v[36:39], v[160:163], v[190:193], v[36:39]
	v_mfma_f32_16x16x32_bf16 v[24:27], v[152:155], v[202:205], v[24:27]
	v_mfma_f32_16x16x32_bf16 v[20:23], v[160:163], v[202:205], v[20:23]
	v_mfma_f32_16x16x32_bf16 v[8:11], v[152:155], v[210:213], v[8:11]
	v_mfma_f32_16x16x32_bf16 v[4:7], v[160:163], v[210:213], v[4:7]
	s_setprio 0
	s_barrier
	s_add_u32 s0, s0, 0x100
	s_addc_u32 s1, s1, 0
	s_add_u32 s6, s6, 0x100
	s_addc_u32 s7, s7, 0
	s_cmp_ge_i32 s8, s80
	s_mov_b32 s4, s8
	s_cbranch_scc0 .LBB0_431

; __device__ __forceinline__ unsigned xb_ld(unsigned* p)              { return __hip_atomic_load(p, __ATOMIC_RELAXED, __HIP_MEMORY_SCOPE_AGENT); }
; __device__ __forceinline__ unsigned xb_add(unsigned* p, unsigned v) { return __hip_atomic_fetch_add(p, v, __ATOMIC_RELAXED, __HIP_MEMORY_SCOPE_AGENT); }
; #define XB_SPIN(cond, bar) do { unsigned _sp = 0; while (cond) { __builtin_amdgcn_s_sleep(1); \
;     if ((++_sp & 255u) == 0u) { if (xb_ld(&(bar)[XB_TMO])) break; if (_sp > XB_SPIN_CAP) { atomicAdd(&(bar)[XB_TMO], 1u); break; } } } } while (0)
; __device__ __forceinline__ void xcd_barrier_thread0(const XcdBarrier& b) {
;     ...
;         if (old + 1u == (gen + 1u) * nloc) {
;             __builtin_amdgcn_fence(__ATOMIC_RELEASE, "agent");
;             asm volatile("s_waitcnt vmcnt(0)" ::: "memory");
;             const unsigned og = xb_add(&bar[XB_TOP], 1u);
;             const unsigned tg = og / nx;
;             if (og + 1u == (tg + 1u) * nx) xb_add(&bar[XB_TOPGEN], 1u);
;             else XB_SPIN(xb_ld(&bar[XB_TOPGEN]) == tg, bar);
;             __builtin_amdgcn_fence(__ATOMIC_ACQUIRE, "agent");
;             xb_add(&bar[XB_XGEN(b.x)], 1u);
;             asm volatile("s_waitcnt vmcnt(0)" ::: "memory");
.LBB0_532:
	s_or_b64 exec, exec, s[6:7]
	s_mov_b64 s[6:7], exec
	v_mbcnt_lo_u32_b32 v4, s6, 0
	v_mbcnt_hi_u32_b32 v4, s7, v4
	v_cmp_eq_u32_e32 vcc, 0, v4
	s_waitcnt vmcnt(0)
	s_and_saveexec_b64 s[8:9], vcc
	s_cbranch_execz .LBB0_534
	s_bcnt1_i32_b64 s6, s[6:7]
	v_mov_b32_e32 v4, s6
	v_readlane_b32 s6, v253, 10
	v_readlane_b32 s7, v253, 11
	s_nop 4
	s_nop 0

; __device__ __forceinline__ unsigned xb_ld(unsigned* p)              { return __hip_atomic_load(p, __ATOMIC_RELAXED, __HIP_MEMORY_SCOPE_AGENT); }
; __device__ __forceinline__ unsigned xb_add(unsigned* p, unsigned v) { return __hip_atomic_fetch_add(p, v, __ATOMIC_RELAXED, __HIP_MEMORY_SCOPE_AGENT); }
; #define XB_SPIN(cond, bar) do { unsigned _sp = 0; while (cond) { __builtin_amdgcn_s_sleep(1); \
;     if ((++_sp & 255u) == 0u) { if (xb_ld(&(bar)[XB_TMO])) break; if (_sp > XB_SPIN_CAP) { atomicAdd(&(bar)[XB_TMO], 1u); break; } } } } while (0)
; __device__ __forceinline__ void xcd_barrier_thread0(const XcdBarrier& b) {
;     ...
;         if (old + 1u == (gen + 1u) * nloc) {
;             __builtin_amdgcn_fence(__ATOMIC_RELEASE, "agent");
;             asm volatile("s_waitcnt vmcnt(0)" ::: "memory");
;             const unsigned og = xb_add(&bar[XB_TOP], 1u);
;             const unsigned tg = og / nx;
;             if (og + 1u == (tg + 1u) * nx) xb_add(&bar[XB_TOPGEN], 1u);
;             else XB_SPIN(xb_ld(&bar[XB_TOPGEN]) == tg, bar);
;             __builtin_amdgcn_fence(__ATOMIC_ACQUIRE, "agent");
;             xb_add(&bar[XB_XGEN(b.x)], 1u);
;             asm volatile("s_waitcnt vmcnt(0)" ::: "memory");
.LBB0_752:
	s_or_b64 exec, exec, s[0:1]
	s_mov_b64 s[0:1], exec
	v_mbcnt_lo_u32_b32 v2, s0, 0
	v_mbcnt_hi_u32_b32 v2, s1, v2
	v_cmp_eq_u32_e32 vcc, 0, v2
	s_waitcnt vmcnt(0)
	s_and_saveexec_b64 s[8:9], vcc
	s_cbranch_execz .LBB0_754
	s_bcnt1_i32_b64 s0, s[0:1]
	v_mov_b32_e32 v2, s0
	v_readlane_b32 s0, v253, 10
	v_readlane_b32 s1, v253, 11
	s_nop 4
	s_nop 0

; __device__ __forceinline__ unsigned xb_ld(unsigned* p)              { return __hip_atomic_load(p, __ATOMIC_RELAXED, __HIP_MEMORY_SCOPE_AGENT); }
; __device__ __forceinline__ unsigned xb_add(unsigned* p, unsigned v) { return __hip_atomic_fetch_add(p, v, __ATOMIC_RELAXED, __HIP_MEMORY_SCOPE_AGENT); }
; #define XB_SPIN(cond, bar) do { unsigned _sp = 0; while (cond) { __builtin_amdgcn_s_sleep(1); \
;     if ((++_sp & 255u) == 0u) { if (xb_ld(&(bar)[XB_TMO])) break; if (_sp > XB_SPIN_CAP) { atomicAdd(&(bar)[XB_TMO], 1u); break; } } } } while (0)
; __device__ __forceinline__ void xcd_barrier_thread0(const XcdBarrier& b) {
;     ...
;         if (old + 1u == (gen + 1u) * nloc) {
;             __builtin_amdgcn_fence(__ATOMIC_RELEASE, "agent");
;             asm volatile("s_waitcnt vmcnt(0)" ::: "memory");
;             const unsigned og = xb_add(&bar[XB_TOP], 1u);
;             const unsigned tg = og / nx;
;             if (og + 1u == (tg + 1u) * nx) xb_add(&bar[XB_TOPGEN], 1u);
;             else XB_SPIN(xb_ld(&bar[XB_TOPGEN]) == tg, bar);
;             __builtin_amdgcn_fence(__ATOMIC_ACQUIRE, "agent");
;             xb_add(&bar[XB_XGEN(b.x)], 1u);
;             asm volatile("s_waitcnt vmcnt(0)" ::: "memory");
.LBB0_1067:
	s_or_b64 exec, exec, s[2:3]
	s_mov_b64 s[2:3], exec
	v_mbcnt_lo_u32_b32 v4, s2, 0
	v_mbcnt_hi_u32_b32 v4, s3, v4
	v_cmp_eq_u32_e32 vcc, 0, v4
	s_waitcnt vmcnt(0)
	s_and_saveexec_b64 s[8:9], vcc
	s_cbranch_execz .LBB0_1069
	s_bcnt1_i32_b64 s2, s[2:3]
	v_mov_b32_e32 v4, s2
	v_readlane_b32 s2, v253, 10
	v_readlane_b32 s3, v253, 11
	s_nop 4
	s_nop 0
